# deleted the per-phase s_setprio 1/0 flips around the MFMA blocks of the 8-phase GEMM loops (A/B per guide 6.3 rule 2)
# speedup vs baseline: 1.0184x; 1.0184x over previous
; #define PG8_STAGE(bufoff, gbase, voff) do { _Pragma("unroll") for (int _i = 0; _i < 2; ++_i) \
;         __builtin_amdgcn_global_load_lds((const unsigned*)((const char*)(gbase) + (voff)[_i]), (PG8_LAS unsigned*)(lds + (bufoff) + ldsw + _i * 8192), 16, 0, 0); } while (0)
; #define PG8_LDA(dst, b, h) do { _Pragma("unroll") for (int m = 0; m < 4; ++m) _Pragma("unroll") for (int k = 0; k < 2; ++k) dst[m][k] = *(const PG8_LAS bf16x8*)(lds + PG8_SA(b, h) + aoff + m * 2048 + k * 1024); } while (0)
; #define PG8_LDB(dst, b, h) do { _Pragma("unroll") for (int n = 0; n < 2; ++n) _Pragma("unroll") for (int k = 0; k < 2; ++k) dst[n][k] = *(const PG8_LAS bf16x8*)(lds + PG8_SB(b, h) + boff + n * 2048 + k * 1024); } while (0)
; #define PG8_WAIT_L(n) asm volatile("s_waitcnt lgkmcnt(" #n ")" ::: "memory")
; #define PG8_BAR __builtin_amdgcn_s_barrier()
; #define PG8_SCHED __builtin_amdgcn_sched_barrier(0)
; template <bool FP8, class Epi, class Sched>
; __device__ __forceinline__ void gemm_phase(PG8_LAS unsigned char* lds, const Gemm g, const Sched& S, const Epi& E) {
;     ...
;             PG8_LDB(B0, 0, 0); PG8_SCHED; PG8_LDA(At, 0, 0); PG8_STAGE(PG8_SA(1, 1), a1 + hstepA, voffA);
;             PG8_WAIT_L(8); PG8_BAR; PG8_WAIT_L(0); PG8_MMA(0, 0, At, B0); PG8_BAR; PG8_SCHED;
;             PG8_LDB(B1, 0, 1); PG8_STAGE(PG8_SB(0, 0), b2, voffB);
;             PG8_BAR; PG8_WAIT_L(0); PG8_MMA(0, 1, At, B1); PG8_BAR;
;             PG8_LDA(At, 0, 1); PG8_STAGE(PG8_SA(0, 0), a2, voffA);
;             PG8_BAR; PG8_WAIT_L(0); PG8_MMA(1, 0, At, B0); PG8_BAR; PG8_SCHED;
.LBB0_139:
	s_add_u32 s12, s0, 0xfff80080
	s_addc_u32 s13, s1, -1
	s_add_i32 s30, 0, 0x10000
	v_add_u32_e32 v140, s30, v143
	ds_read_b128 v[146:149], v140
	ds_read_b128 v[150:153], v140 offset:1024
	ds_read_b128 v[154:157], v140 offset:2048
	ds_read_b128 v[158:161], v140 offset:3072
	s_cmp_eq_u32 vcc_hi, 28
	s_cselect_b32 s69, s17, s13
	s_cselect_b32 s68, s87, s12
	s_cselect_b32 s13, s15, vcc_lo
	s_cselect_b32 s12, s94, s95
	v_lshl_add_u64 v[140:141], s[0:1], 0, v[136:137]
	s_add_i32 m0, s26, 0xc000
	ds_read_b128 v[162:165], v145
	ds_read_b128 v[166:169], v145 offset:1024
	ds_read_b128 v[170:173], v145 offset:2048
	ds_read_b128 v[182:185], v145 offset:3072
	ds_read_b128 v[186:189], v145 offset:4096
	ds_read_b128 v[190:193], v145 offset:5120
	ds_read_b128 v[194:197], v145 offset:6144
	ds_read_b128 v[198:201], v145 offset:7168
	global_load_lds_dwordx4 v[140:141], off
	v_lshl_add_u64 v[140:141], s[0:1], 0, v[138:139]
	s_add_i32 m0, s26, 0xe000
	s_nop 0
	global_load_lds_dwordx4 v[140:141], off
	s_waitcnt lgkmcnt(8)
	s_barrier
	s_waitcnt lgkmcnt(0)
	s_waitcnt lgkmcnt(0)
	v_mfma_f32_16x16x32_bf16 v[126:129], v[146:149], v[162:165], v[126:129]
	v_mfma_f32_16x16x32_bf16 v[122:125], v[154:157], v[162:165], v[122:125]
	v_mfma_f32_16x16x32_bf16 v[110:113], v[146:149], v[170:173], v[110:113]
	v_mfma_f32_16x16x32_bf16 v[106:109], v[154:157], v[170:173], v[106:109]
	v_mfma_f32_16x16x32_bf16 v[94:97], v[146:149], v[186:189], v[94:97]
	v_mfma_f32_16x16x32_bf16 v[90:93], v[154:157], v[186:189], v[90:93]
	v_mfma_f32_16x16x32_bf16 v[78:81], v[146:149], v[194:197], v[78:81]
	v_mfma_f32_16x16x32_bf16 v[74:77], v[154:157], v[194:197], v[74:77]
	v_mfma_f32_16x16x32_bf16 v[126:129], v[150:153], v[166:169], v[126:129]
	v_mfma_f32_16x16x32_bf16 v[122:125], v[158:161], v[166:169], v[122:125]
	v_mfma_f32_16x16x32_bf16 v[110:113], v[150:153], v[182:185], v[110:113]
	v_mfma_f32_16x16x32_bf16 v[106:109], v[158:161], v[182:185], v[106:109]
	v_mfma_f32_16x16x32_bf16 v[94:97], v[150:153], v[190:193], v[94:97]
	v_mfma_f32_16x16x32_bf16 v[90:93], v[158:161], v[190:193], v[90:93]
	v_mfma_f32_16x16x32_bf16 v[78:81], v[150:153], v[198:201], v[78:81]
	v_mfma_f32_16x16x32_bf16 v[74:77], v[158:161], v[198:201], v[74:77]
	s_barrier
	s_add_i32 s86, 0, 0x14000
	v_add_u32_e32 v140, s86, v143
	s_add_i32 s30, s30, s25
	ds_read_b128 v[202:205], v140
	ds_read_b128 v[206:209], v140 offset:1024
	ds_read_b128 v[210:213], v140 offset:2048
	ds_read_b128 v[214:217], v140 offset:3072
	v_lshl_add_u64 v[140:141], s[12:13], 0, v[0:1]
	s_mov_b32 m0, s30
	v_lshl_add_u64 v[174:175], s[12:13], 0, v[130:131]
	global_load_lds_dwordx4 v[140:141], off
	s_add_i32 m0, s30, 0x2000
	s_nop 0
	global_load_lds_dwordx4 v[174:175], off
	s_barrier
	s_waitcnt lgkmcnt(0)
	s_waitcnt lgkmcnt(0)
	v_mfma_f32_16x16x32_bf16 v[118:121], v[202:205], v[162:165], v[118:121]
	v_mfma_f32_16x16x32_bf16 v[114:117], v[210:213], v[162:165], v[114:117]
	v_mfma_f32_16x16x32_bf16 v[102:105], v[202:205], v[170:173], v[102:105]
	v_mfma_f32_16x16x32_bf16 v[98:101], v[210:213], v[170:173], v[98:101]
	v_mfma_f32_16x16x32_bf16 v[86:89], v[202:205], v[186:189], v[86:89]
	v_mfma_f32_16x16x32_bf16 v[82:85], v[210:213], v[186:189], v[82:85]
	v_mfma_f32_16x16x32_bf16 v[70:73], v[202:205], v[194:197], v[70:73]
	v_mfma_f32_16x16x32_bf16 v[66:69], v[210:213], v[194:197], v[66:69]
	v_mfma_f32_16x16x32_bf16 v[118:121], v[206:209], v[166:169], v[118:121]
	v_mfma_f32_16x16x32_bf16 v[114:117], v[214:217], v[166:169], v[114:117]
	v_mfma_f32_16x16x32_bf16 v[102:105], v[206:209], v[182:185], v[102:105]
	v_mfma_f32_16x16x32_bf16 v[98:101], v[214:217], v[182:185], v[98:101]
	v_mfma_f32_16x16x32_bf16 v[86:89], v[206:209], v[190:193], v[86:89]
	v_mfma_f32_16x16x32_bf16 v[82:85], v[214:217], v[190:193], v[82:85]
	v_mfma_f32_16x16x32_bf16 v[70:73], v[206:209], v[198:201], v[70:73]
	v_mfma_f32_16x16x32_bf16 v[66:69], v[214:217], v[198:201], v[66:69]
	s_mov_b32 m0, s26
	v_lshl_add_u64 v[236:237], s[68:69], 0, v[134:135]
	s_barrier
	ds_read_b128 v[162:165], v145 offset:16384
	ds_read_b128 v[166:169], v145 offset:17408
	ds_read_b128 v[170:173], v145 offset:18432
	ds_read_b128 v[182:185], v145 offset:19456
	ds_read_b128 v[186:189], v145 offset:20480
	ds_read_b128 v[190:193], v145 offset:21504
	ds_read_b128 v[194:197], v145 offset:22528
	ds_read_b128 v[198:201], v145 offset:23552
	global_load_lds_dwordx4 v[236:237], off
	v_lshl_add_u64 v[238:239], s[68:69], 0, v[132:133]
	s_mov_b32 m0, s27
	s_nop 0
	global_load_lds_dwordx4 v[238:239], off
	s_barrier
	s_waitcnt lgkmcnt(0)
	s_waitcnt lgkmcnt(0)
	v_mfma_f32_16x16x32_bf16 v[62:65], v[146:149], v[162:165], v[62:65]
	v_mfma_f32_16x16x32_bf16 v[58:61], v[154:157], v[162:165], v[58:61]
	v_mfma_f32_16x16x32_bf16 v[46:49], v[146:149], v[170:173], v[46:49]
	v_mfma_f32_16x16x32_bf16 v[42:45], v[154:157], v[170:173], v[42:45]
	v_mfma_f32_16x16x32_bf16 v[30:33], v[146:149], v[186:189], v[30:33]
	v_mfma_f32_16x16x32_bf16 v[26:29], v[154:157], v[186:189], v[26:29]
	v_mfma_f32_16x16x32_bf16 v[14:17], v[146:149], v[194:197], v[14:17]
	v_mfma_f32_16x16x32_bf16 v[10:13], v[154:157], v[194:197], v[10:13]
	v_mfma_f32_16x16x32_bf16 v[62:65], v[150:153], v[166:169], v[62:65]
	v_mfma_f32_16x16x32_bf16 v[58:61], v[158:161], v[166:169], v[58:61]
	v_mfma_f32_16x16x32_bf16 v[46:49], v[150:153], v[182:185], v[46:49]
	v_mfma_f32_16x16x32_bf16 v[42:45], v[158:161], v[182:185], v[42:45]
	v_mfma_f32_16x16x32_bf16 v[30:33], v[150:153], v[190:193], v[30:33]
	v_mfma_f32_16x16x32_bf16 v[26:29], v[158:161], v[190:193], v[26:29]
	v_mfma_f32_16x16x32_bf16 v[14:17], v[150:153], v[198:201], v[14:17]
	v_mfma_f32_16x16x32_bf16 v[10:13], v[158:161], v[198:201], v[10:13]
	s_barrier
; #define PG8_STAGE(bufoff, gbase, voff) do { _Pragma("unroll") for (int _i = 0; _i < 2; ++_i) \
;         __builtin_amdgcn_global_load_lds((const unsigned*)((const char*)(gbase) + (voff)[_i]), (PG8_LAS unsigned*)(lds + (bufoff) + ldsw + _i * 8192), 16, 0, 0); } while (0)
; #define PG8_LDA(dst, b, h) do { _Pragma("unroll") for (int m = 0; m < 4; ++m) _Pragma("unroll") for (int k = 0; k < 2; ++k) dst[m][k] = *(const PG8_LAS bf16x8*)(lds + PG8_SA(b, h) + aoff + m * 2048 + k * 1024); } while (0)
; #define PG8_LDB(dst, b, h) do { _Pragma("unroll") for (int n = 0; n < 2; ++n) _Pragma("unroll") for (int k = 0; k < 2; ++k) dst[n][k] = *(const PG8_LAS bf16x8*)(lds + PG8_SB(b, h) + boff + n * 2048 + k * 1024); } while (0)
; #define PG8_WAIT_V(n) asm volatile("s_waitcnt vmcnt(" #n ")" ::: "memory")
; #define PG8_WAIT_L(n) asm volatile("s_waitcnt lgkmcnt(" #n ")" ::: "memory")
; #define PG8_BAR __builtin_amdgcn_s_barrier()
; #define PG8_SCHED __builtin_amdgcn_sched_barrier(0)
; template <bool FP8, class Epi, class Sched>
; __device__ __forceinline__ void gemm_phase(PG8_LAS unsigned char* lds, const Gemm g, const Sched& S, const Epi& E) {
;     ...
;             PG8_STAGE(PG8_SB(0, 1), b2 + hstep, voffB);
;             PG8_WAIT_V(6); PG8_BAR; PG8_MMA(1, 1, At, B1); PG8_BAR;
;             PG8_LDB(B0, 1, 0); PG8_SCHED; PG8_LDA(At, 1, 0); PG8_STAGE(PG8_SA(0, 1), a2 + hstepA, voffA);
;             PG8_WAIT_L(8); PG8_BAR; PG8_WAIT_L(0); PG8_MMA(0, 0, At, B0); PG8_BAR; PG8_SCHED;
;             PG8_LDB(B1, 1, 1); PG8_STAGE(PG8_SB(1, 0), b3, voffB);
;             PG8_BAR; PG8_WAIT_L(0); PG8_MMA(0, 1, At, B1); PG8_BAR;
	s_add_u32 s30, s12, 0x80000
	s_addc_u32 s31, s13, 0
	s_add_i32 s86, s86, s25
	v_lshl_add_u64 v[146:147], s[30:31], 0, v[0:1]
	s_mov_b32 m0, s86
	s_nop 0
	global_load_lds_dwordx4 v[146:147], off
	v_lshl_add_u64 v[146:147], s[30:31], 0, v[130:131]
	s_add_i32 m0, s86, 0x2000
	s_nop 0
	global_load_lds_dwordx4 v[146:147], off
	s_waitcnt vmcnt(6)
	s_barrier
	v_mfma_f32_16x16x32_bf16 v[54:57], v[202:205], v[162:165], v[54:57]
	v_mfma_f32_16x16x32_bf16 v[50:53], v[210:213], v[162:165], v[50:53]
	v_mfma_f32_16x16x32_bf16 v[38:41], v[202:205], v[170:173], v[38:41]
	v_mfma_f32_16x16x32_bf16 v[34:37], v[210:213], v[170:173], v[34:37]
	v_mfma_f32_16x16x32_bf16 v[22:25], v[202:205], v[186:189], v[22:25]
	v_mfma_f32_16x16x32_bf16 v[18:21], v[210:213], v[186:189], v[18:21]
	v_mfma_f32_16x16x32_bf16 v[6:9], v[202:205], v[194:197], v[6:9]
	v_mfma_f32_16x16x32_bf16 v[2:5], v[210:213], v[194:197], v[2:5]
	v_mfma_f32_16x16x32_bf16 v[54:57], v[206:209], v[166:169], v[54:57]
	v_mfma_f32_16x16x32_bf16 v[50:53], v[214:217], v[166:169], v[50:53]
	v_mfma_f32_16x16x32_bf16 v[38:41], v[206:209], v[182:185], v[38:41]
	v_mfma_f32_16x16x32_bf16 v[34:37], v[214:217], v[182:185], v[34:37]
	v_mfma_f32_16x16x32_bf16 v[22:25], v[206:209], v[190:193], v[22:25]
	v_mfma_f32_16x16x32_bf16 v[18:21], v[214:217], v[190:193], v[18:21]
	v_mfma_f32_16x16x32_bf16 v[6:9], v[206:209], v[198:201], v[6:9]
	v_mfma_f32_16x16x32_bf16 v[2:5], v[214:217], v[198:201], v[2:5]
	s_add_i32 s86, 0, 0x18000
	v_add_u32_e32 v158, s86, v143
	s_barrier
	ds_read_b128 v[146:149], v158
	ds_read_b128 v[150:153], v158 offset:1024
	ds_read_b128 v[154:157], v158 offset:2048
	ds_read_b128 v[158:161], v158 offset:3072
	s_add_u32 s30, s68, 0x80000
	s_addc_u32 s31, s69, 0
	s_mov_b32 m0, s54
	v_lshl_add_u64 v[202:203], s[30:31], 0, v[134:135]
	ds_read_b128 v[162:165], v145 offset:32768
	ds_read_b128 v[166:169], v145 offset:33792
	ds_read_b128 v[170:173], v145 offset:34816
	ds_read_b128 v[182:185], v145 offset:35840
	ds_read_b128 v[186:189], v145 offset:36864
	ds_read_b128 v[190:193], v145 offset:37888
	ds_read_b128 v[194:197], v145 offset:38912
	ds_read_b128 v[198:201], v145 offset:39936
	global_load_lds_dwordx4 v[202:203], off
	v_lshl_add_u64 v[202:203], s[30:31], 0, v[132:133]
	s_mov_b32 m0, s70
	s_nop 0
	global_load_lds_dwordx4 v[202:203], off
	s_waitcnt lgkmcnt(8)
	s_barrier
	s_waitcnt lgkmcnt(0)
	s_waitcnt lgkmcnt(0)
	v_mfma_f32_16x16x32_bf16 v[126:129], v[146:149], v[162:165], v[126:129]
	v_mfma_f32_16x16x32_bf16 v[122:125], v[154:157], v[162:165], v[122:125]
	v_mfma_f32_16x16x32_bf16 v[110:113], v[146:149], v[170:173], v[110:113]
	v_mfma_f32_16x16x32_bf16 v[106:109], v[154:157], v[170:173], v[106:109]
	v_mfma_f32_16x16x32_bf16 v[94:97], v[146:149], v[186:189], v[94:97]
	v_mfma_f32_16x16x32_bf16 v[90:93], v[154:157], v[186:189], v[90:93]
	v_mfma_f32_16x16x32_bf16 v[78:81], v[146:149], v[194:197], v[78:81]
	v_mfma_f32_16x16x32_bf16 v[74:77], v[154:157], v[194:197], v[74:77]
	v_mfma_f32_16x16x32_bf16 v[126:129], v[150:153], v[166:169], v[126:129]
	v_mfma_f32_16x16x32_bf16 v[122:125], v[158:161], v[166:169], v[122:125]
	v_mfma_f32_16x16x32_bf16 v[110:113], v[150:153], v[182:185], v[110:113]
	v_mfma_f32_16x16x32_bf16 v[106:109], v[158:161], v[182:185], v[106:109]
	v_mfma_f32_16x16x32_bf16 v[94:97], v[150:153], v[190:193], v[94:97]
	v_mfma_f32_16x16x32_bf16 v[90:93], v[158:161], v[190:193], v[90:93]
	v_mfma_f32_16x16x32_bf16 v[78:81], v[150:153], v[198:201], v[78:81]
	v_mfma_f32_16x16x32_bf16 v[74:77], v[158:161], v[198:201], v[74:77]
	s_barrier
	s_add_i32 s30, 0, 0x1c000
	s_add_i32 s31, s86, s25
	v_add_u32_e32 v214, s30, v143
	v_lshl_add_u64 v[140:141], v[140:141], 0, s[56:57]
	s_mov_b32 m0, s31
	ds_read_b128 v[202:205], v214
	ds_read_b128 v[206:209], v214 offset:1024
	ds_read_b128 v[210:213], v214 offset:2048
	ds_read_b128 v[214:217], v214 offset:3072
	global_load_lds_dwordx4 v[140:141], off
	v_lshl_add_u64 v[140:141], v[174:175], 0, s[56:57]
	s_add_i32 m0, s31, 0x2000
	s_nop 0
	global_load_lds_dwordx4 v[140:141], off
	s_barrier
	s_waitcnt lgkmcnt(0)
	s_waitcnt lgkmcnt(0)
	v_mfma_f32_16x16x32_bf16 v[118:121], v[202:205], v[162:165], v[118:121]
	v_mfma_f32_16x16x32_bf16 v[114:117], v[210:213], v[162:165], v[114:117]
	v_mfma_f32_16x16x32_bf16 v[102:105], v[202:205], v[170:173], v[102:105]
	v_mfma_f32_16x16x32_bf16 v[98:101], v[210:213], v[170:173], v[98:101]
	v_mfma_f32_16x16x32_bf16 v[86:89], v[202:205], v[186:189], v[86:89]
	v_mfma_f32_16x16x32_bf16 v[82:85], v[210:213], v[186:189], v[82:85]
	v_mfma_f32_16x16x32_bf16 v[70:73], v[202:205], v[194:197], v[70:73]
	v_mfma_f32_16x16x32_bf16 v[66:69], v[210:213], v[194:197], v[66:69]
	v_mfma_f32_16x16x32_bf16 v[118:121], v[206:209], v[166:169], v[118:121]
	v_mfma_f32_16x16x32_bf16 v[114:117], v[214:217], v[166:169], v[114:117]
	v_mfma_f32_16x16x32_bf16 v[102:105], v[206:209], v[182:185], v[102:105]
	v_mfma_f32_16x16x32_bf16 v[98:101], v[214:217], v[182:185], v[98:101]
	v_mfma_f32_16x16x32_bf16 v[86:89], v[206:209], v[190:193], v[86:89]
	v_mfma_f32_16x16x32_bf16 v[82:85], v[214:217], v[190:193], v[82:85]
	v_mfma_f32_16x16x32_bf16 v[70:73], v[206:209], v[198:201], v[70:73]
	v_mfma_f32_16x16x32_bf16 v[66:69], v[214:217], v[198:201], v[66:69]
	s_mov_b32 m0, s71
	v_lshl_add_u64 v[140:141], v[236:237], 0, s[56:57]
	s_barrier
; #define PG8_STAGE(bufoff, gbase, voff) do { _Pragma("unroll") for (int _i = 0; _i < 2; ++_i) \
;         __builtin_amdgcn_global_load_lds((const unsigned*)((const char*)(gbase) + (voff)[_i]), (PG8_LAS unsigned*)(lds + (bufoff) + ldsw + _i * 8192), 16, 0, 0); } while (0)
; #define PG8_BAR __builtin_amdgcn_s_barrier()
; template <bool FP8, class Epi, class Sched>
; __device__ __forceinline__ void gemm_phase(PG8_LAS unsigned char* lds, const Gemm g, const Sched& S, const Epi& E) {
;     ...
;             PG8_LDA(At, 1, 1); PG8_STAGE(PG8_SA(1, 0), a3, voffA);
;             PG8_BAR; PG8_WAIT_L(0); PG8_MMA(1, 0, At, B0); PG8_BAR; PG8_SCHED;
;             PG8_STAGE(PG8_SB(1, 1), b3 + hstep, voffB);
;             PG8_WAIT_V(6); PG8_BAR; PG8_MMA(1, 1, At, B1); PG8_BAR;
;   DI void operator()(const f32x4 (&acc)[2][2][4][2], const pg8::Unit& u, int wr, int wc, int fr, int fq) const {
;     const int row0 = u.pm * 256 + wr * 64 + fr, colb = u.pn * 256 + wc * 32 + 8 * fq;
; #pragma unroll
;     for (int ai = 0; ai < 2; ++ai)
; #pragma unroll
;       for (int m = 0; m < 4; ++m) {
;         const int row = row0 + ai * 128 + m * 16;
; #pragma unroll
;         for (int bj = 0; bj < 2; ++bj) {
;           const int col = colb + bj * 128;
;           f32x4 v0 = acc[ai][bj][m][0] * sc, v1 = acc[ai][bj][m][1] * sc;
;           u16* dst = nullptr;
;           if (MODE == 0) { if (col < N) dst = d0 + (size_t)row * ld0 + (col + coff2 + ((col < csplit) ? (coff1 - coff2) : 0)); }
;           else if (MODE == 1) {
;             const int oc = col + coff2 + ((col < csplit) ? (coff1 - coff2) : 0);
;             if (col < N) {
;               if (oc < 2048) dst = d0 + (size_t)row * 2048 + oc;
;               else if (oc < 2112) { rot(v0, v1, row, oc); dst = d2 + (size_t)row * 64 + (oc - 2048); }
;               else dst = d1 + (size_t)row * 4096 + (oc - 2112);
;             }
;           } else if (MODE == 3) {
;             if (col < N) { const bool lo = col < csplit; u16* bp = lo ? d0 : d1; const int ldd = lo ? 2048 : 4096, oc = lo ? col : col + (coff2 - 2112); dst = bp + (size_t)row * ldd + oc + (lo ? coff1 : 0); }
;           } else {
;             if (((col >> 6) % 3) == 2) rot(v0, v1, row, col);
;             dst = d0 + (size_t)row * 3072 + col;
;           }
;           if (dst) { u32x4 w = {pk2(v0[0], v0[1]), pk2(v0[2], v0[3]), pk2(v1[0], v1[1]), pk2(v1[2], v1[3])}; *(u32x4*)dst = w; }
	ds_read_b128 v[162:165], v145 offset:49152
	ds_read_b128 v[166:169], v145 offset:50176
	ds_read_b128 v[170:173], v145 offset:51200
	ds_read_b128 v[182:185], v145 offset:52224
	ds_read_b128 v[186:189], v145 offset:53248
	ds_read_b128 v[190:193], v145 offset:54272
	ds_read_b128 v[194:197], v145 offset:55296
	ds_read_b128 v[198:201], v145 offset:56320
	global_load_lds_dwordx4 v[140:141], off
	v_lshl_add_u64 v[140:141], v[238:239], 0, s[56:57]
	s_mov_b32 m0, s72
	s_nop 0
	global_load_lds_dwordx4 v[140:141], off
	s_barrier
	s_waitcnt lgkmcnt(0)
	s_waitcnt lgkmcnt(0)
	v_mfma_f32_16x16x32_bf16 v[62:65], v[146:149], v[162:165], v[62:65]
	v_mfma_f32_16x16x32_bf16 v[58:61], v[154:157], v[162:165], v[58:61]
	v_mfma_f32_16x16x32_bf16 v[46:49], v[146:149], v[170:173], v[46:49]
	v_mfma_f32_16x16x32_bf16 v[42:45], v[154:157], v[170:173], v[42:45]
	v_mfma_f32_16x16x32_bf16 v[30:33], v[146:149], v[186:189], v[30:33]
	v_mfma_f32_16x16x32_bf16 v[26:29], v[154:157], v[186:189], v[26:29]
	v_mfma_f32_16x16x32_bf16 v[14:17], v[146:149], v[194:197], v[14:17]
	v_mfma_f32_16x16x32_bf16 v[10:13], v[154:157], v[194:197], v[10:13]
	v_mfma_f32_16x16x32_bf16 v[62:65], v[150:153], v[166:169], v[62:65]
	v_mfma_f32_16x16x32_bf16 v[58:61], v[158:161], v[166:169], v[58:61]
	v_mfma_f32_16x16x32_bf16 v[46:49], v[150:153], v[182:185], v[46:49]
	v_mfma_f32_16x16x32_bf16 v[42:45], v[158:161], v[182:185], v[42:45]
	v_mfma_f32_16x16x32_bf16 v[30:33], v[150:153], v[190:193], v[30:33]
	v_mfma_f32_16x16x32_bf16 v[26:29], v[158:161], v[190:193], v[26:29]
	v_mfma_f32_16x16x32_bf16 v[14:17], v[150:153], v[198:201], v[14:17]
	v_mfma_f32_16x16x32_bf16 v[10:13], v[158:161], v[198:201], v[10:13]
	s_barrier
	s_add_u32 s12, s12, 0x80080
	s_addc_u32 s13, s13, 0
	s_add_i32 s30, s30, s25
	v_lshl_add_u64 v[140:141], s[12:13], 0, v[0:1]
	s_mov_b32 m0, s30
	s_nop 0
	global_load_lds_dwordx4 v[140:141], off
	v_lshl_add_u64 v[140:141], s[12:13], 0, v[130:131]
	s_add_i32 m0, s30, 0x2000
	s_nop 0
	global_load_lds_dwordx4 v[140:141], off
	s_waitcnt vmcnt(6)
	s_barrier
	v_mfma_f32_16x16x32_bf16 v[54:57], v[202:205], v[162:165], v[54:57]
	v_mfma_f32_16x16x32_bf16 v[50:53], v[210:213], v[162:165], v[50:53]
	v_mfma_f32_16x16x32_bf16 v[38:41], v[202:205], v[170:173], v[38:41]
	v_mfma_f32_16x16x32_bf16 v[34:37], v[210:213], v[170:173], v[34:37]
	v_mfma_f32_16x16x32_bf16 v[22:25], v[202:205], v[186:189], v[22:25]
	v_mfma_f32_16x16x32_bf16 v[18:21], v[210:213], v[186:189], v[18:21]
	v_mfma_f32_16x16x32_bf16 v[6:9], v[202:205], v[194:197], v[6:9]
	v_mfma_f32_16x16x32_bf16 v[2:5], v[210:213], v[194:197], v[2:5]
	v_mfma_f32_16x16x32_bf16 v[54:57], v[206:209], v[166:169], v[54:57]
	v_mfma_f32_16x16x32_bf16 v[50:53], v[214:217], v[166:169], v[50:53]
	v_mfma_f32_16x16x32_bf16 v[38:41], v[206:209], v[182:185], v[38:41]
	v_mfma_f32_16x16x32_bf16 v[34:37], v[214:217], v[182:185], v[34:37]
	v_mfma_f32_16x16x32_bf16 v[22:25], v[206:209], v[190:193], v[22:25]
	v_mfma_f32_16x16x32_bf16 v[18:21], v[214:217], v[190:193], v[18:21]
	v_mfma_f32_16x16x32_bf16 v[6:9], v[206:209], v[198:201], v[6:9]
	v_mfma_f32_16x16x32_bf16 v[2:5], v[214:217], v[198:201], v[2:5]
	s_add_i32 vcc_hi, vcc_hi, 2
	s_add_u32 s0, s0, 0x100
	s_addc_u32 s1, s1, 0
	s_add_u32 s95, s95, 0x100
	s_addc_u32 vcc_lo, vcc_lo, 0
	s_cmp_gt_u32 vcc_hi, 29
	s_barrier
	s_cbranch_scc0 .LBB0_139
	v_lshl_or_b32 v146, s28, 8, v144
	s_movk_i32 s0, 0xe00
	v_lshl_add_u32 v147, s29, 8, v142
	v_cmp_gt_i32_e32 vcc, s0, v146
	v_mov_b64_e32 v[140:141], 0
	s_and_saveexec_b64 s[12:13], vcc
	v_mov_b64_e32 v[140:141], s[96:97]
	s_movk_i32 s0, 0x3400
	v_mad_i64_i32 v[140:141], s[0:1], v147, s0, v[140:141]
	s_movk_i32 s0, 0x200
	s_nop 0
	v_cmp_gt_i32_e64 s[0:1], s0, v146
	s_nop 1
	v_cndmask_b32_e64 v148, 0, v227, s[0:1]
	v_add3_u32 v148, v146, v148, s34
	v_ashrrev_i32_e32 v149, 31, v148
	v_lshl_add_u64 v[140:141], v[148:149], 1, v[140:141]
	s_or_b64 exec, exec, s[12:13]
	v_cmp_ne_u64_e64 s[0:1], 0, v[140:141]
	s_and_saveexec_b64 s[12:13], s[0:1]
	s_movk_i32 s20, 0x600
	s_mov_b32 s86, 0x800000
	s_movk_i32 s87, 0x3fff
	v_readlane_b32 s3, v254, 29
	s_cbranch_execz .LBB0_144
	v_cvt_pk_bf16_f32 v126, v126, v127
	v_cvt_pk_bf16_f32 v127, v128, v129
	v_cvt_pk_bf16_f32 v128, v122, v123
	v_cvt_pk_bf16_f32 v129, v124, v125
	global_store_dwordx4 v[140:141], v[126:129], off

; #define PG8_STAGE(bufoff, gbase, voff) do { _Pragma("unroll") for (int _i = 0; _i < 2; ++_i) \
;         __builtin_amdgcn_global_load_lds((const unsigned*)((const char*)(gbase) + (voff)[_i]), (PG8_LAS unsigned*)(lds + (bufoff) + ldsw + _i * 8192), 16, 0, 0); } while (0)
; #define PG8_LDA(dst, b, h) do { _Pragma("unroll") for (int m = 0; m < 4; ++m) _Pragma("unroll") for (int k = 0; k < 2; ++k) dst[m][k] = *(const PG8_LAS bf16x8*)(lds + PG8_SA(b, h) + aoff + m * 2048 + k * 1024); } while (0)
; #define PG8_LDB(dst, b, h) do { _Pragma("unroll") for (int n = 0; n < 2; ++n) _Pragma("unroll") for (int k = 0; k < 2; ++k) dst[n][k] = *(const PG8_LAS bf16x8*)(lds + PG8_SB(b, h) + boff + n * 2048 + k * 1024); } while (0)
; #define PG8_WAIT_V(n) asm volatile("s_waitcnt vmcnt(" #n ")" ::: "memory")
; #define PG8_WAIT_L(n) asm volatile("s_waitcnt lgkmcnt(" #n ")" ::: "memory")
; #define PG8_BAR __builtin_amdgcn_s_barrier()
; #define PG8_SCHED __builtin_amdgcn_sched_barrier(0)
; template <bool FP8, class Epi, class Sched>
; __device__ __forceinline__ void gemm_phase(PG8_LAS unsigned char* lds, const Gemm g, const Sched& S, const Epi& E) {
;     ...
;             PG8_LDB(B0, 0, 0); PG8_SCHED; PG8_LDA(At, 0, 0); PG8_STAGE(PG8_SA(1, 1), a1 + hstepA, voffA);
;             PG8_WAIT_L(8); PG8_BAR; PG8_WAIT_L(0); PG8_MMA(0, 0, At, B0); PG8_BAR; PG8_SCHED;
;             PG8_LDB(B1, 0, 1); PG8_STAGE(PG8_SB(0, 0), b2, voffB);
;             PG8_BAR; PG8_WAIT_L(0); PG8_MMA(0, 1, At, B1); PG8_BAR;
;             PG8_LDA(At, 0, 1); PG8_STAGE(PG8_SA(0, 0), a2, voffA);
;             PG8_BAR; PG8_WAIT_L(0); PG8_MMA(1, 0, At, B0); PG8_BAR; PG8_SCHED;
;             PG8_STAGE(PG8_SB(0, 1), b2 + hstep, voffB);
;             PG8_WAIT_V(6); PG8_BAR; PG8_MMA(1, 1, At, B1); PG8_BAR;
;             PG8_LDB(B0, 1, 0); PG8_SCHED; PG8_LDA(At, 1, 0); PG8_STAGE(PG8_SA(0, 1), a2 + hstepA, voffA);
.LBB0_226:
	s_add_u32 s10, s0, 0xfffc0080
	s_addc_u32 s11, s1, -1
	s_add_i32 s30, 0, 0x10000
	v_add_u32_e32 v6, s30, v174
	ds_read_b128 v[10:13], v6
	ds_read_b128 v[14:17], v6 offset:1024
	ds_read_b128 v[2:5], v6 offset:2048
	ds_read_b128 v[6:9], v6 offset:3072
	s_cmp_eq_u32 vcc_hi, 12
	s_cselect_b32 s69, s15, s11
	s_cselect_b32 s68, s87, s10
	s_cselect_b32 s11, s13, vcc_lo
	s_cselect_b32 s10, s94, s95
	v_lshl_add_u64 v[18:19], s[0:1], 0, v[160:161]
	s_add_i32 m0, s26, 0xc000
	ds_read_b128 v[184:187], v182
	ds_read_b128 v[188:191], v182 offset:1024
	ds_read_b128 v[192:195], v182 offset:2048
	ds_read_b128 v[196:199], v182 offset:3072
	ds_read_b128 v[200:203], v182 offset:4096
	ds_read_b128 v[204:207], v182 offset:5120
	ds_read_b128 v[208:211], v182 offset:6144
	ds_read_b128 v[212:215], v182 offset:7168
	global_load_lds_dwordx4 v[18:19], off
	v_lshl_add_u64 v[18:19], s[0:1], 0, v[162:163]
	s_add_i32 m0, s26, 0xe000
	s_nop 0
	global_load_lds_dwordx4 v[18:19], off
	s_waitcnt lgkmcnt(8)
	s_barrier
	s_waitcnt lgkmcnt(0)
	s_waitcnt lgkmcnt(0)
	s_nop 1
	v_mfma_scale_f32_16x16x128_f8f6f4 v[150:153], v[10:17], v[184:191], v[150:153], v172, v172 op_sel_hi:[0,0,0]
	s_nop 1
	v_mfma_scale_f32_16x16x128_f8f6f4 v[146:149], v[2:9], v[184:191], v[146:149], v172, v172 op_sel_hi:[0,0,0]
	s_nop 1
	v_mfma_scale_f32_16x16x128_f8f6f4 v[134:137], v[10:17], v[192:199], v[134:137], v172, v172 op_sel_hi:[0,0,0]
	s_nop 1
	v_mfma_scale_f32_16x16x128_f8f6f4 v[130:133], v[2:9], v[192:199], v[130:133], v172, v172 op_sel_hi:[0,0,0]
	s_nop 1
	v_mfma_scale_f32_16x16x128_f8f6f4 v[118:121], v[10:17], v[200:207], v[118:121], v172, v172 op_sel_hi:[0,0,0]
	s_nop 1
	v_mfma_scale_f32_16x16x128_f8f6f4 v[114:117], v[2:9], v[200:207], v[114:117], v172, v172 op_sel_hi:[0,0,0]
	s_nop 1
	v_mfma_scale_f32_16x16x128_f8f6f4 v[102:105], v[10:17], v[208:215], v[102:105], v172, v172 op_sel_hi:[0,0,0]
	s_nop 1
	v_mfma_scale_f32_16x16x128_f8f6f4 v[98:101], v[2:9], v[208:215], v[98:101], v172, v172 op_sel_hi:[0,0,0]
	s_barrier
	s_add_i32 s86, 0, 0x14000
	s_add_i32 s30, s30, s25
	v_add_u32_e32 v22, s86, v174
	v_lshl_add_u64 v[164:165], s[10:11], 0, v[0:1]
	s_mov_b32 m0, s30
	ds_read_b128 v[236:239], v22
	ds_read_b128 v[240:243], v22 offset:1024
	ds_read_b128 v[18:21], v22 offset:2048
	ds_read_b128 v[22:25], v22 offset:3072
	global_load_lds_dwordx4 v[164:165], off
	v_lshl_add_u64 v[166:167], s[10:11], 0, v[158:159]
	s_add_i32 m0, s30, 0x2000
	s_nop 0
	global_load_lds_dwordx4 v[166:167], off
	s_barrier
	s_waitcnt lgkmcnt(0)
	s_waitcnt lgkmcnt(0)
	s_nop 1
	v_mfma_scale_f32_16x16x128_f8f6f4 v[142:145], v[236:243], v[184:191], v[142:145], v172, v172 op_sel_hi:[0,0,0]
	s_nop 1
	v_mfma_scale_f32_16x16x128_f8f6f4 v[138:141], v[18:25], v[184:191], v[138:141], v172, v172 op_sel_hi:[0,0,0]
	s_nop 1
	v_mfma_scale_f32_16x16x128_f8f6f4 v[126:129], v[236:243], v[192:199], v[126:129], v172, v172 op_sel_hi:[0,0,0]
	s_nop 1
	v_mfma_scale_f32_16x16x128_f8f6f4 v[122:125], v[18:25], v[192:199], v[122:125], v172, v172 op_sel_hi:[0,0,0]
	s_nop 1
	v_mfma_scale_f32_16x16x128_f8f6f4 v[110:113], v[236:243], v[200:207], v[110:113], v172, v172 op_sel_hi:[0,0,0]
	s_nop 1
	v_mfma_scale_f32_16x16x128_f8f6f4 v[106:109], v[18:25], v[200:207], v[106:109], v172, v172 op_sel_hi:[0,0,0]
	s_nop 1
	v_mfma_scale_f32_16x16x128_f8f6f4 v[94:97], v[236:243], v[208:215], v[94:97], v172, v172 op_sel_hi:[0,0,0]
	s_nop 1
	v_mfma_scale_f32_16x16x128_f8f6f4 v[90:93], v[18:25], v[208:215], v[90:93], v172, v172 op_sel_hi:[0,0,0]
	s_mov_b32 m0, s26
	v_lshl_add_u64 v[168:169], s[68:69], 0, v[154:155]
	s_barrier
	ds_read_b128 v[184:187], v182 offset:16384
	ds_read_b128 v[188:191], v182 offset:17408
	ds_read_b128 v[192:195], v182 offset:18432
	ds_read_b128 v[196:199], v182 offset:19456
	ds_read_b128 v[200:203], v182 offset:20480
	ds_read_b128 v[204:207], v182 offset:21504
	ds_read_b128 v[208:211], v182 offset:22528
	ds_read_b128 v[212:215], v182 offset:23552
	global_load_lds_dwordx4 v[168:169], off
	v_lshl_add_u64 v[170:171], s[68:69], 0, v[156:157]
	s_mov_b32 m0, s27
	s_nop 0
	global_load_lds_dwordx4 v[170:171], off
	s_barrier
	s_waitcnt lgkmcnt(0)
	s_waitcnt lgkmcnt(0)
	s_nop 1
	v_mfma_scale_f32_16x16x128_f8f6f4 v[86:89], v[10:17], v[184:191], v[86:89], v172, v172 op_sel_hi:[0,0,0]
	s_nop 1
	v_mfma_scale_f32_16x16x128_f8f6f4 v[82:85], v[2:9], v[184:191], v[82:85], v172, v172 op_sel_hi:[0,0,0]
	s_nop 1
	v_mfma_scale_f32_16x16x128_f8f6f4 v[70:73], v[10:17], v[192:199], v[70:73], v172, v172 op_sel_hi:[0,0,0]
	s_nop 1
	v_mfma_scale_f32_16x16x128_f8f6f4 v[66:69], v[2:9], v[192:199], v[66:69], v172, v172 op_sel_hi:[0,0,0]
	s_nop 1
	v_mfma_scale_f32_16x16x128_f8f6f4 v[54:57], v[10:17], v[200:207], v[54:57], v172, v172 op_sel_hi:[0,0,0]
	s_nop 1
	v_mfma_scale_f32_16x16x128_f8f6f4 v[50:53], v[2:9], v[200:207], v[50:53], v172, v172 op_sel_hi:[0,0,0]
	s_nop 1
	v_mfma_scale_f32_16x16x128_f8f6f4 v[38:41], v[10:17], v[208:215], v[38:41], v172, v172 op_sel_hi:[0,0,0]
	s_nop 1
	v_mfma_scale_f32_16x16x128_f8f6f4 v[34:37], v[2:9], v[208:215], v[34:37], v172, v172 op_sel_hi:[0,0,0]
	s_barrier
	s_add_u32 s30, s10, 0x40000
	s_addc_u32 s31, s11, 0
	s_add_i32 s86, s86, s25
	v_lshl_add_u64 v[2:3], s[30:31], 0, v[0:1]
	s_mov_b32 m0, s86
	s_nop 0
	global_load_lds_dwordx4 v[2:3], off
	v_lshl_add_u64 v[2:3], s[30:31], 0, v[158:159]
	s_add_i32 m0, s86, 0x2000
	s_nop 0
	global_load_lds_dwordx4 v[2:3], off
	s_waitcnt vmcnt(6)
	s_barrier
; #define PG8_STAGE(bufoff, gbase, voff) do { _Pragma("unroll") for (int _i = 0; _i < 2; ++_i) \
;         __builtin_amdgcn_global_load_lds((const unsigned*)((const char*)(gbase) + (voff)[_i]), (PG8_LAS unsigned*)(lds + (bufoff) + ldsw + _i * 8192), 16, 0, 0); } while (0)
; #define PG8_LDA(dst, b, h) do { _Pragma("unroll") for (int m = 0; m < 4; ++m) _Pragma("unroll") for (int k = 0; k < 2; ++k) dst[m][k] = *(const PG8_LAS bf16x8*)(lds + PG8_SA(b, h) + aoff + m * 2048 + k * 1024); } while (0)
; #define PG8_LDB(dst, b, h) do { _Pragma("unroll") for (int n = 0; n < 2; ++n) _Pragma("unroll") for (int k = 0; k < 2; ++k) dst[n][k] = *(const PG8_LAS bf16x8*)(lds + PG8_SB(b, h) + boff + n * 2048 + k * 1024); } while (0)
; #define PG8_WAIT_V(n) asm volatile("s_waitcnt vmcnt(" #n ")" ::: "memory")
; #define PG8_WAIT_L(n) asm volatile("s_waitcnt lgkmcnt(" #n ")" ::: "memory")
; #define PG8_BAR __builtin_amdgcn_s_barrier()
; #define PG8_SCHED __builtin_amdgcn_sched_barrier(0)
; template <bool FP8, class Epi, class Sched>
; __device__ __forceinline__ void gemm_phase(PG8_LAS unsigned char* lds, const Gemm g, const Sched& S, const Epi& E) {
;     ...
;             PG8_STAGE(PG8_SB(0, 1), b2 + hstep, voffB);
;             PG8_WAIT_V(6); PG8_BAR; PG8_MMA(1, 1, At, B1); PG8_BAR;
;             PG8_LDB(B0, 1, 0); PG8_SCHED; PG8_LDA(At, 1, 0); PG8_STAGE(PG8_SA(0, 1), a2 + hstepA, voffA);
;             PG8_WAIT_L(8); PG8_BAR; PG8_WAIT_L(0); PG8_MMA(0, 0, At, B0); PG8_BAR; PG8_SCHED;
;             PG8_LDB(B1, 1, 1); PG8_STAGE(PG8_SB(1, 0), b3, voffB);
;             PG8_BAR; PG8_WAIT_L(0); PG8_MMA(0, 1, At, B1); PG8_BAR;
	s_nop 1
	v_mfma_scale_f32_16x16x128_f8f6f4 v[78:81], v[236:243], v[184:191], v[78:81], v172, v172 op_sel_hi:[0,0,0]
	s_nop 1
	v_mfma_scale_f32_16x16x128_f8f6f4 v[74:77], v[18:25], v[184:191], v[74:77], v172, v172 op_sel_hi:[0,0,0]
	s_nop 1
	v_mfma_scale_f32_16x16x128_f8f6f4 v[62:65], v[236:243], v[192:199], v[62:65], v172, v172 op_sel_hi:[0,0,0]
	s_nop 1
	v_mfma_scale_f32_16x16x128_f8f6f4 v[58:61], v[18:25], v[192:199], v[58:61], v172, v172 op_sel_hi:[0,0,0]
	s_nop 1
	v_mfma_scale_f32_16x16x128_f8f6f4 v[46:49], v[236:243], v[200:207], v[46:49], v172, v172 op_sel_hi:[0,0,0]
	s_nop 1
	v_mfma_scale_f32_16x16x128_f8f6f4 v[42:45], v[18:25], v[200:207], v[42:45], v172, v172 op_sel_hi:[0,0,0]
	s_nop 1
	v_mfma_scale_f32_16x16x128_f8f6f4 v[30:33], v[236:243], v[208:215], v[30:33], v172, v172 op_sel_hi:[0,0,0]
	s_nop 1
	v_mfma_scale_f32_16x16x128_f8f6f4 v[26:29], v[18:25], v[208:215], v[26:29], v172, v172 op_sel_hi:[0,0,0]
	s_add_i32 s86, 0, 0x18000
	v_add_u32_e32 v14, s86, v174
	s_barrier
	ds_read_b128 v[2:5], v14
	ds_read_b128 v[6:9], v14 offset:1024
	ds_read_b128 v[10:13], v14 offset:2048
	ds_read_b128 v[14:17], v14 offset:3072
	s_add_u32 s30, s68, 0x40000
	s_addc_u32 s31, s69, 0
	s_mov_b32 m0, s54
	v_lshl_add_u64 v[208:209], s[30:31], 0, v[154:155]
	ds_read_b128 v[18:21], v182 offset:32768
	ds_read_b128 v[22:25], v182 offset:33792
	ds_read_b128 v[184:187], v182 offset:34816
	ds_read_b128 v[188:191], v182 offset:35840
	ds_read_b128 v[192:195], v182 offset:36864
	ds_read_b128 v[196:199], v182 offset:37888
	ds_read_b128 v[200:203], v182 offset:38912
	ds_read_b128 v[204:207], v182 offset:39936
	global_load_lds_dwordx4 v[208:209], off
	v_lshl_add_u64 v[208:209], s[30:31], 0, v[156:157]
	s_mov_b32 m0, s70
	s_nop 0
	global_load_lds_dwordx4 v[208:209], off
	s_waitcnt lgkmcnt(8)
	s_barrier
	s_waitcnt lgkmcnt(0)
	s_waitcnt lgkmcnt(0)
	s_nop 1
	v_mfma_scale_f32_16x16x128_f8f6f4 v[150:153], v[2:9], v[18:25], v[150:153], v172, v172 op_sel_hi:[0,0,0]
	s_nop 1
	v_mfma_scale_f32_16x16x128_f8f6f4 v[146:149], v[10:17], v[18:25], v[146:149], v172, v172 op_sel_hi:[0,0,0]
	s_nop 1
	v_mfma_scale_f32_16x16x128_f8f6f4 v[134:137], v[2:9], v[184:191], v[134:137], v172, v172 op_sel_hi:[0,0,0]
	s_nop 1
	v_mfma_scale_f32_16x16x128_f8f6f4 v[130:133], v[10:17], v[184:191], v[130:133], v172, v172 op_sel_hi:[0,0,0]
	s_nop 1
	v_mfma_scale_f32_16x16x128_f8f6f4 v[118:121], v[2:9], v[192:199], v[118:121], v172, v172 op_sel_hi:[0,0,0]
	s_nop 1
	v_mfma_scale_f32_16x16x128_f8f6f4 v[114:117], v[10:17], v[192:199], v[114:117], v172, v172 op_sel_hi:[0,0,0]
	s_nop 1
	v_mfma_scale_f32_16x16x128_f8f6f4 v[102:105], v[2:9], v[200:207], v[102:105], v172, v172 op_sel_hi:[0,0,0]
	s_nop 1
	v_mfma_scale_f32_16x16x128_f8f6f4 v[98:101], v[10:17], v[200:207], v[98:101], v172, v172 op_sel_hi:[0,0,0]
	s_barrier
	s_add_i32 s30, 0, 0x1c000
	s_add_i32 s31, s86, s25
	v_add_u32_e32 v183, s30, v174
	v_lshl_add_u64 v[164:165], v[164:165], 0, s[56:57]
	s_mov_b32 m0, s31
	ds_read_b128 v[208:211], v183
	ds_read_b128 v[212:215], v183 offset:1024
	ds_read_b128 v[236:239], v183 offset:2048
	ds_read_b128 v[240:243], v183 offset:3072
	global_load_lds_dwordx4 v[164:165], off
	v_lshl_add_u64 v[164:165], v[166:167], 0, s[56:57]
	s_add_i32 m0, s31, 0x2000
	s_nop 0
	global_load_lds_dwordx4 v[164:165], off
	s_barrier
	s_waitcnt lgkmcnt(0)
	s_waitcnt lgkmcnt(0)
	s_nop 1
	v_mfma_scale_f32_16x16x128_f8f6f4 v[142:145], v[208:215], v[18:25], v[142:145], v172, v172 op_sel_hi:[0,0,0]
	s_nop 1
	v_mfma_scale_f32_16x16x128_f8f6f4 v[138:141], v[236:243], v[18:25], v[138:141], v172, v172 op_sel_hi:[0,0,0]
	s_nop 1
	v_mfma_scale_f32_16x16x128_f8f6f4 v[126:129], v[208:215], v[184:191], v[126:129], v172, v172 op_sel_hi:[0,0,0]
	s_nop 1
	v_mfma_scale_f32_16x16x128_f8f6f4 v[122:125], v[236:243], v[184:191], v[122:125], v172, v172 op_sel_hi:[0,0,0]
	s_nop 1
	v_mfma_scale_f32_16x16x128_f8f6f4 v[110:113], v[208:215], v[192:199], v[110:113], v172, v172 op_sel_hi:[0,0,0]
	s_nop 1
	v_mfma_scale_f32_16x16x128_f8f6f4 v[106:109], v[236:243], v[192:199], v[106:109], v172, v172 op_sel_hi:[0,0,0]
	s_nop 1
	v_mfma_scale_f32_16x16x128_f8f6f4 v[94:97], v[208:215], v[200:207], v[94:97], v172, v172 op_sel_hi:[0,0,0]
	s_nop 1
	v_mfma_scale_f32_16x16x128_f8f6f4 v[90:93], v[236:243], v[200:207], v[90:93], v172, v172 op_sel_hi:[0,0,0]
	s_mov_b32 m0, s71
	v_lshl_add_u64 v[164:165], v[168:169], 0, s[56:57]
	s_barrier
; #define PG8_STAGE(bufoff, gbase, voff) do { _Pragma("unroll") for (int _i = 0; _i < 2; ++_i) \
;         __builtin_amdgcn_global_load_lds((const unsigned*)((const char*)(gbase) + (voff)[_i]), (PG8_LAS unsigned*)(lds + (bufoff) + ldsw + _i * 8192), 16, 0, 0); } while (0)
; #define PG8_LDA(dst, b, h) do { _Pragma("unroll") for (int m = 0; m < 4; ++m) _Pragma("unroll") for (int k = 0; k < 2; ++k) dst[m][k] = *(const PG8_LAS bf16x8*)(lds + PG8_SA(b, h) + aoff + m * 2048 + k * 1024); } while (0)
; template <bool FP8, class Epi, class Sched>
; __device__ __forceinline__ void gemm_phase(PG8_LAS unsigned char* lds, const Gemm g, const Sched& S, const Epi& E) {
;     ...
;             PG8_LDA(At, 1, 1); PG8_STAGE(PG8_SA(1, 0), a3, voffA);
;             PG8_BAR; PG8_WAIT_L(0); PG8_MMA(1, 0, At, B0); PG8_BAR; PG8_SCHED;
;             PG8_STAGE(PG8_SB(1, 1), b3 + hstep, voffB);
;             PG8_WAIT_V(6); PG8_BAR; PG8_MMA(1, 1, At, B1); PG8_BAR;
;         }
;         if constexpr (FP8) asm volatile("s_nop 15\n\ts_nop 15" ::: "memory");
;   DI void operator()(const f32x4 (&acc)[2][2][4][2], const pg8::Unit& u, int wr, int wc, int fr, int fq) const {
;     ...
;           const int col = colb + bj * 128;
;           f32x4 v0 = acc[ai][bj][m][0] * sc, v1 = acc[ai][bj][m][1] * sc;
;           u16* dst = nullptr;
;           if (MODE == 0) { if (col < N) dst = d0 + (size_t)row * ld0 + (col + coff2 + ((col < csplit) ? (coff1 - coff2) : 0)); }
;           else if (MODE == 1) {
;             const int oc = col + coff2 + ((col < csplit) ? (coff1 - coff2) : 0);
;             if (col < N) {
;               if (oc < 2048) dst = d0 + (size_t)row * 2048 + oc;
;               else if (oc < 2112) { rot(v0, v1, row, oc); dst = d2 + (size_t)row * 64 + (oc - 2048); }
;               else dst = d1 + (size_t)row * 4096 + (oc - 2112);
;             }
;           } else if (MODE == 3) {
;             if (col < N) { const bool lo = col < csplit; u16* bp = lo ? d0 : d1; const int ldd = lo ? 2048 : 4096, oc = lo ? col : col + (coff2 - 2112); dst = bp + (size_t)row * ldd + oc + (lo ? coff1 : 0); }
;           } else {
;             if (((col >> 6) % 3) == 2) rot(v0, v1, row, col);
;             dst = d0 + (size_t)row * 3072 + col;
;           }
;           if (dst) { u32x4 w = {pk2(v0[0], v0[1]), pk2(v0[2], v0[3]), pk2(v1[0], v1[1]), pk2(v1[2], v1[3])}; *(u32x4*)dst = w; }
	ds_read_b128 v[18:21], v182 offset:49152
	ds_read_b128 v[22:25], v182 offset:50176
	ds_read_b128 v[184:187], v182 offset:51200
	ds_read_b128 v[188:191], v182 offset:52224
	ds_read_b128 v[192:195], v182 offset:53248
	ds_read_b128 v[196:199], v182 offset:54272
	ds_read_b128 v[200:203], v182 offset:55296
	ds_read_b128 v[204:207], v182 offset:56320
	global_load_lds_dwordx4 v[164:165], off
	v_lshl_add_u64 v[164:165], v[170:171], 0, s[56:57]
	s_mov_b32 m0, s72
	s_nop 0
	global_load_lds_dwordx4 v[164:165], off
	s_barrier
	s_waitcnt lgkmcnt(0)
	s_waitcnt lgkmcnt(0)
	s_nop 1
	v_mfma_scale_f32_16x16x128_f8f6f4 v[86:89], v[2:9], v[18:25], v[86:89], v172, v172 op_sel_hi:[0,0,0]
	s_nop 1
	v_mfma_scale_f32_16x16x128_f8f6f4 v[82:85], v[10:17], v[18:25], v[82:85], v172, v172 op_sel_hi:[0,0,0]
	s_nop 1
	v_mfma_scale_f32_16x16x128_f8f6f4 v[70:73], v[2:9], v[184:191], v[70:73], v172, v172 op_sel_hi:[0,0,0]
	s_nop 1
	v_mfma_scale_f32_16x16x128_f8f6f4 v[66:69], v[10:17], v[184:191], v[66:69], v172, v172 op_sel_hi:[0,0,0]
	s_nop 1
	v_mfma_scale_f32_16x16x128_f8f6f4 v[54:57], v[2:9], v[192:199], v[54:57], v172, v172 op_sel_hi:[0,0,0]
	s_nop 1
	v_mfma_scale_f32_16x16x128_f8f6f4 v[50:53], v[10:17], v[192:199], v[50:53], v172, v172 op_sel_hi:[0,0,0]
	s_nop 1
	v_mfma_scale_f32_16x16x128_f8f6f4 v[38:41], v[2:9], v[200:207], v[38:41], v172, v172 op_sel_hi:[0,0,0]
	s_nop 1
	v_mfma_scale_f32_16x16x128_f8f6f4 v[34:37], v[10:17], v[200:207], v[34:37], v172, v172 op_sel_hi:[0,0,0]
	s_barrier
	s_add_u32 s10, s10, 0x40080
	s_addc_u32 s11, s11, 0
	s_add_i32 s30, s30, s25
	v_lshl_add_u64 v[2:3], s[10:11], 0, v[0:1]
	s_mov_b32 m0, s30
	s_nop 0
	global_load_lds_dwordx4 v[2:3], off
	v_lshl_add_u64 v[2:3], s[10:11], 0, v[158:159]
	s_add_i32 m0, s30, 0x2000
	s_nop 0
	global_load_lds_dwordx4 v[2:3], off
	s_waitcnt vmcnt(6)
	s_barrier
	s_nop 1
	v_mfma_scale_f32_16x16x128_f8f6f4 v[78:81], v[208:215], v[18:25], v[78:81], v172, v172 op_sel_hi:[0,0,0]
	s_nop 1
	v_mfma_scale_f32_16x16x128_f8f6f4 v[74:77], v[236:243], v[18:25], v[74:77], v172, v172 op_sel_hi:[0,0,0]
	s_nop 1
	v_mfma_scale_f32_16x16x128_f8f6f4 v[62:65], v[208:215], v[184:191], v[62:65], v172, v172 op_sel_hi:[0,0,0]
	s_nop 1
	v_mfma_scale_f32_16x16x128_f8f6f4 v[58:61], v[236:243], v[184:191], v[58:61], v172, v172 op_sel_hi:[0,0,0]
	s_nop 1
	v_mfma_scale_f32_16x16x128_f8f6f4 v[46:49], v[208:215], v[192:199], v[46:49], v172, v172 op_sel_hi:[0,0,0]
	s_nop 1
	v_mfma_scale_f32_16x16x128_f8f6f4 v[42:45], v[236:243], v[192:199], v[42:45], v172, v172 op_sel_hi:[0,0,0]
	s_nop 1
	v_mfma_scale_f32_16x16x128_f8f6f4 v[30:33], v[208:215], v[200:207], v[30:33], v172, v172 op_sel_hi:[0,0,0]
	s_nop 1
	v_mfma_scale_f32_16x16x128_f8f6f4 v[26:29], v[236:243], v[200:207], v[26:29], v172, v172 op_sel_hi:[0,0,0]
	s_add_i32 vcc_hi, vcc_hi, 2
	s_add_u32 s0, s0, 0x100
	s_addc_u32 s1, s1, 0
	s_add_u32 s95, s95, 0x100
	s_addc_u32 vcc_lo, vcc_lo, 0
	s_cmp_gt_u32 vcc_hi, 13
	s_barrier
	s_cbranch_scc0 .LBB0_226
	s_nop 15
	s_nop 15
	v_lshl_or_b32 v2, s28, 8, v175
	v_lshl_add_u32 v8, s29, 8, v173
	v_cmp_gt_i32_e32 vcc, s34, v2
	v_mov_b64_e32 v[4:5], 0
	v_add_u32_e32 v6, 0x200, v2
	s_and_saveexec_b64 s[10:11], vcc
	v_mov_b64_e32 v[4:5], s[96:97]
	s_movk_i32 s0, 0x3400
	v_mad_i64_i32 v[4:5], s[0:1], v8, s0, v[4:5]
	s_movk_i32 s0, 0x800
	s_nop 0
	v_cmp_gt_i32_e64 s[0:1], s0, v2
	s_nop 1
	v_cndmask_b32_e64 v10, v6, v2, s[0:1]
	v_ashrrev_i32_e32 v11, 31, v10
	v_lshl_add_u64 v[4:5], v[10:11], 1, v[4:5]
	s_or_b64 exec, exec, s[10:11]
	v_cmp_ne_u64_e64 s[0:1], 0, v[4:5]
	s_and_saveexec_b64 s[10:11], s[0:1]
	s_movk_i32 s20, 0x600
	s_mov_b32 s86, 0x800000
	s_movk_i32 s87, 0x3fff
	v_readlane_b32 s3, v254, 29
	s_cbranch_execz .LBB0_231
	v_pk_mul_f32 v[12:13], v[152:153], s[88:89] op_sel_hi:[1,0]
	v_pk_mul_f32 v[10:11], v[150:151], s[88:89] op_sel_hi:[1,0]
	v_pk_mul_f32 v[14:15], v[148:149], s[88:89] op_sel_hi:[1,0]
	v_pk_mul_f32 v[16:17], v[146:147], s[88:89] op_sel_hi:[1,0]
	v_cvt_pk_bf16_f32 v10, v10, v11
	v_cvt_pk_bf16_f32 v11, v12, v13
	v_cvt_pk_bf16_f32 v12, v16, v17
	v_cvt_pk_bf16_f32 v13, v14, v15
	global_store_dwordx4 v[4:5], v[10:13], off

; #define PG8_STAGE(bufoff, gbase, voff) do { _Pragma("unroll") for (int _i = 0; _i < 2; ++_i) \
;         __builtin_amdgcn_global_load_lds((const unsigned*)((const char*)(gbase) + (voff)[_i]), (PG8_LAS unsigned*)(lds + (bufoff) + ldsw + _i * 8192), 16, 0, 0); } while (0)
; #define PG8_LDA(dst, b, h) do { _Pragma("unroll") for (int m = 0; m < 4; ++m) _Pragma("unroll") for (int k = 0; k < 2; ++k) dst[m][k] = *(const PG8_LAS bf16x8*)(lds + PG8_SA(b, h) + aoff + m * 2048 + k * 1024); } while (0)
; #define PG8_LDB(dst, b, h) do { _Pragma("unroll") for (int n = 0; n < 2; ++n) _Pragma("unroll") for (int k = 0; k < 2; ++k) dst[n][k] = *(const PG8_LAS bf16x8*)(lds + PG8_SB(b, h) + boff + n * 2048 + k * 1024); } while (0)
; #define PG8_WAIT_L(n) asm volatile("s_waitcnt lgkmcnt(" #n ")" ::: "memory")
; #define PG8_BAR __builtin_amdgcn_s_barrier()
; #define PG8_SCHED __builtin_amdgcn_sched_barrier(0)
; template <bool FP8, class Epi, class Sched>
; __device__ __forceinline__ void gemm_phase(PG8_LAS unsigned char* lds, const Gemm g, const Sched& S, const Epi& E) {
;     ...
;             PG8_LDB(B0, 0, 0); PG8_SCHED; PG8_LDA(At, 0, 0); PG8_STAGE(PG8_SA(1, 1), a1 + hstepA, voffA);
;             PG8_WAIT_L(8); PG8_BAR; PG8_WAIT_L(0); PG8_MMA(0, 0, At, B0); PG8_BAR; PG8_SCHED;
;             PG8_LDB(B1, 0, 1); PG8_STAGE(PG8_SB(0, 0), b2, voffB);
;             PG8_BAR; PG8_WAIT_L(0); PG8_MMA(0, 1, At, B1); PG8_BAR;
;             PG8_LDA(At, 0, 1); PG8_STAGE(PG8_SA(0, 0), a2, voffA);
;             PG8_BAR; PG8_WAIT_L(0); PG8_MMA(1, 0, At, B0); PG8_BAR; PG8_SCHED;
.LBB0_304:
	s_add_u32 s12, s0, 0xfff80080
	s_addc_u32 s13, s1, -1
	s_add_i32 s30, 0, 0x10000
	v_add_u32_e32 v140, s30, v143
	ds_read_b128 v[146:149], v140
	ds_read_b128 v[150:153], v140 offset:1024
	ds_read_b128 v[154:157], v140 offset:2048
	ds_read_b128 v[158:161], v140 offset:3072
	s_cmp_eq_u32 vcc_hi, 28
	s_cselect_b32 s69, s17, s13
	s_cselect_b32 s68, s87, s12
	s_cselect_b32 s13, s15, vcc_lo
	s_cselect_b32 s12, s94, s95
	v_lshl_add_u64 v[140:141], s[0:1], 0, v[136:137]
	s_add_i32 m0, s26, 0xc000
	ds_read_b128 v[162:165], v145
	ds_read_b128 v[166:169], v145 offset:1024
	ds_read_b128 v[170:173], v145 offset:2048
	ds_read_b128 v[182:185], v145 offset:3072
	ds_read_b128 v[186:189], v145 offset:4096
	ds_read_b128 v[190:193], v145 offset:5120
	ds_read_b128 v[194:197], v145 offset:6144
	ds_read_b128 v[198:201], v145 offset:7168
	global_load_lds_dwordx4 v[140:141], off
	v_lshl_add_u64 v[140:141], s[0:1], 0, v[138:139]
	s_add_i32 m0, s26, 0xe000
	s_nop 0
	global_load_lds_dwordx4 v[140:141], off
	s_waitcnt lgkmcnt(8)
	s_barrier
	s_waitcnt lgkmcnt(0)
	s_waitcnt lgkmcnt(0)
	v_mfma_f32_16x16x32_bf16 v[126:129], v[146:149], v[162:165], v[126:129]
	v_mfma_f32_16x16x32_bf16 v[122:125], v[154:157], v[162:165], v[122:125]
	v_mfma_f32_16x16x32_bf16 v[110:113], v[146:149], v[170:173], v[110:113]
	v_mfma_f32_16x16x32_bf16 v[106:109], v[154:157], v[170:173], v[106:109]
	v_mfma_f32_16x16x32_bf16 v[94:97], v[146:149], v[186:189], v[94:97]
	v_mfma_f32_16x16x32_bf16 v[90:93], v[154:157], v[186:189], v[90:93]
	v_mfma_f32_16x16x32_bf16 v[78:81], v[146:149], v[194:197], v[78:81]
	v_mfma_f32_16x16x32_bf16 v[74:77], v[154:157], v[194:197], v[74:77]
	v_mfma_f32_16x16x32_bf16 v[126:129], v[150:153], v[166:169], v[126:129]
	v_mfma_f32_16x16x32_bf16 v[122:125], v[158:161], v[166:169], v[122:125]
	v_mfma_f32_16x16x32_bf16 v[110:113], v[150:153], v[182:185], v[110:113]
	v_mfma_f32_16x16x32_bf16 v[106:109], v[158:161], v[182:185], v[106:109]
	v_mfma_f32_16x16x32_bf16 v[94:97], v[150:153], v[190:193], v[94:97]
	v_mfma_f32_16x16x32_bf16 v[90:93], v[158:161], v[190:193], v[90:93]
	v_mfma_f32_16x16x32_bf16 v[78:81], v[150:153], v[198:201], v[78:81]
	v_mfma_f32_16x16x32_bf16 v[74:77], v[158:161], v[198:201], v[74:77]
	s_barrier
	s_add_i32 s86, 0, 0x14000
	v_add_u32_e32 v140, s86, v143
	s_add_i32 s30, s30, s25
	ds_read_b128 v[202:205], v140
	ds_read_b128 v[206:209], v140 offset:1024
	ds_read_b128 v[210:213], v140 offset:2048
	ds_read_b128 v[214:217], v140 offset:3072
	v_lshl_add_u64 v[140:141], s[12:13], 0, v[0:1]
	s_mov_b32 m0, s30
	v_lshl_add_u64 v[174:175], s[12:13], 0, v[130:131]
	global_load_lds_dwordx4 v[140:141], off
	s_add_i32 m0, s30, 0x2000
	s_nop 0
	global_load_lds_dwordx4 v[174:175], off
	s_barrier
	s_waitcnt lgkmcnt(0)
	s_waitcnt lgkmcnt(0)
	v_mfma_f32_16x16x32_bf16 v[118:121], v[202:205], v[162:165], v[118:121]
	v_mfma_f32_16x16x32_bf16 v[114:117], v[210:213], v[162:165], v[114:117]
	v_mfma_f32_16x16x32_bf16 v[102:105], v[202:205], v[170:173], v[102:105]
	v_mfma_f32_16x16x32_bf16 v[98:101], v[210:213], v[170:173], v[98:101]
	v_mfma_f32_16x16x32_bf16 v[86:89], v[202:205], v[186:189], v[86:89]
	v_mfma_f32_16x16x32_bf16 v[82:85], v[210:213], v[186:189], v[82:85]
	v_mfma_f32_16x16x32_bf16 v[70:73], v[202:205], v[194:197], v[70:73]
	v_mfma_f32_16x16x32_bf16 v[66:69], v[210:213], v[194:197], v[66:69]
	v_mfma_f32_16x16x32_bf16 v[118:121], v[206:209], v[166:169], v[118:121]
	v_mfma_f32_16x16x32_bf16 v[114:117], v[214:217], v[166:169], v[114:117]
	v_mfma_f32_16x16x32_bf16 v[102:105], v[206:209], v[182:185], v[102:105]
	v_mfma_f32_16x16x32_bf16 v[98:101], v[214:217], v[182:185], v[98:101]
	v_mfma_f32_16x16x32_bf16 v[86:89], v[206:209], v[190:193], v[86:89]
	v_mfma_f32_16x16x32_bf16 v[82:85], v[214:217], v[190:193], v[82:85]
	v_mfma_f32_16x16x32_bf16 v[70:73], v[206:209], v[198:201], v[70:73]
	v_mfma_f32_16x16x32_bf16 v[66:69], v[214:217], v[198:201], v[66:69]
	s_mov_b32 m0, s26
	v_lshl_add_u64 v[236:237], s[68:69], 0, v[134:135]
	s_barrier
	ds_read_b128 v[162:165], v145 offset:16384
	ds_read_b128 v[166:169], v145 offset:17408
	ds_read_b128 v[170:173], v145 offset:18432
	ds_read_b128 v[182:185], v145 offset:19456
	ds_read_b128 v[186:189], v145 offset:20480
	ds_read_b128 v[190:193], v145 offset:21504
	ds_read_b128 v[194:197], v145 offset:22528
	ds_read_b128 v[198:201], v145 offset:23552
	global_load_lds_dwordx4 v[236:237], off
	v_lshl_add_u64 v[238:239], s[68:69], 0, v[132:133]
	s_mov_b32 m0, s27
	s_nop 0
	global_load_lds_dwordx4 v[238:239], off
	s_barrier
	s_waitcnt lgkmcnt(0)
	s_waitcnt lgkmcnt(0)
	v_mfma_f32_16x16x32_bf16 v[62:65], v[146:149], v[162:165], v[62:65]
	v_mfma_f32_16x16x32_bf16 v[58:61], v[154:157], v[162:165], v[58:61]
	v_mfma_f32_16x16x32_bf16 v[46:49], v[146:149], v[170:173], v[46:49]
	v_mfma_f32_16x16x32_bf16 v[42:45], v[154:157], v[170:173], v[42:45]
	v_mfma_f32_16x16x32_bf16 v[30:33], v[146:149], v[186:189], v[30:33]
	v_mfma_f32_16x16x32_bf16 v[26:29], v[154:157], v[186:189], v[26:29]
	v_mfma_f32_16x16x32_bf16 v[14:17], v[146:149], v[194:197], v[14:17]
	v_mfma_f32_16x16x32_bf16 v[10:13], v[154:157], v[194:197], v[10:13]
	v_mfma_f32_16x16x32_bf16 v[62:65], v[150:153], v[166:169], v[62:65]
	v_mfma_f32_16x16x32_bf16 v[58:61], v[158:161], v[166:169], v[58:61]
	v_mfma_f32_16x16x32_bf16 v[46:49], v[150:153], v[182:185], v[46:49]
	v_mfma_f32_16x16x32_bf16 v[42:45], v[158:161], v[182:185], v[42:45]
	v_mfma_f32_16x16x32_bf16 v[30:33], v[150:153], v[190:193], v[30:33]
	v_mfma_f32_16x16x32_bf16 v[26:29], v[158:161], v[190:193], v[26:29]
	v_mfma_f32_16x16x32_bf16 v[14:17], v[150:153], v[198:201], v[14:17]
	v_mfma_f32_16x16x32_bf16 v[10:13], v[158:161], v[198:201], v[10:13]
	s_barrier
; #define PG8_STAGE(bufoff, gbase, voff) do { _Pragma("unroll") for (int _i = 0; _i < 2; ++_i) \
;         __builtin_amdgcn_global_load_lds((const unsigned*)((const char*)(gbase) + (voff)[_i]), (PG8_LAS unsigned*)(lds + (bufoff) + ldsw + _i * 8192), 16, 0, 0); } while (0)
; #define PG8_LDA(dst, b, h) do { _Pragma("unroll") for (int m = 0; m < 4; ++m) _Pragma("unroll") for (int k = 0; k < 2; ++k) dst[m][k] = *(const PG8_LAS bf16x8*)(lds + PG8_SA(b, h) + aoff + m * 2048 + k * 1024); } while (0)
; #define PG8_LDB(dst, b, h) do { _Pragma("unroll") for (int n = 0; n < 2; ++n) _Pragma("unroll") for (int k = 0; k < 2; ++k) dst[n][k] = *(const PG8_LAS bf16x8*)(lds + PG8_SB(b, h) + boff + n * 2048 + k * 1024); } while (0)
; #define PG8_WAIT_V(n) asm volatile("s_waitcnt vmcnt(" #n ")" ::: "memory")
; #define PG8_WAIT_L(n) asm volatile("s_waitcnt lgkmcnt(" #n ")" ::: "memory")
; #define PG8_BAR __builtin_amdgcn_s_barrier()
; #define PG8_SCHED __builtin_amdgcn_sched_barrier(0)
; template <bool FP8, class Epi, class Sched>
; __device__ __forceinline__ void gemm_phase(PG8_LAS unsigned char* lds, const Gemm g, const Sched& S, const Epi& E) {
;     ...
;             PG8_STAGE(PG8_SB(0, 1), b2 + hstep, voffB);
;             PG8_WAIT_V(6); PG8_BAR; PG8_MMA(1, 1, At, B1); PG8_BAR;
;             PG8_LDB(B0, 1, 0); PG8_SCHED; PG8_LDA(At, 1, 0); PG8_STAGE(PG8_SA(0, 1), a2 + hstepA, voffA);
;             PG8_WAIT_L(8); PG8_BAR; PG8_WAIT_L(0); PG8_MMA(0, 0, At, B0); PG8_BAR; PG8_SCHED;
;             PG8_LDB(B1, 1, 1); PG8_STAGE(PG8_SB(1, 0), b3, voffB);
;             PG8_BAR; PG8_WAIT_L(0); PG8_MMA(0, 1, At, B1); PG8_BAR;
	s_add_u32 s30, s12, 0x80000
	s_addc_u32 s31, s13, 0
	s_add_i32 s86, s86, s25
	v_lshl_add_u64 v[146:147], s[30:31], 0, v[0:1]
	s_mov_b32 m0, s86
	s_nop 0
	global_load_lds_dwordx4 v[146:147], off
	v_lshl_add_u64 v[146:147], s[30:31], 0, v[130:131]
	s_add_i32 m0, s86, 0x2000
	s_nop 0
	global_load_lds_dwordx4 v[146:147], off
	s_waitcnt vmcnt(6)
	s_barrier
	v_mfma_f32_16x16x32_bf16 v[54:57], v[202:205], v[162:165], v[54:57]
	v_mfma_f32_16x16x32_bf16 v[50:53], v[210:213], v[162:165], v[50:53]
	v_mfma_f32_16x16x32_bf16 v[38:41], v[202:205], v[170:173], v[38:41]
	v_mfma_f32_16x16x32_bf16 v[34:37], v[210:213], v[170:173], v[34:37]
	v_mfma_f32_16x16x32_bf16 v[22:25], v[202:205], v[186:189], v[22:25]
	v_mfma_f32_16x16x32_bf16 v[18:21], v[210:213], v[186:189], v[18:21]
	v_mfma_f32_16x16x32_bf16 v[6:9], v[202:205], v[194:197], v[6:9]
	v_mfma_f32_16x16x32_bf16 v[2:5], v[210:213], v[194:197], v[2:5]
	v_mfma_f32_16x16x32_bf16 v[54:57], v[206:209], v[166:169], v[54:57]
	v_mfma_f32_16x16x32_bf16 v[50:53], v[214:217], v[166:169], v[50:53]
	v_mfma_f32_16x16x32_bf16 v[38:41], v[206:209], v[182:185], v[38:41]
	v_mfma_f32_16x16x32_bf16 v[34:37], v[214:217], v[182:185], v[34:37]
	v_mfma_f32_16x16x32_bf16 v[22:25], v[206:209], v[190:193], v[22:25]
	v_mfma_f32_16x16x32_bf16 v[18:21], v[214:217], v[190:193], v[18:21]
	v_mfma_f32_16x16x32_bf16 v[6:9], v[206:209], v[198:201], v[6:9]
	v_mfma_f32_16x16x32_bf16 v[2:5], v[214:217], v[198:201], v[2:5]
	s_add_i32 s86, 0, 0x18000
	v_add_u32_e32 v158, s86, v143
	s_barrier
	ds_read_b128 v[146:149], v158
	ds_read_b128 v[150:153], v158 offset:1024
	ds_read_b128 v[154:157], v158 offset:2048
	ds_read_b128 v[158:161], v158 offset:3072
	s_add_u32 s30, s68, 0x80000
	s_addc_u32 s31, s69, 0
	s_mov_b32 m0, s54
	v_lshl_add_u64 v[202:203], s[30:31], 0, v[134:135]
	ds_read_b128 v[162:165], v145 offset:32768
	ds_read_b128 v[166:169], v145 offset:33792
	ds_read_b128 v[170:173], v145 offset:34816
	ds_read_b128 v[182:185], v145 offset:35840
	ds_read_b128 v[186:189], v145 offset:36864
	ds_read_b128 v[190:193], v145 offset:37888
	ds_read_b128 v[194:197], v145 offset:38912
	ds_read_b128 v[198:201], v145 offset:39936
	global_load_lds_dwordx4 v[202:203], off
	v_lshl_add_u64 v[202:203], s[30:31], 0, v[132:133]
	s_mov_b32 m0, s70
	s_nop 0
	global_load_lds_dwordx4 v[202:203], off
	s_waitcnt lgkmcnt(8)
	s_barrier
	s_waitcnt lgkmcnt(0)
	s_waitcnt lgkmcnt(0)
	v_mfma_f32_16x16x32_bf16 v[126:129], v[146:149], v[162:165], v[126:129]
	v_mfma_f32_16x16x32_bf16 v[122:125], v[154:157], v[162:165], v[122:125]
	v_mfma_f32_16x16x32_bf16 v[110:113], v[146:149], v[170:173], v[110:113]
	v_mfma_f32_16x16x32_bf16 v[106:109], v[154:157], v[170:173], v[106:109]
	v_mfma_f32_16x16x32_bf16 v[94:97], v[146:149], v[186:189], v[94:97]
	v_mfma_f32_16x16x32_bf16 v[90:93], v[154:157], v[186:189], v[90:93]
	v_mfma_f32_16x16x32_bf16 v[78:81], v[146:149], v[194:197], v[78:81]
	v_mfma_f32_16x16x32_bf16 v[74:77], v[154:157], v[194:197], v[74:77]
	v_mfma_f32_16x16x32_bf16 v[126:129], v[150:153], v[166:169], v[126:129]
	v_mfma_f32_16x16x32_bf16 v[122:125], v[158:161], v[166:169], v[122:125]
	v_mfma_f32_16x16x32_bf16 v[110:113], v[150:153], v[182:185], v[110:113]
	v_mfma_f32_16x16x32_bf16 v[106:109], v[158:161], v[182:185], v[106:109]
	v_mfma_f32_16x16x32_bf16 v[94:97], v[150:153], v[190:193], v[94:97]
	v_mfma_f32_16x16x32_bf16 v[90:93], v[158:161], v[190:193], v[90:93]
	v_mfma_f32_16x16x32_bf16 v[78:81], v[150:153], v[198:201], v[78:81]
	v_mfma_f32_16x16x32_bf16 v[74:77], v[158:161], v[198:201], v[74:77]
	s_barrier
	s_add_i32 s30, 0, 0x1c000
	s_add_i32 s31, s86, s25
	v_add_u32_e32 v214, s30, v143
	v_lshl_add_u64 v[140:141], v[140:141], 0, s[56:57]
	s_mov_b32 m0, s31
	ds_read_b128 v[202:205], v214
	ds_read_b128 v[206:209], v214 offset:1024
	ds_read_b128 v[210:213], v214 offset:2048
	ds_read_b128 v[214:217], v214 offset:3072
	global_load_lds_dwordx4 v[140:141], off
	v_lshl_add_u64 v[140:141], v[174:175], 0, s[56:57]
	s_add_i32 m0, s31, 0x2000
	s_nop 0
	global_load_lds_dwordx4 v[140:141], off
	s_barrier
	s_waitcnt lgkmcnt(0)
	s_waitcnt lgkmcnt(0)
	v_mfma_f32_16x16x32_bf16 v[118:121], v[202:205], v[162:165], v[118:121]
	v_mfma_f32_16x16x32_bf16 v[114:117], v[210:213], v[162:165], v[114:117]
	v_mfma_f32_16x16x32_bf16 v[102:105], v[202:205], v[170:173], v[102:105]
	v_mfma_f32_16x16x32_bf16 v[98:101], v[210:213], v[170:173], v[98:101]
	v_mfma_f32_16x16x32_bf16 v[86:89], v[202:205], v[186:189], v[86:89]
	v_mfma_f32_16x16x32_bf16 v[82:85], v[210:213], v[186:189], v[82:85]
	v_mfma_f32_16x16x32_bf16 v[70:73], v[202:205], v[194:197], v[70:73]
	v_mfma_f32_16x16x32_bf16 v[66:69], v[210:213], v[194:197], v[66:69]
	v_mfma_f32_16x16x32_bf16 v[118:121], v[206:209], v[166:169], v[118:121]
	v_mfma_f32_16x16x32_bf16 v[114:117], v[214:217], v[166:169], v[114:117]
	v_mfma_f32_16x16x32_bf16 v[102:105], v[206:209], v[182:185], v[102:105]
	v_mfma_f32_16x16x32_bf16 v[98:101], v[214:217], v[182:185], v[98:101]
	v_mfma_f32_16x16x32_bf16 v[86:89], v[206:209], v[190:193], v[86:89]
	v_mfma_f32_16x16x32_bf16 v[82:85], v[214:217], v[190:193], v[82:85]
	v_mfma_f32_16x16x32_bf16 v[70:73], v[206:209], v[198:201], v[70:73]
	v_mfma_f32_16x16x32_bf16 v[66:69], v[214:217], v[198:201], v[66:69]
	s_mov_b32 m0, s71
	v_lshl_add_u64 v[140:141], v[236:237], 0, s[56:57]
	s_barrier
; #define PG8_STAGE(bufoff, gbase, voff) do { _Pragma("unroll") for (int _i = 0; _i < 2; ++_i) \
;         __builtin_amdgcn_global_load_lds((const unsigned*)((const char*)(gbase) + (voff)[_i]), (PG8_LAS unsigned*)(lds + (bufoff) + ldsw + _i * 8192), 16, 0, 0); } while (0)
; #define PG8_BAR __builtin_amdgcn_s_barrier()
; template <bool FP8, class Epi, class Sched>
; __device__ __forceinline__ void gemm_phase(PG8_LAS unsigned char* lds, const Gemm g, const Sched& S, const Epi& E) {
;     ...
;             PG8_LDA(At, 1, 1); PG8_STAGE(PG8_SA(1, 0), a3, voffA);
;             PG8_BAR; PG8_WAIT_L(0); PG8_MMA(1, 0, At, B0); PG8_BAR; PG8_SCHED;
;             PG8_STAGE(PG8_SB(1, 1), b3 + hstep, voffB);
;             PG8_WAIT_V(6); PG8_BAR; PG8_MMA(1, 1, At, B1); PG8_BAR;
;   DI void operator()(const f32x4 (&acc)[2][2][4][2], const pg8::Unit& u, int wr, int wc, int fr, int fq) const {
;     const int row0 = u.pm * 256 + wr * 64 + fr, colb = u.pn * 256 + wc * 32 + 8 * fq;
; #pragma unroll
;     for (int ai = 0; ai < 2; ++ai)
; #pragma unroll
;       for (int m = 0; m < 4; ++m) {
;         const int row = row0 + ai * 128 + m * 16;
; #pragma unroll
;         for (int bj = 0; bj < 2; ++bj) {
;           const int col = colb + bj * 128;
;           f32x4 v0 = acc[ai][bj][m][0] * sc, v1 = acc[ai][bj][m][1] * sc;
;           u16* dst = nullptr;
;           if (MODE == 0) { if (col < N) dst = d0 + (size_t)row * ld0 + (col + coff2 + ((col < csplit) ? (coff1 - coff2) : 0)); }
;           else if (MODE == 1) {
;             const int oc = col + coff2 + ((col < csplit) ? (coff1 - coff2) : 0);
;             if (col < N) {
;               if (oc < 2048) dst = d0 + (size_t)row * 2048 + oc;
;               else if (oc < 2112) { rot(v0, v1, row, oc); dst = d2 + (size_t)row * 64 + (oc - 2048); }
;               else dst = d1 + (size_t)row * 4096 + (oc - 2112);
;             }
;           } else if (MODE == 3) {
;             if (col < N) { const bool lo = col < csplit; u16* bp = lo ? d0 : d1; const int ldd = lo ? 2048 : 4096, oc = lo ? col : col + (coff2 - 2112); dst = bp + (size_t)row * ldd + oc + (lo ? coff1 : 0); }
;           } else {
;             if (((col >> 6) % 3) == 2) rot(v0, v1, row, col);
;             dst = d0 + (size_t)row * 3072 + col;
;           }
;           if (dst) { u32x4 w = {pk2(v0[0], v0[1]), pk2(v0[2], v0[3]), pk2(v1[0], v1[1]), pk2(v1[2], v1[3])}; *(u32x4*)dst = w; }
	ds_read_b128 v[162:165], v145 offset:49152
	ds_read_b128 v[166:169], v145 offset:50176
	ds_read_b128 v[170:173], v145 offset:51200
	ds_read_b128 v[182:185], v145 offset:52224
	ds_read_b128 v[186:189], v145 offset:53248
	ds_read_b128 v[190:193], v145 offset:54272
	ds_read_b128 v[194:197], v145 offset:55296
	ds_read_b128 v[198:201], v145 offset:56320
	global_load_lds_dwordx4 v[140:141], off
	v_lshl_add_u64 v[140:141], v[238:239], 0, s[56:57]
	s_mov_b32 m0, s72
	s_nop 0
	global_load_lds_dwordx4 v[140:141], off
	s_barrier
	s_waitcnt lgkmcnt(0)
	s_waitcnt lgkmcnt(0)
	v_mfma_f32_16x16x32_bf16 v[62:65], v[146:149], v[162:165], v[62:65]
	v_mfma_f32_16x16x32_bf16 v[58:61], v[154:157], v[162:165], v[58:61]
	v_mfma_f32_16x16x32_bf16 v[46:49], v[146:149], v[170:173], v[46:49]
	v_mfma_f32_16x16x32_bf16 v[42:45], v[154:157], v[170:173], v[42:45]
	v_mfma_f32_16x16x32_bf16 v[30:33], v[146:149], v[186:189], v[30:33]
	v_mfma_f32_16x16x32_bf16 v[26:29], v[154:157], v[186:189], v[26:29]
	v_mfma_f32_16x16x32_bf16 v[14:17], v[146:149], v[194:197], v[14:17]
	v_mfma_f32_16x16x32_bf16 v[10:13], v[154:157], v[194:197], v[10:13]
	v_mfma_f32_16x16x32_bf16 v[62:65], v[150:153], v[166:169], v[62:65]
	v_mfma_f32_16x16x32_bf16 v[58:61], v[158:161], v[166:169], v[58:61]
	v_mfma_f32_16x16x32_bf16 v[46:49], v[150:153], v[182:185], v[46:49]
	v_mfma_f32_16x16x32_bf16 v[42:45], v[158:161], v[182:185], v[42:45]
	v_mfma_f32_16x16x32_bf16 v[30:33], v[150:153], v[190:193], v[30:33]
	v_mfma_f32_16x16x32_bf16 v[26:29], v[158:161], v[190:193], v[26:29]
	v_mfma_f32_16x16x32_bf16 v[14:17], v[150:153], v[198:201], v[14:17]
	v_mfma_f32_16x16x32_bf16 v[10:13], v[158:161], v[198:201], v[10:13]
	s_barrier
	s_add_u32 s12, s12, 0x80080
	s_addc_u32 s13, s13, 0
	s_add_i32 s30, s30, s25
	v_lshl_add_u64 v[140:141], s[12:13], 0, v[0:1]
	s_mov_b32 m0, s30
	s_nop 0
	global_load_lds_dwordx4 v[140:141], off
	v_lshl_add_u64 v[140:141], s[12:13], 0, v[130:131]
	s_add_i32 m0, s30, 0x2000
	s_nop 0
	global_load_lds_dwordx4 v[140:141], off
	s_waitcnt vmcnt(6)
	s_barrier
	v_mfma_f32_16x16x32_bf16 v[54:57], v[202:205], v[162:165], v[54:57]
	v_mfma_f32_16x16x32_bf16 v[50:53], v[210:213], v[162:165], v[50:53]
	v_mfma_f32_16x16x32_bf16 v[38:41], v[202:205], v[170:173], v[38:41]
	v_mfma_f32_16x16x32_bf16 v[34:37], v[210:213], v[170:173], v[34:37]
	v_mfma_f32_16x16x32_bf16 v[22:25], v[202:205], v[186:189], v[22:25]
	v_mfma_f32_16x16x32_bf16 v[18:21], v[210:213], v[186:189], v[18:21]
	v_mfma_f32_16x16x32_bf16 v[6:9], v[202:205], v[194:197], v[6:9]
	v_mfma_f32_16x16x32_bf16 v[2:5], v[210:213], v[194:197], v[2:5]
	v_mfma_f32_16x16x32_bf16 v[54:57], v[206:209], v[166:169], v[54:57]
	v_mfma_f32_16x16x32_bf16 v[50:53], v[214:217], v[166:169], v[50:53]
	v_mfma_f32_16x16x32_bf16 v[38:41], v[206:209], v[182:185], v[38:41]
	v_mfma_f32_16x16x32_bf16 v[34:37], v[214:217], v[182:185], v[34:37]
	v_mfma_f32_16x16x32_bf16 v[22:25], v[206:209], v[190:193], v[22:25]
	v_mfma_f32_16x16x32_bf16 v[18:21], v[214:217], v[190:193], v[18:21]
	v_mfma_f32_16x16x32_bf16 v[6:9], v[206:209], v[198:201], v[6:9]
	v_mfma_f32_16x16x32_bf16 v[2:5], v[214:217], v[198:201], v[2:5]
	s_add_i32 vcc_hi, vcc_hi, 2
	s_add_u32 s0, s0, 0x100
	s_addc_u32 s1, s1, 0
	s_add_u32 s95, s95, 0x100
	s_addc_u32 vcc_lo, vcc_lo, 0
	s_cmp_gt_u32 vcc_hi, 29
	s_barrier
	s_cbranch_scc0 .LBB0_304
	v_lshl_or_b32 v146, s29, 8, v144
	s_movk_i32 s0, 0x1250
	v_lshl_add_u32 v147, s73, 8, v142
	v_cmp_gt_i32_e32 vcc, s0, v146
	v_mov_b64_e32 v[140:141], 0
	s_and_saveexec_b64 s[12:13], vcc
	v_mov_b64_e32 v[140:141], s[96:97]
	s_movk_i32 s0, 0x3d00
	v_mad_i64_i32 v[140:141], s[0:1], v147, s0, v[140:141]
	s_movk_i32 s0, 0x650
	s_nop 0
	v_cmp_gt_i32_e64 s[0:1], s0, v146
	s_nop 1
	v_cndmask_b32_e64 v148, 0, v227, s[0:1]
	v_add3_u32 v148, v146, v148, s34
	v_ashrrev_i32_e32 v149, 31, v148
	v_lshl_add_u64 v[140:141], v[148:149], 1, v[140:141]
	s_or_b64 exec, exec, s[12:13]
	v_cmp_ne_u64_e64 s[0:1], 0, v[140:141]
	s_and_saveexec_b64 s[12:13], s[0:1]
	s_movk_i32 s20, 0x600
	s_mov_b32 s86, 0x800000
	s_movk_i32 s87, 0x3fff
	v_readlane_b32 s3, v254, 29
	s_cbranch_execz .LBB0_309
	v_cvt_pk_bf16_f32 v126, v126, v127
	v_cvt_pk_bf16_f32 v127, v128, v129
	v_cvt_pk_bf16_f32 v128, v122, v123
	v_cvt_pk_bf16_f32 v129, v124, v125
	global_store_dwordx4 v[140:141], v[126:129], off

; #define PG8_STAGE(bufoff, gbase, voff) do { _Pragma("unroll") for (int _i = 0; _i < 2; ++_i) \
;         __builtin_amdgcn_global_load_lds((const unsigned*)((const char*)(gbase) + (voff)[_i]), (PG8_LAS unsigned*)(lds + (bufoff) + ldsw + _i * 8192), 16, 0, 0); } while (0)
; #define PG8_LDA(dst, b, h) do { _Pragma("unroll") for (int m = 0; m < 4; ++m) _Pragma("unroll") for (int k = 0; k < 2; ++k) dst[m][k] = *(const PG8_LAS bf16x8*)(lds + PG8_SA(b, h) + aoff + m * 2048 + k * 1024); } while (0)
; #define PG8_LDB(dst, b, h) do { _Pragma("unroll") for (int n = 0; n < 2; ++n) _Pragma("unroll") for (int k = 0; k < 2; ++k) dst[n][k] = *(const PG8_LAS bf16x8*)(lds + PG8_SB(b, h) + boff + n * 2048 + k * 1024); } while (0)
; #define PG8_WAIT_V(n) asm volatile("s_waitcnt vmcnt(" #n ")" ::: "memory")
; #define PG8_WAIT_L(n) asm volatile("s_waitcnt lgkmcnt(" #n ")" ::: "memory")
; #define PG8_BAR __builtin_amdgcn_s_barrier()
; #define PG8_SCHED __builtin_amdgcn_sched_barrier(0)
; template <bool FP8, class Epi, class Sched>
; __device__ __forceinline__ void gemm_phase(PG8_LAS unsigned char* lds, const Gemm g, const Sched& S, const Epi& E) {
;     ...
;             PG8_LDB(B0, 0, 0); PG8_SCHED; PG8_LDA(At, 0, 0); PG8_STAGE(PG8_SA(1, 1), a1 + hstepA, voffA);
;             PG8_WAIT_L(8); PG8_BAR; PG8_WAIT_L(0); PG8_MMA(0, 0, At, B0); PG8_BAR; PG8_SCHED;
;             PG8_LDB(B1, 0, 1); PG8_STAGE(PG8_SB(0, 0), b2, voffB);
;             PG8_BAR; PG8_WAIT_L(0); PG8_MMA(0, 1, At, B1); PG8_BAR;
;             PG8_LDA(At, 0, 1); PG8_STAGE(PG8_SA(0, 0), a2, voffA);
;             PG8_BAR; PG8_WAIT_L(0); PG8_MMA(1, 0, At, B0); PG8_BAR; PG8_SCHED;
;             PG8_STAGE(PG8_SB(0, 1), b2 + hstep, voffB);
;             PG8_WAIT_V(6); PG8_BAR; PG8_MMA(1, 1, At, B1); PG8_BAR;
;             PG8_LDB(B0, 1, 0); PG8_SCHED; PG8_LDA(At, 1, 0); PG8_STAGE(PG8_SA(0, 1), a2 + hstepA, voffA);
.LBB0_381:
	s_add_u32 s12, s0, 0xfffc0080
	s_addc_u32 s13, s1, -1
	s_add_i32 s30, 0, 0x10000
	v_add_u32_e32 v6, s30, v174
	ds_read_b128 v[10:13], v6
	ds_read_b128 v[14:17], v6 offset:1024
	ds_read_b128 v[2:5], v6 offset:2048
	ds_read_b128 v[6:9], v6 offset:3072
	s_cmp_eq_u32 vcc_hi, 12
	s_cselect_b32 s69, s17, s13
	s_cselect_b32 s68, s87, s12
	s_cselect_b32 s13, s15, vcc_lo
	s_cselect_b32 s12, s94, s95
	v_lshl_add_u64 v[18:19], s[0:1], 0, v[160:161]
	s_add_i32 m0, s26, 0xc000
	ds_read_b128 v[184:187], v182
	ds_read_b128 v[188:191], v182 offset:1024
	ds_read_b128 v[192:195], v182 offset:2048
	ds_read_b128 v[196:199], v182 offset:3072
	ds_read_b128 v[200:203], v182 offset:4096
	ds_read_b128 v[204:207], v182 offset:5120
	ds_read_b128 v[208:211], v182 offset:6144
	ds_read_b128 v[212:215], v182 offset:7168
	global_load_lds_dwordx4 v[18:19], off
	v_lshl_add_u64 v[18:19], s[0:1], 0, v[162:163]
	s_add_i32 m0, s26, 0xe000
	s_nop 0
	global_load_lds_dwordx4 v[18:19], off
	s_waitcnt lgkmcnt(8)
	s_barrier
	s_waitcnt lgkmcnt(0)
	s_waitcnt lgkmcnt(0)
	s_nop 1
	v_mfma_scale_f32_16x16x128_f8f6f4 v[150:153], v[10:17], v[184:191], v[150:153], v172, v172 op_sel_hi:[0,0,0]
	s_nop 1
	v_mfma_scale_f32_16x16x128_f8f6f4 v[146:149], v[2:9], v[184:191], v[146:149], v172, v172 op_sel_hi:[0,0,0]
	s_nop 1
	v_mfma_scale_f32_16x16x128_f8f6f4 v[134:137], v[10:17], v[192:199], v[134:137], v172, v172 op_sel_hi:[0,0,0]
	s_nop 1
	v_mfma_scale_f32_16x16x128_f8f6f4 v[130:133], v[2:9], v[192:199], v[130:133], v172, v172 op_sel_hi:[0,0,0]
	s_nop 1
	v_mfma_scale_f32_16x16x128_f8f6f4 v[118:121], v[10:17], v[200:207], v[118:121], v172, v172 op_sel_hi:[0,0,0]
	s_nop 1
	v_mfma_scale_f32_16x16x128_f8f6f4 v[114:117], v[2:9], v[200:207], v[114:117], v172, v172 op_sel_hi:[0,0,0]
	s_nop 1
	v_mfma_scale_f32_16x16x128_f8f6f4 v[102:105], v[10:17], v[208:215], v[102:105], v172, v172 op_sel_hi:[0,0,0]
	s_nop 1
	v_mfma_scale_f32_16x16x128_f8f6f4 v[98:101], v[2:9], v[208:215], v[98:101], v172, v172 op_sel_hi:[0,0,0]
	s_barrier
	s_add_i32 s86, 0, 0x14000
	s_add_i32 s30, s30, s25
	v_add_u32_e32 v22, s86, v174
	v_lshl_add_u64 v[164:165], s[12:13], 0, v[0:1]
	s_mov_b32 m0, s30
	ds_read_b128 v[236:239], v22
	ds_read_b128 v[240:243], v22 offset:1024
	ds_read_b128 v[18:21], v22 offset:2048
	ds_read_b128 v[22:25], v22 offset:3072
	global_load_lds_dwordx4 v[164:165], off
	v_lshl_add_u64 v[166:167], s[12:13], 0, v[154:155]
	s_add_i32 m0, s30, 0x2000
	s_nop 0
	global_load_lds_dwordx4 v[166:167], off
	s_barrier
	s_waitcnt lgkmcnt(0)
	s_waitcnt lgkmcnt(0)
	s_nop 1
	v_mfma_scale_f32_16x16x128_f8f6f4 v[142:145], v[236:243], v[184:191], v[142:145], v172, v172 op_sel_hi:[0,0,0]
	s_nop 1
	v_mfma_scale_f32_16x16x128_f8f6f4 v[138:141], v[18:25], v[184:191], v[138:141], v172, v172 op_sel_hi:[0,0,0]
	s_nop 1
	v_mfma_scale_f32_16x16x128_f8f6f4 v[126:129], v[236:243], v[192:199], v[126:129], v172, v172 op_sel_hi:[0,0,0]
	s_nop 1
	v_mfma_scale_f32_16x16x128_f8f6f4 v[122:125], v[18:25], v[192:199], v[122:125], v172, v172 op_sel_hi:[0,0,0]
	s_nop 1
	v_mfma_scale_f32_16x16x128_f8f6f4 v[110:113], v[236:243], v[200:207], v[110:113], v172, v172 op_sel_hi:[0,0,0]
	s_nop 1
	v_mfma_scale_f32_16x16x128_f8f6f4 v[106:109], v[18:25], v[200:207], v[106:109], v172, v172 op_sel_hi:[0,0,0]
	s_nop 1
	v_mfma_scale_f32_16x16x128_f8f6f4 v[94:97], v[236:243], v[208:215], v[94:97], v172, v172 op_sel_hi:[0,0,0]
	s_nop 1
	v_mfma_scale_f32_16x16x128_f8f6f4 v[90:93], v[18:25], v[208:215], v[90:93], v172, v172 op_sel_hi:[0,0,0]
	s_mov_b32 m0, s26
	v_lshl_add_u64 v[168:169], s[68:69], 0, v[158:159]
	s_barrier
	ds_read_b128 v[184:187], v182 offset:16384
	ds_read_b128 v[188:191], v182 offset:17408
	ds_read_b128 v[192:195], v182 offset:18432
	ds_read_b128 v[196:199], v182 offset:19456
	ds_read_b128 v[200:203], v182 offset:20480
	ds_read_b128 v[204:207], v182 offset:21504
	ds_read_b128 v[208:211], v182 offset:22528
	ds_read_b128 v[212:215], v182 offset:23552
	global_load_lds_dwordx4 v[168:169], off
	v_lshl_add_u64 v[170:171], s[68:69], 0, v[156:157]
	s_mov_b32 m0, s27
	s_nop 0
	global_load_lds_dwordx4 v[170:171], off
	s_barrier
	s_waitcnt lgkmcnt(0)
	s_waitcnt lgkmcnt(0)
	s_nop 1
	v_mfma_scale_f32_16x16x128_f8f6f4 v[86:89], v[10:17], v[184:191], v[86:89], v172, v172 op_sel_hi:[0,0,0]
	s_nop 1
	v_mfma_scale_f32_16x16x128_f8f6f4 v[82:85], v[2:9], v[184:191], v[82:85], v172, v172 op_sel_hi:[0,0,0]
	s_nop 1
	v_mfma_scale_f32_16x16x128_f8f6f4 v[70:73], v[10:17], v[192:199], v[70:73], v172, v172 op_sel_hi:[0,0,0]
	s_nop 1
	v_mfma_scale_f32_16x16x128_f8f6f4 v[66:69], v[2:9], v[192:199], v[66:69], v172, v172 op_sel_hi:[0,0,0]
	s_nop 1
	v_mfma_scale_f32_16x16x128_f8f6f4 v[54:57], v[10:17], v[200:207], v[54:57], v172, v172 op_sel_hi:[0,0,0]
	s_nop 1
	v_mfma_scale_f32_16x16x128_f8f6f4 v[50:53], v[2:9], v[200:207], v[50:53], v172, v172 op_sel_hi:[0,0,0]
	s_nop 1
	v_mfma_scale_f32_16x16x128_f8f6f4 v[38:41], v[10:17], v[208:215], v[38:41], v172, v172 op_sel_hi:[0,0,0]
	s_nop 1
	v_mfma_scale_f32_16x16x128_f8f6f4 v[34:37], v[2:9], v[208:215], v[34:37], v172, v172 op_sel_hi:[0,0,0]
	s_barrier
	s_add_u32 s30, s12, 0x40000
	s_addc_u32 s31, s13, 0
	s_add_i32 s86, s86, s25
	v_lshl_add_u64 v[2:3], s[30:31], 0, v[0:1]
	s_mov_b32 m0, s86
	s_nop 0
	global_load_lds_dwordx4 v[2:3], off
	v_lshl_add_u64 v[2:3], s[30:31], 0, v[154:155]
	s_add_i32 m0, s86, 0x2000
	s_nop 0
	global_load_lds_dwordx4 v[2:3], off
	s_waitcnt vmcnt(6)
	s_barrier
; #define PG8_STAGE(bufoff, gbase, voff) do { _Pragma("unroll") for (int _i = 0; _i < 2; ++_i) \
;         __builtin_amdgcn_global_load_lds((const unsigned*)((const char*)(gbase) + (voff)[_i]), (PG8_LAS unsigned*)(lds + (bufoff) + ldsw + _i * 8192), 16, 0, 0); } while (0)
; #define PG8_LDA(dst, b, h) do { _Pragma("unroll") for (int m = 0; m < 4; ++m) _Pragma("unroll") for (int k = 0; k < 2; ++k) dst[m][k] = *(const PG8_LAS bf16x8*)(lds + PG8_SA(b, h) + aoff + m * 2048 + k * 1024); } while (0)
; #define PG8_LDB(dst, b, h) do { _Pragma("unroll") for (int n = 0; n < 2; ++n) _Pragma("unroll") for (int k = 0; k < 2; ++k) dst[n][k] = *(const PG8_LAS bf16x8*)(lds + PG8_SB(b, h) + boff + n * 2048 + k * 1024); } while (0)
; #define PG8_WAIT_V(n) asm volatile("s_waitcnt vmcnt(" #n ")" ::: "memory")
; #define PG8_WAIT_L(n) asm volatile("s_waitcnt lgkmcnt(" #n ")" ::: "memory")
; #define PG8_BAR __builtin_amdgcn_s_barrier()
; #define PG8_SCHED __builtin_amdgcn_sched_barrier(0)
; template <bool FP8, class Epi, class Sched>
; __device__ __forceinline__ void gemm_phase(PG8_LAS unsigned char* lds, const Gemm g, const Sched& S, const Epi& E) {
;     ...
;             PG8_STAGE(PG8_SB(0, 1), b2 + hstep, voffB);
;             PG8_WAIT_V(6); PG8_BAR; PG8_MMA(1, 1, At, B1); PG8_BAR;
;             PG8_LDB(B0, 1, 0); PG8_SCHED; PG8_LDA(At, 1, 0); PG8_STAGE(PG8_SA(0, 1), a2 + hstepA, voffA);
;             PG8_WAIT_L(8); PG8_BAR; PG8_WAIT_L(0); PG8_MMA(0, 0, At, B0); PG8_BAR; PG8_SCHED;
;             PG8_LDB(B1, 1, 1); PG8_STAGE(PG8_SB(1, 0), b3, voffB);
;             PG8_BAR; PG8_WAIT_L(0); PG8_MMA(0, 1, At, B1); PG8_BAR;
	s_nop 1
	v_mfma_scale_f32_16x16x128_f8f6f4 v[78:81], v[236:243], v[184:191], v[78:81], v172, v172 op_sel_hi:[0,0,0]
	s_nop 1
	v_mfma_scale_f32_16x16x128_f8f6f4 v[74:77], v[18:25], v[184:191], v[74:77], v172, v172 op_sel_hi:[0,0,0]
	s_nop 1
	v_mfma_scale_f32_16x16x128_f8f6f4 v[62:65], v[236:243], v[192:199], v[62:65], v172, v172 op_sel_hi:[0,0,0]
	s_nop 1
	v_mfma_scale_f32_16x16x128_f8f6f4 v[58:61], v[18:25], v[192:199], v[58:61], v172, v172 op_sel_hi:[0,0,0]
	s_nop 1
	v_mfma_scale_f32_16x16x128_f8f6f4 v[46:49], v[236:243], v[200:207], v[46:49], v172, v172 op_sel_hi:[0,0,0]
	s_nop 1
	v_mfma_scale_f32_16x16x128_f8f6f4 v[42:45], v[18:25], v[200:207], v[42:45], v172, v172 op_sel_hi:[0,0,0]
	s_nop 1
	v_mfma_scale_f32_16x16x128_f8f6f4 v[30:33], v[236:243], v[208:215], v[30:33], v172, v172 op_sel_hi:[0,0,0]
	s_nop 1
	v_mfma_scale_f32_16x16x128_f8f6f4 v[26:29], v[18:25], v[208:215], v[26:29], v172, v172 op_sel_hi:[0,0,0]
	s_add_i32 s86, 0, 0x18000
	v_add_u32_e32 v14, s86, v174
	s_barrier
	ds_read_b128 v[2:5], v14
	ds_read_b128 v[6:9], v14 offset:1024
	ds_read_b128 v[10:13], v14 offset:2048
	ds_read_b128 v[14:17], v14 offset:3072
	s_add_u32 s30, s68, 0x40000
	s_addc_u32 s31, s69, 0
	s_mov_b32 m0, s54
	v_lshl_add_u64 v[208:209], s[30:31], 0, v[158:159]
	ds_read_b128 v[18:21], v182 offset:32768
	ds_read_b128 v[22:25], v182 offset:33792
	ds_read_b128 v[184:187], v182 offset:34816
	ds_read_b128 v[188:191], v182 offset:35840
	ds_read_b128 v[192:195], v182 offset:36864
	ds_read_b128 v[196:199], v182 offset:37888
	ds_read_b128 v[200:203], v182 offset:38912
	ds_read_b128 v[204:207], v182 offset:39936
	global_load_lds_dwordx4 v[208:209], off
	v_lshl_add_u64 v[208:209], s[30:31], 0, v[156:157]
	s_mov_b32 m0, s70
	s_nop 0
	global_load_lds_dwordx4 v[208:209], off
	s_waitcnt lgkmcnt(8)
	s_barrier
	s_waitcnt lgkmcnt(0)
	s_waitcnt lgkmcnt(0)
	s_nop 1
	v_mfma_scale_f32_16x16x128_f8f6f4 v[150:153], v[2:9], v[18:25], v[150:153], v172, v172 op_sel_hi:[0,0,0]
	s_nop 1
	v_mfma_scale_f32_16x16x128_f8f6f4 v[146:149], v[10:17], v[18:25], v[146:149], v172, v172 op_sel_hi:[0,0,0]
	s_nop 1
	v_mfma_scale_f32_16x16x128_f8f6f4 v[134:137], v[2:9], v[184:191], v[134:137], v172, v172 op_sel_hi:[0,0,0]
	s_nop 1
	v_mfma_scale_f32_16x16x128_f8f6f4 v[130:133], v[10:17], v[184:191], v[130:133], v172, v172 op_sel_hi:[0,0,0]
	s_nop 1
	v_mfma_scale_f32_16x16x128_f8f6f4 v[118:121], v[2:9], v[192:199], v[118:121], v172, v172 op_sel_hi:[0,0,0]
	s_nop 1
	v_mfma_scale_f32_16x16x128_f8f6f4 v[114:117], v[10:17], v[192:199], v[114:117], v172, v172 op_sel_hi:[0,0,0]
	s_nop 1
	v_mfma_scale_f32_16x16x128_f8f6f4 v[102:105], v[2:9], v[200:207], v[102:105], v172, v172 op_sel_hi:[0,0,0]
	s_nop 1
	v_mfma_scale_f32_16x16x128_f8f6f4 v[98:101], v[10:17], v[200:207], v[98:101], v172, v172 op_sel_hi:[0,0,0]
	s_barrier
	s_add_i32 s30, 0, 0x1c000
	s_add_i32 s31, s86, s25
	v_add_u32_e32 v183, s30, v174
	v_lshl_add_u64 v[164:165], v[164:165], 0, s[56:57]
	s_mov_b32 m0, s31
	ds_read_b128 v[208:211], v183
	ds_read_b128 v[212:215], v183 offset:1024
	ds_read_b128 v[236:239], v183 offset:2048
	ds_read_b128 v[240:243], v183 offset:3072
	global_load_lds_dwordx4 v[164:165], off
	v_lshl_add_u64 v[164:165], v[166:167], 0, s[56:57]
	s_add_i32 m0, s31, 0x2000
	s_nop 0
	global_load_lds_dwordx4 v[164:165], off
	s_barrier
	s_waitcnt lgkmcnt(0)
	s_waitcnt lgkmcnt(0)
	s_nop 1
	v_mfma_scale_f32_16x16x128_f8f6f4 v[142:145], v[208:215], v[18:25], v[142:145], v172, v172 op_sel_hi:[0,0,0]
	s_nop 1
	v_mfma_scale_f32_16x16x128_f8f6f4 v[138:141], v[236:243], v[18:25], v[138:141], v172, v172 op_sel_hi:[0,0,0]
	s_nop 1
	v_mfma_scale_f32_16x16x128_f8f6f4 v[126:129], v[208:215], v[184:191], v[126:129], v172, v172 op_sel_hi:[0,0,0]
	s_nop 1
	v_mfma_scale_f32_16x16x128_f8f6f4 v[122:125], v[236:243], v[184:191], v[122:125], v172, v172 op_sel_hi:[0,0,0]
	s_nop 1
	v_mfma_scale_f32_16x16x128_f8f6f4 v[110:113], v[208:215], v[192:199], v[110:113], v172, v172 op_sel_hi:[0,0,0]
	s_nop 1
	v_mfma_scale_f32_16x16x128_f8f6f4 v[106:109], v[236:243], v[192:199], v[106:109], v172, v172 op_sel_hi:[0,0,0]
	s_nop 1
	v_mfma_scale_f32_16x16x128_f8f6f4 v[94:97], v[208:215], v[200:207], v[94:97], v172, v172 op_sel_hi:[0,0,0]
	s_nop 1
	v_mfma_scale_f32_16x16x128_f8f6f4 v[90:93], v[236:243], v[200:207], v[90:93], v172, v172 op_sel_hi:[0,0,0]
	s_mov_b32 m0, s71
	v_lshl_add_u64 v[164:165], v[168:169], 0, s[56:57]
	s_barrier
; #define PG8_STAGE(bufoff, gbase, voff) do { _Pragma("unroll") for (int _i = 0; _i < 2; ++_i) \
;         __builtin_amdgcn_global_load_lds((const unsigned*)((const char*)(gbase) + (voff)[_i]), (PG8_LAS unsigned*)(lds + (bufoff) + ldsw + _i * 8192), 16, 0, 0); } while (0)
; #define PG8_LDA(dst, b, h) do { _Pragma("unroll") for (int m = 0; m < 4; ++m) _Pragma("unroll") for (int k = 0; k < 2; ++k) dst[m][k] = *(const PG8_LAS bf16x8*)(lds + PG8_SA(b, h) + aoff + m * 2048 + k * 1024); } while (0)
; template <bool FP8, class Epi, class Sched>
; __device__ __forceinline__ void gemm_phase(PG8_LAS unsigned char* lds, const Gemm g, const Sched& S, const Epi& E) {
;     ...
;             PG8_LDA(At, 1, 1); PG8_STAGE(PG8_SA(1, 0), a3, voffA);
;             PG8_BAR; PG8_WAIT_L(0); PG8_MMA(1, 0, At, B0); PG8_BAR; PG8_SCHED;
;             PG8_STAGE(PG8_SB(1, 1), b3 + hstep, voffB);
;             PG8_WAIT_V(6); PG8_BAR; PG8_MMA(1, 1, At, B1); PG8_BAR;
;         }
;         if constexpr (FP8) asm volatile("s_nop 15\n\ts_nop 15" ::: "memory");
;   DI void operator()(const f32x4 (&acc)[2][2][4][2], const pg8::Unit& u, int wr, int wc, int fr, int fq) const {
;     ...
;           const int col = colb + bj * 128;
;           f32x4 v0 = acc[ai][bj][m][0] * sc, v1 = acc[ai][bj][m][1] * sc;
;           u16* dst = nullptr;
;           if (MODE == 0) { if (col < N) dst = d0 + (size_t)row * ld0 + (col + coff2 + ((col < csplit) ? (coff1 - coff2) : 0)); }
;           else if (MODE == 1) {
;             const int oc = col + coff2 + ((col < csplit) ? (coff1 - coff2) : 0);
;             if (col < N) {
;               if (oc < 2048) dst = d0 + (size_t)row * 2048 + oc;
;               else if (oc < 2112) { rot(v0, v1, row, oc); dst = d2 + (size_t)row * 64 + (oc - 2048); }
;               else dst = d1 + (size_t)row * 4096 + (oc - 2112);
;             }
;           } else if (MODE == 3) {
;             if (col < N) { const bool lo = col < csplit; u16* bp = lo ? d0 : d1; const int ldd = lo ? 2048 : 4096, oc = lo ? col : col + (coff2 - 2112); dst = bp + (size_t)row * ldd + oc + (lo ? coff1 : 0); }
;           } else {
;             if (((col >> 6) % 3) == 2) rot(v0, v1, row, col);
;             dst = d0 + (size_t)row * 3072 + col;
;           }
;           if (dst) { u32x4 w = {pk2(v0[0], v0[1]), pk2(v0[2], v0[3]), pk2(v1[0], v1[1]), pk2(v1[2], v1[3])}; *(u32x4*)dst = w; }
	ds_read_b128 v[18:21], v182 offset:49152
	ds_read_b128 v[22:25], v182 offset:50176
	ds_read_b128 v[184:187], v182 offset:51200
	ds_read_b128 v[188:191], v182 offset:52224
	ds_read_b128 v[192:195], v182 offset:53248
	ds_read_b128 v[196:199], v182 offset:54272
	ds_read_b128 v[200:203], v182 offset:55296
	ds_read_b128 v[204:207], v182 offset:56320
	global_load_lds_dwordx4 v[164:165], off
	v_lshl_add_u64 v[164:165], v[170:171], 0, s[56:57]
	s_mov_b32 m0, s72
	s_nop 0
	global_load_lds_dwordx4 v[164:165], off
	s_barrier
	s_waitcnt lgkmcnt(0)
	s_waitcnt lgkmcnt(0)
	s_nop 1
	v_mfma_scale_f32_16x16x128_f8f6f4 v[86:89], v[2:9], v[18:25], v[86:89], v172, v172 op_sel_hi:[0,0,0]
	s_nop 1
	v_mfma_scale_f32_16x16x128_f8f6f4 v[82:85], v[10:17], v[18:25], v[82:85], v172, v172 op_sel_hi:[0,0,0]
	s_nop 1
	v_mfma_scale_f32_16x16x128_f8f6f4 v[70:73], v[2:9], v[184:191], v[70:73], v172, v172 op_sel_hi:[0,0,0]
	s_nop 1
	v_mfma_scale_f32_16x16x128_f8f6f4 v[66:69], v[10:17], v[184:191], v[66:69], v172, v172 op_sel_hi:[0,0,0]
	s_nop 1
	v_mfma_scale_f32_16x16x128_f8f6f4 v[54:57], v[2:9], v[192:199], v[54:57], v172, v172 op_sel_hi:[0,0,0]
	s_nop 1
	v_mfma_scale_f32_16x16x128_f8f6f4 v[50:53], v[10:17], v[192:199], v[50:53], v172, v172 op_sel_hi:[0,0,0]
	s_nop 1
	v_mfma_scale_f32_16x16x128_f8f6f4 v[38:41], v[2:9], v[200:207], v[38:41], v172, v172 op_sel_hi:[0,0,0]
	s_nop 1
	v_mfma_scale_f32_16x16x128_f8f6f4 v[34:37], v[10:17], v[200:207], v[34:37], v172, v172 op_sel_hi:[0,0,0]
	s_barrier
	s_add_u32 s12, s12, 0x40080
	s_addc_u32 s13, s13, 0
	s_add_i32 s30, s30, s25
	v_lshl_add_u64 v[2:3], s[12:13], 0, v[0:1]
	s_mov_b32 m0, s30
	s_nop 0
	global_load_lds_dwordx4 v[2:3], off
	v_lshl_add_u64 v[2:3], s[12:13], 0, v[154:155]
	s_add_i32 m0, s30, 0x2000
	s_nop 0
	global_load_lds_dwordx4 v[2:3], off
	s_waitcnt vmcnt(6)
	s_barrier
	s_nop 1
	v_mfma_scale_f32_16x16x128_f8f6f4 v[78:81], v[208:215], v[18:25], v[78:81], v172, v172 op_sel_hi:[0,0,0]
	s_nop 1
	v_mfma_scale_f32_16x16x128_f8f6f4 v[74:77], v[236:243], v[18:25], v[74:77], v172, v172 op_sel_hi:[0,0,0]
	s_nop 1
	v_mfma_scale_f32_16x16x128_f8f6f4 v[62:65], v[208:215], v[184:191], v[62:65], v172, v172 op_sel_hi:[0,0,0]
	s_nop 1
	v_mfma_scale_f32_16x16x128_f8f6f4 v[58:61], v[236:243], v[184:191], v[58:61], v172, v172 op_sel_hi:[0,0,0]
	s_nop 1
	v_mfma_scale_f32_16x16x128_f8f6f4 v[46:49], v[208:215], v[192:199], v[46:49], v172, v172 op_sel_hi:[0,0,0]
	s_nop 1
	v_mfma_scale_f32_16x16x128_f8f6f4 v[42:45], v[236:243], v[192:199], v[42:45], v172, v172 op_sel_hi:[0,0,0]
	s_nop 1
	v_mfma_scale_f32_16x16x128_f8f6f4 v[30:33], v[208:215], v[200:207], v[30:33], v172, v172 op_sel_hi:[0,0,0]
	s_nop 1
	v_mfma_scale_f32_16x16x128_f8f6f4 v[26:29], v[236:243], v[200:207], v[26:29], v172, v172 op_sel_hi:[0,0,0]
	s_add_i32 vcc_hi, vcc_hi, 2
	s_add_u32 s0, s0, 0x100
	s_addc_u32 s1, s1, 0
	s_add_u32 s95, s95, 0x100
	s_addc_u32 vcc_lo, vcc_lo, 0
	s_cmp_gt_u32 vcc_hi, 13
	s_barrier
	s_cbranch_scc0 .LBB0_381
	s_nop 15
	s_nop 15
	v_lshl_or_b32 v2, s28, 8, v175
	v_lshl_add_u32 v8, s29, 8, v173
	v_cmp_gt_i32_e32 vcc, s34, v2
	v_mov_b64_e32 v[4:5], 0
	v_add_u32_e32 v6, 0x650, v2
	s_and_saveexec_b64 s[12:13], vcc
	v_mov_b64_e32 v[4:5], s[96:97]
	s_movk_i32 s0, 0x3d00
	v_mad_i64_i32 v[4:5], s[0:1], v8, s0, v[4:5]
	s_movk_i32 s0, 0x800
	s_nop 0
	v_cmp_gt_i32_e64 s[0:1], s0, v2
	s_nop 1
	v_cndmask_b32_e64 v10, v6, v2, s[0:1]
	v_ashrrev_i32_e32 v11, 31, v10
	v_lshl_add_u64 v[4:5], v[10:11], 1, v[4:5]
	s_or_b64 exec, exec, s[12:13]
	v_cmp_ne_u64_e64 s[0:1], 0, v[4:5]
	s_and_saveexec_b64 s[12:13], s[0:1]
	s_movk_i32 s20, 0x600
	s_mov_b32 s86, 0x800000
	s_movk_i32 s87, 0x3fff
	v_readlane_b32 s3, v254, 29
	s_cbranch_execz .LBB0_386
	v_pk_mul_f32 v[12:13], v[152:153], s[88:89] op_sel_hi:[1,0]
	v_pk_mul_f32 v[10:11], v[150:151], s[88:89] op_sel_hi:[1,0]
	v_pk_mul_f32 v[14:15], v[148:149], s[88:89] op_sel_hi:[1,0]
	v_pk_mul_f32 v[16:17], v[146:147], s[88:89] op_sel_hi:[1,0]
	v_cvt_pk_bf16_f32 v10, v10, v11
	v_cvt_pk_bf16_f32 v11, v12, v13
	v_cvt_pk_bf16_f32 v12, v16, v17
	v_cvt_pk_bf16_f32 v13, v14, v15
	global_store_dwordx4 v[4:5], v[10:13], off

; #define PG8_STAGE(bufoff, gbase, voff) do { _Pragma("unroll") for (int _i = 0; _i < 2; ++_i) \
;         __builtin_amdgcn_global_load_lds((const unsigned*)((const char*)(gbase) + (voff)[_i]), (PG8_LAS unsigned*)(lds + (bufoff) + ldsw + _i * 8192), 16, 0, 0); } while (0)
; #define PG8_LDA(dst, b, h) do { _Pragma("unroll") for (int m = 0; m < 4; ++m) _Pragma("unroll") for (int k = 0; k < 2; ++k) dst[m][k] = *(const PG8_LAS bf16x8*)(lds + PG8_SA(b, h) + aoff + m * 2048 + k * 1024); } while (0)
; #define PG8_LDB(dst, b, h) do { _Pragma("unroll") for (int n = 0; n < 2; ++n) _Pragma("unroll") for (int k = 0; k < 2; ++k) dst[n][k] = *(const PG8_LAS bf16x8*)(lds + PG8_SB(b, h) + boff + n * 2048 + k * 1024); } while (0)
; #define PG8_WAIT_L(n) asm volatile("s_waitcnt lgkmcnt(" #n ")" ::: "memory")
; #define PG8_BAR __builtin_amdgcn_s_barrier()
; #define PG8_SCHED __builtin_amdgcn_sched_barrier(0)
; template <bool FP8, class Epi, class Sched>
; __device__ __forceinline__ void gemm_phase(PG8_LAS unsigned char* lds, const Gemm g, const Sched& S, const Epi& E) {
;     ...
;             PG8_LDB(B0, 0, 0); PG8_SCHED; PG8_LDA(At, 0, 0); PG8_STAGE(PG8_SA(1, 1), a1 + hstepA, voffA);
;             PG8_WAIT_L(8); PG8_BAR; PG8_WAIT_L(0); PG8_MMA(0, 0, At, B0); PG8_BAR; PG8_SCHED;
;             PG8_LDB(B1, 0, 1); PG8_STAGE(PG8_SB(0, 0), b2, voffB);
;             PG8_BAR; PG8_WAIT_L(0); PG8_MMA(0, 1, At, B1); PG8_BAR;
;             PG8_LDA(At, 0, 1); PG8_STAGE(PG8_SA(0, 0), a2, voffA);
;             PG8_BAR; PG8_WAIT_L(0); PG8_MMA(1, 0, At, B0); PG8_BAR; PG8_SCHED;
.LBB0_458:
	s_add_u32 s12, s0, 0xfff80080
	s_addc_u32 s13, s1, -1
	s_add_i32 s30, 0, 0x10000
	v_add_u32_e32 v0, s30, v167
	ds_read_b128 v[142:145], v0
	ds_read_b128 v[146:149], v0 offset:1024
	ds_read_b128 v[150:153], v0 offset:2048
	ds_read_b128 v[154:157], v0 offset:3072
	s_cmp_eq_u32 vcc_hi, 28
	s_cselect_b32 s69, s17, s13
	s_cselect_b32 s68, s70, s12
	s_cselect_b32 s13, s15, vcc_lo
	s_cselect_b32 s12, s71, s95
	v_lshl_add_u64 v[174:175], s[0:1], 0, v[138:139]
	s_add_i32 m0, s26, 0xc000
	ds_read_b128 v[158:161], v169
	ds_read_b128 v[162:165], v169 offset:1024
	ds_read_b128 v[170:173], v169 offset:2048
	ds_read_b128 v[182:185], v169 offset:3072
	ds_read_b128 v[186:189], v169 offset:4096
	ds_read_b128 v[190:193], v169 offset:5120
	ds_read_b128 v[194:197], v169 offset:6144
	ds_read_b128 v[198:201], v169 offset:7168
	global_load_lds_dwordx4 v[174:175], off
	v_lshl_add_u64 v[174:175], s[0:1], 0, v[140:141]
	s_add_i32 m0, s26, 0xe000
	s_nop 0
	global_load_lds_dwordx4 v[174:175], off
	s_waitcnt lgkmcnt(8)
	s_barrier
	s_waitcnt lgkmcnt(0)
	s_waitcnt lgkmcnt(0)
	v_mfma_f32_16x16x32_bf16 v[126:129], v[142:145], v[158:161], v[126:129]
	v_mfma_f32_16x16x32_bf16 v[122:125], v[150:153], v[158:161], v[122:125]
	v_mfma_f32_16x16x32_bf16 v[110:113], v[142:145], v[170:173], v[110:113]
	v_mfma_f32_16x16x32_bf16 v[106:109], v[150:153], v[170:173], v[106:109]
	v_mfma_f32_16x16x32_bf16 v[94:97], v[142:145], v[186:189], v[94:97]
	v_mfma_f32_16x16x32_bf16 v[90:93], v[150:153], v[186:189], v[90:93]
	v_mfma_f32_16x16x32_bf16 v[78:81], v[142:145], v[194:197], v[78:81]
	v_mfma_f32_16x16x32_bf16 v[74:77], v[150:153], v[194:197], v[74:77]
	v_mfma_f32_16x16x32_bf16 v[126:129], v[146:149], v[162:165], v[126:129]
	v_mfma_f32_16x16x32_bf16 v[122:125], v[154:157], v[162:165], v[122:125]
	v_mfma_f32_16x16x32_bf16 v[110:113], v[146:149], v[182:185], v[110:113]
	v_mfma_f32_16x16x32_bf16 v[106:109], v[154:157], v[182:185], v[106:109]
	v_mfma_f32_16x16x32_bf16 v[94:97], v[146:149], v[190:193], v[94:97]
	v_mfma_f32_16x16x32_bf16 v[90:93], v[154:157], v[190:193], v[90:93]
	v_mfma_f32_16x16x32_bf16 v[78:81], v[146:149], v[198:201], v[78:81]
	v_mfma_f32_16x16x32_bf16 v[74:77], v[154:157], v[198:201], v[74:77]
	s_barrier
	s_add_i32 s86, 0, 0x14000
	s_add_i32 s30, s30, s25
	v_add_u32_e32 v0, s86, v167
	v_lshl_add_u64 v[174:175], s[12:13], 0, v[134:135]
	s_mov_b32 m0, s30
	ds_read_b128 v[202:205], v0
	ds_read_b128 v[206:209], v0 offset:1024
	ds_read_b128 v[210:213], v0 offset:2048
	ds_read_b128 v[214:217], v0 offset:3072
	global_load_lds_dwordx4 v[174:175], off
	v_lshl_add_u64 v[236:237], s[12:13], 0, v[130:131]
	s_add_i32 m0, s30, 0x2000
	s_nop 0
	global_load_lds_dwordx4 v[236:237], off
	s_barrier
	s_waitcnt lgkmcnt(0)
	s_waitcnt lgkmcnt(0)
	v_mfma_f32_16x16x32_bf16 v[118:121], v[202:205], v[158:161], v[118:121]
	v_mfma_f32_16x16x32_bf16 v[114:117], v[210:213], v[158:161], v[114:117]
	v_mfma_f32_16x16x32_bf16 v[102:105], v[202:205], v[170:173], v[102:105]
	v_mfma_f32_16x16x32_bf16 v[98:101], v[210:213], v[170:173], v[98:101]
	v_mfma_f32_16x16x32_bf16 v[86:89], v[202:205], v[186:189], v[86:89]
	v_mfma_f32_16x16x32_bf16 v[82:85], v[210:213], v[186:189], v[82:85]
	v_mfma_f32_16x16x32_bf16 v[70:73], v[202:205], v[194:197], v[70:73]
	v_mfma_f32_16x16x32_bf16 v[66:69], v[210:213], v[194:197], v[66:69]
	v_mfma_f32_16x16x32_bf16 v[118:121], v[206:209], v[162:165], v[118:121]
	v_mfma_f32_16x16x32_bf16 v[114:117], v[214:217], v[162:165], v[114:117]
	v_mfma_f32_16x16x32_bf16 v[102:105], v[206:209], v[182:185], v[102:105]
	v_mfma_f32_16x16x32_bf16 v[98:101], v[214:217], v[182:185], v[98:101]
	v_mfma_f32_16x16x32_bf16 v[86:89], v[206:209], v[190:193], v[86:89]
	v_mfma_f32_16x16x32_bf16 v[82:85], v[214:217], v[190:193], v[82:85]
	v_mfma_f32_16x16x32_bf16 v[70:73], v[206:209], v[198:201], v[70:73]
	v_mfma_f32_16x16x32_bf16 v[66:69], v[214:217], v[198:201], v[66:69]
	s_mov_b32 m0, s26
	v_lshl_add_u64 v[238:239], s[68:69], 0, v[136:137]
	s_barrier
	ds_read_b128 v[158:161], v169 offset:16384
	ds_read_b128 v[162:165], v169 offset:17408
	ds_read_b128 v[170:173], v169 offset:18432
	ds_read_b128 v[182:185], v169 offset:19456
	ds_read_b128 v[186:189], v169 offset:20480
	ds_read_b128 v[190:193], v169 offset:21504
	ds_read_b128 v[194:197], v169 offset:22528
	ds_read_b128 v[198:201], v169 offset:23552
	global_load_lds_dwordx4 v[238:239], off
	v_lshl_add_u64 v[240:241], s[68:69], 0, v[132:133]
	s_mov_b32 m0, s27
	s_nop 0
	global_load_lds_dwordx4 v[240:241], off
	s_barrier
	s_waitcnt lgkmcnt(0)
	s_waitcnt lgkmcnt(0)
	v_mfma_f32_16x16x32_bf16 v[62:65], v[142:145], v[158:161], v[62:65]
	v_mfma_f32_16x16x32_bf16 v[58:61], v[150:153], v[158:161], v[58:61]
	v_mfma_f32_16x16x32_bf16 v[46:49], v[142:145], v[170:173], v[46:49]
	v_mfma_f32_16x16x32_bf16 v[42:45], v[150:153], v[170:173], v[42:45]
	v_mfma_f32_16x16x32_bf16 v[30:33], v[142:145], v[186:189], v[30:33]
	v_mfma_f32_16x16x32_bf16 v[26:29], v[150:153], v[186:189], v[26:29]
	v_mfma_f32_16x16x32_bf16 v[14:17], v[142:145], v[194:197], v[14:17]
	v_mfma_f32_16x16x32_bf16 v[10:13], v[150:153], v[194:197], v[10:13]
	v_mfma_f32_16x16x32_bf16 v[62:65], v[146:149], v[162:165], v[62:65]
	v_mfma_f32_16x16x32_bf16 v[58:61], v[154:157], v[162:165], v[58:61]
	v_mfma_f32_16x16x32_bf16 v[46:49], v[146:149], v[182:185], v[46:49]
	v_mfma_f32_16x16x32_bf16 v[42:45], v[154:157], v[182:185], v[42:45]
	v_mfma_f32_16x16x32_bf16 v[30:33], v[146:149], v[190:193], v[30:33]
	v_mfma_f32_16x16x32_bf16 v[26:29], v[154:157], v[190:193], v[26:29]
	v_mfma_f32_16x16x32_bf16 v[14:17], v[146:149], v[198:201], v[14:17]
	v_mfma_f32_16x16x32_bf16 v[10:13], v[154:157], v[198:201], v[10:13]
	s_barrier
; #define PG8_STAGE(bufoff, gbase, voff) do { _Pragma("unroll") for (int _i = 0; _i < 2; ++_i) \
;         __builtin_amdgcn_global_load_lds((const unsigned*)((const char*)(gbase) + (voff)[_i]), (PG8_LAS unsigned*)(lds + (bufoff) + ldsw + _i * 8192), 16, 0, 0); } while (0)
; #define PG8_LDA(dst, b, h) do { _Pragma("unroll") for (int m = 0; m < 4; ++m) _Pragma("unroll") for (int k = 0; k < 2; ++k) dst[m][k] = *(const PG8_LAS bf16x8*)(lds + PG8_SA(b, h) + aoff + m * 2048 + k * 1024); } while (0)
; #define PG8_LDB(dst, b, h) do { _Pragma("unroll") for (int n = 0; n < 2; ++n) _Pragma("unroll") for (int k = 0; k < 2; ++k) dst[n][k] = *(const PG8_LAS bf16x8*)(lds + PG8_SB(b, h) + boff + n * 2048 + k * 1024); } while (0)
; #define PG8_WAIT_V(n) asm volatile("s_waitcnt vmcnt(" #n ")" ::: "memory")
; #define PG8_WAIT_L(n) asm volatile("s_waitcnt lgkmcnt(" #n ")" ::: "memory")
; #define PG8_BAR __builtin_amdgcn_s_barrier()
; #define PG8_SCHED __builtin_amdgcn_sched_barrier(0)
; template <bool FP8, class Epi, class Sched>
; __device__ __forceinline__ void gemm_phase(PG8_LAS unsigned char* lds, const Gemm g, const Sched& S, const Epi& E) {
;     ...
;             PG8_STAGE(PG8_SB(0, 1), b2 + hstep, voffB);
;             PG8_WAIT_V(6); PG8_BAR; PG8_MMA(1, 1, At, B1); PG8_BAR;
;             PG8_LDB(B0, 1, 0); PG8_SCHED; PG8_LDA(At, 1, 0); PG8_STAGE(PG8_SA(0, 1), a2 + hstepA, voffA);
;             PG8_WAIT_L(8); PG8_BAR; PG8_WAIT_L(0); PG8_MMA(0, 0, At, B0); PG8_BAR; PG8_SCHED;
;             PG8_LDB(B1, 1, 1); PG8_STAGE(PG8_SB(1, 0), b3, voffB);
;             PG8_BAR; PG8_WAIT_L(0); PG8_MMA(0, 1, At, B1); PG8_BAR;
;             PG8_LDA(At, 1, 1); PG8_STAGE(PG8_SA(1, 0), a3, voffA);
;             PG8_BAR; PG8_WAIT_L(0); PG8_MMA(1, 0, At, B0); PG8_BAR; PG8_SCHED;
	s_add_u32 s30, s12, 0x80000
	s_addc_u32 s31, s13, 0
	s_add_i32 s86, s86, s25
	v_lshl_add_u64 v[142:143], s[30:31], 0, v[134:135]
	s_mov_b32 m0, s86
	s_nop 0
	global_load_lds_dwordx4 v[142:143], off
	v_lshl_add_u64 v[142:143], s[30:31], 0, v[130:131]
	s_add_i32 m0, s86, 0x2000
	s_nop 0
	global_load_lds_dwordx4 v[142:143], off
	s_waitcnt vmcnt(6)
	s_barrier
	v_mfma_f32_16x16x32_bf16 v[54:57], v[202:205], v[158:161], v[54:57]
	v_mfma_f32_16x16x32_bf16 v[50:53], v[210:213], v[158:161], v[50:53]
	v_mfma_f32_16x16x32_bf16 v[38:41], v[202:205], v[170:173], v[38:41]
	v_mfma_f32_16x16x32_bf16 v[34:37], v[210:213], v[170:173], v[34:37]
	v_mfma_f32_16x16x32_bf16 v[22:25], v[202:205], v[186:189], v[22:25]
	v_mfma_f32_16x16x32_bf16 v[18:21], v[210:213], v[186:189], v[18:21]
	v_mfma_f32_16x16x32_bf16 v[6:9], v[202:205], v[194:197], v[6:9]
	v_mfma_f32_16x16x32_bf16 v[2:5], v[210:213], v[194:197], v[2:5]
	v_mfma_f32_16x16x32_bf16 v[54:57], v[206:209], v[162:165], v[54:57]
	v_mfma_f32_16x16x32_bf16 v[50:53], v[214:217], v[162:165], v[50:53]
	v_mfma_f32_16x16x32_bf16 v[38:41], v[206:209], v[182:185], v[38:41]
	v_mfma_f32_16x16x32_bf16 v[34:37], v[214:217], v[182:185], v[34:37]
	v_mfma_f32_16x16x32_bf16 v[22:25], v[206:209], v[190:193], v[22:25]
	v_mfma_f32_16x16x32_bf16 v[18:21], v[214:217], v[190:193], v[18:21]
	v_mfma_f32_16x16x32_bf16 v[6:9], v[206:209], v[198:201], v[6:9]
	v_mfma_f32_16x16x32_bf16 v[2:5], v[214:217], v[198:201], v[2:5]
	s_add_i32 s86, 0, 0x18000
	v_add_u32_e32 v0, s86, v167
	s_barrier
	ds_read_b128 v[142:145], v0
	ds_read_b128 v[146:149], v0 offset:1024
	ds_read_b128 v[150:153], v0 offset:2048
	ds_read_b128 v[154:157], v0 offset:3072
	s_add_u32 s30, s68, 0x80000
	s_addc_u32 s31, s69, 0
	s_mov_b32 m0, s54
	v_lshl_add_u64 v[202:203], s[30:31], 0, v[136:137]
	ds_read_b128 v[158:161], v169 offset:32768
	ds_read_b128 v[162:165], v169 offset:33792
	ds_read_b128 v[170:173], v169 offset:34816
	ds_read_b128 v[182:185], v169 offset:35840
	ds_read_b128 v[186:189], v169 offset:36864
	ds_read_b128 v[190:193], v169 offset:37888
	ds_read_b128 v[194:197], v169 offset:38912
	ds_read_b128 v[198:201], v169 offset:39936
	global_load_lds_dwordx4 v[202:203], off
	v_lshl_add_u64 v[202:203], s[30:31], 0, v[132:133]
	s_mov_b32 m0, s72
	s_nop 0
	global_load_lds_dwordx4 v[202:203], off
	s_waitcnt lgkmcnt(8)
	s_barrier
	s_waitcnt lgkmcnt(0)
	s_waitcnt lgkmcnt(0)
	v_mfma_f32_16x16x32_bf16 v[126:129], v[142:145], v[158:161], v[126:129]
	v_mfma_f32_16x16x32_bf16 v[122:125], v[150:153], v[158:161], v[122:125]
	v_mfma_f32_16x16x32_bf16 v[110:113], v[142:145], v[170:173], v[110:113]
	v_mfma_f32_16x16x32_bf16 v[106:109], v[150:153], v[170:173], v[106:109]
	v_mfma_f32_16x16x32_bf16 v[94:97], v[142:145], v[186:189], v[94:97]
	v_mfma_f32_16x16x32_bf16 v[90:93], v[150:153], v[186:189], v[90:93]
	v_mfma_f32_16x16x32_bf16 v[78:81], v[142:145], v[194:197], v[78:81]
	v_mfma_f32_16x16x32_bf16 v[74:77], v[150:153], v[194:197], v[74:77]
	v_mfma_f32_16x16x32_bf16 v[126:129], v[146:149], v[162:165], v[126:129]
	v_mfma_f32_16x16x32_bf16 v[122:125], v[154:157], v[162:165], v[122:125]
	v_mfma_f32_16x16x32_bf16 v[110:113], v[146:149], v[182:185], v[110:113]
	v_mfma_f32_16x16x32_bf16 v[106:109], v[154:157], v[182:185], v[106:109]
	v_mfma_f32_16x16x32_bf16 v[94:97], v[146:149], v[190:193], v[94:97]
	v_mfma_f32_16x16x32_bf16 v[90:93], v[154:157], v[190:193], v[90:93]
	v_mfma_f32_16x16x32_bf16 v[78:81], v[146:149], v[198:201], v[78:81]
	v_mfma_f32_16x16x32_bf16 v[74:77], v[154:157], v[198:201], v[74:77]
	s_barrier
	s_add_i32 s30, 0, 0x1c000
	s_add_i32 s31, s86, s25
	v_add_u32_e32 v0, s30, v167
	v_lshl_add_u64 v[174:175], v[174:175], 0, s[56:57]
	s_mov_b32 m0, s31
	ds_read_b128 v[202:205], v0
	ds_read_b128 v[206:209], v0 offset:1024
	ds_read_b128 v[210:213], v0 offset:2048
	ds_read_b128 v[214:217], v0 offset:3072
	global_load_lds_dwordx4 v[174:175], off
	v_lshl_add_u64 v[174:175], v[236:237], 0, s[56:57]
	s_add_i32 m0, s31, 0x2000
	s_nop 0
	global_load_lds_dwordx4 v[174:175], off
	s_barrier
	s_waitcnt lgkmcnt(0)
	s_waitcnt lgkmcnt(0)
	v_mfma_f32_16x16x32_bf16 v[118:121], v[202:205], v[158:161], v[118:121]
	v_mfma_f32_16x16x32_bf16 v[114:117], v[210:213], v[158:161], v[114:117]
	v_mfma_f32_16x16x32_bf16 v[102:105], v[202:205], v[170:173], v[102:105]
	v_mfma_f32_16x16x32_bf16 v[98:101], v[210:213], v[170:173], v[98:101]
	v_mfma_f32_16x16x32_bf16 v[86:89], v[202:205], v[186:189], v[86:89]
	v_mfma_f32_16x16x32_bf16 v[82:85], v[210:213], v[186:189], v[82:85]
	v_mfma_f32_16x16x32_bf16 v[70:73], v[202:205], v[194:197], v[70:73]
	v_mfma_f32_16x16x32_bf16 v[66:69], v[210:213], v[194:197], v[66:69]
	v_mfma_f32_16x16x32_bf16 v[118:121], v[206:209], v[162:165], v[118:121]
	v_mfma_f32_16x16x32_bf16 v[114:117], v[214:217], v[162:165], v[114:117]
	v_mfma_f32_16x16x32_bf16 v[102:105], v[206:209], v[182:185], v[102:105]
	v_mfma_f32_16x16x32_bf16 v[98:101], v[214:217], v[182:185], v[98:101]
	v_mfma_f32_16x16x32_bf16 v[86:89], v[206:209], v[190:193], v[86:89]
	v_mfma_f32_16x16x32_bf16 v[82:85], v[214:217], v[190:193], v[82:85]
	v_mfma_f32_16x16x32_bf16 v[70:73], v[206:209], v[198:201], v[70:73]
	v_mfma_f32_16x16x32_bf16 v[66:69], v[214:217], v[198:201], v[66:69]
	s_mov_b32 m0, s73
	v_lshl_add_u64 v[174:175], v[238:239], 0, s[56:57]
	s_barrier
	ds_read_b128 v[158:161], v169 offset:49152
	ds_read_b128 v[162:165], v169 offset:50176
	ds_read_b128 v[170:173], v169 offset:51200
	ds_read_b128 v[182:185], v169 offset:52224
	ds_read_b128 v[186:189], v169 offset:53248
	ds_read_b128 v[190:193], v169 offset:54272
	ds_read_b128 v[194:197], v169 offset:55296
	ds_read_b128 v[198:201], v169 offset:56320
	global_load_lds_dwordx4 v[174:175], off
	v_lshl_add_u64 v[174:175], v[240:241], 0, s[56:57]
	s_mov_b32 m0, s87
	s_nop 0
	global_load_lds_dwordx4 v[174:175], off
	s_barrier
; #define PG8_STAGE(bufoff, gbase, voff) do { _Pragma("unroll") for (int _i = 0; _i < 2; ++_i) \
;         __builtin_amdgcn_global_load_lds((const unsigned*)((const char*)(gbase) + (voff)[_i]), (PG8_LAS unsigned*)(lds + (bufoff) + ldsw + _i * 8192), 16, 0, 0); } while (0)
; #define PG8_WAIT_V(n) asm volatile("s_waitcnt vmcnt(" #n ")" ::: "memory")
; #define PG8_WAIT_L(n) asm volatile("s_waitcnt lgkmcnt(" #n ")" ::: "memory")
; #define PG8_BAR __builtin_amdgcn_s_barrier()
; #define PG8_SCHED __builtin_amdgcn_sched_barrier(0)
; template <bool FP8, class Epi, class Sched>
; __device__ __forceinline__ void gemm_phase(PG8_LAS unsigned char* lds, const Gemm g, const Sched& S, const Epi& E) {
;     ...
;             PG8_BAR; PG8_WAIT_L(0); PG8_MMA(1, 0, At, B0); PG8_BAR; PG8_SCHED;
;             PG8_STAGE(PG8_SB(1, 1), b3 + hstep, voffB);
;             PG8_WAIT_V(6); PG8_BAR; PG8_MMA(1, 1, At, B1); PG8_BAR;
;   DI void operator()(const f32x4 (&acc)[2][2][4][2], const pg8::Unit& u, int wr, int wc, int fr, int fq) const {
;     ...
;           if (MODE == 0) { if (col < N) dst = d0 + (size_t)row * ld0 + (col + coff2 + ((col < csplit) ? (coff1 - coff2) : 0)); }
;           else if (MODE == 1) {
;             const int oc = col + coff2 + ((col < csplit) ? (coff1 - coff2) : 0);
;             if (col < N) {
;               if (oc < 2048) dst = d0 + (size_t)row * 2048 + oc;
;               else if (oc < 2112) { rot(v0, v1, row, oc); dst = d2 + (size_t)row * 64 + (oc - 2048); }
;               else dst = d1 + (size_t)row * 4096 + (oc - 2112);
;             }
;           } else if (MODE == 3) {
;             if (col < N) { const bool lo = col < csplit; u16* bp = lo ? d0 : d1; const int ldd = lo ? 2048 : 4096, oc = lo ? col : col + (coff2 - 2112); dst = bp + (size_t)row * ldd + oc + (lo ? coff1 : 0); }
;           } else {
;             if (((col >> 6) % 3) == 2) rot(v0, v1, row, col);
;             dst = d0 + (size_t)row * 3072 + col;
;           }
;           if (dst) { u32x4 w = {pk2(v0[0], v0[1]), pk2(v0[2], v0[3]), pk2(v1[0], v1[1]), pk2(v1[2], v1[3])}; *(u32x4*)dst = w; }
	s_waitcnt lgkmcnt(0)
	s_waitcnt lgkmcnt(0)
	v_mfma_f32_16x16x32_bf16 v[62:65], v[142:145], v[158:161], v[62:65]
	v_mfma_f32_16x16x32_bf16 v[58:61], v[150:153], v[158:161], v[58:61]
	v_mfma_f32_16x16x32_bf16 v[46:49], v[142:145], v[170:173], v[46:49]
	v_mfma_f32_16x16x32_bf16 v[42:45], v[150:153], v[170:173], v[42:45]
	v_mfma_f32_16x16x32_bf16 v[30:33], v[142:145], v[186:189], v[30:33]
	v_mfma_f32_16x16x32_bf16 v[26:29], v[150:153], v[186:189], v[26:29]
	v_mfma_f32_16x16x32_bf16 v[14:17], v[142:145], v[194:197], v[14:17]
	v_mfma_f32_16x16x32_bf16 v[10:13], v[150:153], v[194:197], v[10:13]
	v_mfma_f32_16x16x32_bf16 v[62:65], v[146:149], v[162:165], v[62:65]
	v_mfma_f32_16x16x32_bf16 v[58:61], v[154:157], v[162:165], v[58:61]
	v_mfma_f32_16x16x32_bf16 v[46:49], v[146:149], v[182:185], v[46:49]
	v_mfma_f32_16x16x32_bf16 v[42:45], v[154:157], v[182:185], v[42:45]
	v_mfma_f32_16x16x32_bf16 v[30:33], v[146:149], v[190:193], v[30:33]
	v_mfma_f32_16x16x32_bf16 v[26:29], v[154:157], v[190:193], v[26:29]
	v_mfma_f32_16x16x32_bf16 v[14:17], v[146:149], v[198:201], v[14:17]
	v_mfma_f32_16x16x32_bf16 v[10:13], v[154:157], v[198:201], v[10:13]
	s_barrier
	s_add_u32 s12, s12, 0x80080
	s_addc_u32 s13, s13, 0
	s_add_i32 s30, s30, s25
	v_lshl_add_u64 v[142:143], s[12:13], 0, v[134:135]
	s_mov_b32 m0, s30
	s_nop 0
	global_load_lds_dwordx4 v[142:143], off
	v_lshl_add_u64 v[142:143], s[12:13], 0, v[130:131]
	s_add_i32 m0, s30, 0x2000
	s_nop 0
	global_load_lds_dwordx4 v[142:143], off
	s_waitcnt vmcnt(6)
	s_barrier
	v_mfma_f32_16x16x32_bf16 v[54:57], v[202:205], v[158:161], v[54:57]
	v_mfma_f32_16x16x32_bf16 v[50:53], v[210:213], v[158:161], v[50:53]
	v_mfma_f32_16x16x32_bf16 v[38:41], v[202:205], v[170:173], v[38:41]
	v_mfma_f32_16x16x32_bf16 v[34:37], v[210:213], v[170:173], v[34:37]
	v_mfma_f32_16x16x32_bf16 v[22:25], v[202:205], v[186:189], v[22:25]
	v_mfma_f32_16x16x32_bf16 v[18:21], v[210:213], v[186:189], v[18:21]
	v_mfma_f32_16x16x32_bf16 v[6:9], v[202:205], v[194:197], v[6:9]
	v_mfma_f32_16x16x32_bf16 v[2:5], v[210:213], v[194:197], v[2:5]
	v_mfma_f32_16x16x32_bf16 v[54:57], v[206:209], v[162:165], v[54:57]
	v_mfma_f32_16x16x32_bf16 v[50:53], v[214:217], v[162:165], v[50:53]
	v_mfma_f32_16x16x32_bf16 v[38:41], v[206:209], v[182:185], v[38:41]
	v_mfma_f32_16x16x32_bf16 v[34:37], v[214:217], v[182:185], v[34:37]
	v_mfma_f32_16x16x32_bf16 v[22:25], v[206:209], v[190:193], v[22:25]
	v_mfma_f32_16x16x32_bf16 v[18:21], v[214:217], v[190:193], v[18:21]
	v_mfma_f32_16x16x32_bf16 v[6:9], v[206:209], v[198:201], v[6:9]
	v_mfma_f32_16x16x32_bf16 v[2:5], v[214:217], v[198:201], v[2:5]
	s_add_i32 vcc_hi, vcc_hi, 2
	s_add_u32 s0, s0, 0x100
	s_addc_u32 s1, s1, 0
	s_add_u32 s95, s95, 0x100
	s_addc_u32 vcc_lo, vcc_lo, 0
	s_cmp_gt_u32 vcc_hi, 29
	s_barrier
	s_cbranch_scc0 .LBB0_458
	v_lshl_add_u32 v144, s29, 8, v166
	v_lshl_or_b32 v170, s28, 8, v168
	s_movk_i32 s0, 0x240
	v_lshlrev_b32_e32 v0, 5, v144
	v_cmp_gt_i32_e32 vcc, s0, v170
	v_and_b32_e32 v171, 0xf9e0, v0
	s_movk_i32 s0, 0xa00
	v_cndmask_b32_e32 v0, 0, v227, vcc
	v_ashrrev_i32_e32 v145, 31, v144
	v_add3_u32 v142, v170, v0, s0
	s_movk_i32 s0, 0xe40
	v_lshlrev_b64 v[150:151], 13, v[144:145]
	v_lshlrev_b64 v[146:147], 7, v[144:145]
	v_lshlrev_b64 v[148:149], 12, v[144:145]
	v_cmp_gt_i32_e32 vcc, s0, v170
	v_mov_b64_e32 v[164:165], 0
	s_and_saveexec_b64 s[12:13], vcc
	s_movk_i32 s15, 0x7ff
	s_movk_i32 s17, 0x83f
	v_readlane_b32 s3, v254, 29
	s_cbranch_execz .LBB0_469
	v_cmp_lt_i32_e64 s[0:1], s15, v142
	s_and_saveexec_b64 s[28:29], s[0:1]
	s_xor_b64 s[68:69], exec, s[28:29]
	s_cbranch_execz .LBB0_466
	v_cmp_lt_u32_e64 s[0:1], s17, v142
	s_and_saveexec_b64 s[28:29], s[0:1]
	s_xor_b64 s[0:1], exec, s[28:29]
	v_lshl_add_u64 v[152:153], s[4:5], 0, v[150:151]
	v_mov_b32_e32 v143, v1
	s_movk_i32 s28, 0xef80
	v_lshl_add_u64 v[152:153], v[142:143], 1, v[152:153]
	s_mov_b32 s29, -1
	v_lshl_add_u64 v[164:165], v[152:153], 0, s[28:29]
	s_or_saveexec_b64 s[0:1], s[0:1]
	v_mov_b32_e32 v152, v129
	v_mov_b32_e32 v154, v128
	v_mov_b32_e32 v157, v127
	v_mov_b32_e32 v0, v126
	v_mov_b32_e32 v158, v125
	v_mov_b32_e32 v160, v124
	v_mov_b32_e32 v163, v123
	v_mov_b32_e32 v143, v122
	s_xor_b64 exec, exec, s[0:1]
	s_cbranch_execz .LBB0_465
	v_lshlrev_b32_e32 v0, 3, v171
	v_lshl_add_u64 v[152:153], s[52:53], 0, v[0:1]
	v_lshlrev_b32_e32 v0, 2, v170
	v_and_b32_e32 v0, 0xe0, v0
	v_lshl_add_u64 v[152:153], v[152:153], 0, v[0:1]
	global_load_dwordx4 v[162:165], v[152:153], off offset:16
	global_load_dwordx4 v[156:159], v[152:153], off
	v_readlane_b32 s28, v250, 44
	v_readlane_b32 s29, v250, 45
	v_mov_b32_e32 v143, v1
	s_waitcnt vmcnt(0)
	v_pk_mul_f32 v[182:183], v[122:123], v[162:163]
	v_mul_f32_e32 v0, v129, v159
	v_pk_fma_f32 v[154:155], v[128:129], v[158:159], v[0:1] op_sel_hi:[1,1,0] neg_lo:[0,0,1] neg_hi:[0,0,1]
	v_mul_f32_e32 v0, v128, v159
	v_pk_fma_f32 v[152:153], v[128:129], v[158:159], v[0:1] op_sel:[1,0,0] op_sel_hi:[0,1,0]
	v_mul_f32_e32 v0, v125, v165
	v_pk_fma_f32 v[160:161], v[124:125], v[164:165], v[0:1] op_sel_hi:[1,1,0] neg_lo:[0,0,1] neg_hi:[0,0,1]
	v_mul_f32_e32 v0, v124, v165
	v_pk_fma_f32 v[158:159], v[124:125], v[164:165], v[0:1] op_sel:[1,0,0] op_sel_hi:[0,1,0]
	v_lshl_add_u64 v[164:165], s[28:29], 0, v[146:147]
	s_movk_i32 s28, 0xf000
	v_pk_mul_f32 v[172:173], v[126:127], v[156:157]
	v_pk_mul_f32 v[174:175], v[126:127], v[156:157] op_sel:[1,1] op_sel_hi:[0,1]
	v_pk_mul_f32 v[184:185], v[122:123], v[162:163] op_sel:[1,1] op_sel_hi:[0,1]
	v_lshl_add_u64 v[164:165], v[142:143], 1, v[164:165]
	s_mov_b32 s29, -1
	v_pk_fma_f32 v[156:157], v[126:127], v[156:157], v[174:175] op_sel_hi:[1,0,1]
	v_pk_fma_f32 v[162:163], v[122:123], v[162:163], v[184:185] op_sel_hi:[1,0,1]
	v_lshl_add_u64 v[164:165], v[164:165], 0, s[28:29]
	v_sub_f32_e32 v143, v182, v184
	v_sub_f32_e32 v0, v172, v174

; #define PG8_STAGE(bufoff, gbase, voff) do { _Pragma("unroll") for (int _i = 0; _i < 2; ++_i) \
;         __builtin_amdgcn_global_load_lds((const unsigned*)((const char*)(gbase) + (voff)[_i]), (PG8_LAS unsigned*)(lds + (bufoff) + ldsw + _i * 8192), 16, 0, 0); } while (0)
; #define PG8_LDA(dst, b, h) do { _Pragma("unroll") for (int m = 0; m < 4; ++m) _Pragma("unroll") for (int k = 0; k < 2; ++k) dst[m][k] = *(const PG8_LAS bf16x8*)(lds + PG8_SA(b, h) + aoff + m * 2048 + k * 1024); } while (0)
; #define PG8_LDB(dst, b, h) do { _Pragma("unroll") for (int n = 0; n < 2; ++n) _Pragma("unroll") for (int k = 0; k < 2; ++k) dst[n][k] = *(const PG8_LAS bf16x8*)(lds + PG8_SB(b, h) + boff + n * 2048 + k * 1024); } while (0)
; #define PG8_WAIT_V(n) asm volatile("s_waitcnt vmcnt(" #n ")" ::: "memory")
; #define PG8_WAIT_L(n) asm volatile("s_waitcnt lgkmcnt(" #n ")" ::: "memory")
; #define PG8_BAR __builtin_amdgcn_s_barrier()
; #define PG8_SCHED __builtin_amdgcn_sched_barrier(0)
; template <bool FP8, class Epi, class Sched>
; __device__ __forceinline__ void gemm_phase(PG8_LAS unsigned char* lds, const Gemm g, const Sched& S, const Epi& E) {
;     ...
;             PG8_LDB(B0, 0, 0); PG8_SCHED; PG8_LDA(At, 0, 0); PG8_STAGE(PG8_SA(1, 1), a1 + hstepA, voffA);
;             PG8_WAIT_L(8); PG8_BAR; PG8_WAIT_L(0); PG8_MMA(0, 0, At, B0); PG8_BAR; PG8_SCHED;
;             PG8_LDB(B1, 0, 1); PG8_STAGE(PG8_SB(0, 0), b2, voffB);
;             PG8_BAR; PG8_WAIT_L(0); PG8_MMA(0, 1, At, B1); PG8_BAR;
;             PG8_LDA(At, 0, 1); PG8_STAGE(PG8_SA(0, 0), a2, voffA);
;             PG8_BAR; PG8_WAIT_L(0); PG8_MMA(1, 0, At, B0); PG8_BAR; PG8_SCHED;
;             PG8_STAGE(PG8_SB(0, 1), b2 + hstep, voffB);
;             PG8_WAIT_V(6); PG8_BAR; PG8_MMA(1, 1, At, B1); PG8_BAR;
;             PG8_LDB(B0, 1, 0); PG8_SCHED; PG8_LDA(At, 1, 0); PG8_STAGE(PG8_SA(0, 1), a2 + hstepA, voffA);
.LBB0_672:
	s_add_u32 s10, s0, 0xfffc0080
	s_addc_u32 s11, s1, -1
	s_add_i32 s30, 0, 0x10000
	v_add_u32_e32 v6, s30, v174
	ds_read_b128 v[10:13], v6
	ds_read_b128 v[14:17], v6 offset:1024
	ds_read_b128 v[2:5], v6 offset:2048
	ds_read_b128 v[6:9], v6 offset:3072
	s_cmp_eq_u32 vcc_hi, 12
	s_cselect_b32 s69, s15, s11
	s_cselect_b32 s68, s87, s10
	s_cselect_b32 s11, s13, vcc_lo
	s_cselect_b32 s10, s94, s95
	v_lshl_add_u64 v[18:19], s[0:1], 0, v[160:161]
	s_add_i32 m0, s26, 0xc000
	ds_read_b128 v[184:187], v182
	ds_read_b128 v[188:191], v182 offset:1024
	ds_read_b128 v[192:195], v182 offset:2048
	ds_read_b128 v[196:199], v182 offset:3072
	ds_read_b128 v[200:203], v182 offset:4096
	ds_read_b128 v[204:207], v182 offset:5120
	ds_read_b128 v[236:239], v182 offset:6144
	ds_read_b128 v[240:243], v182 offset:7168
	global_load_lds_dwordx4 v[18:19], off
	v_lshl_add_u64 v[18:19], s[0:1], 0, v[162:163]
	s_add_i32 m0, s26, 0xe000
	s_nop 0
	global_load_lds_dwordx4 v[18:19], off
	s_waitcnt lgkmcnt(8)
	s_barrier
	s_waitcnt lgkmcnt(0)
	s_waitcnt lgkmcnt(0)
	s_nop 1
	v_mfma_scale_f32_16x16x128_f8f6f4 v[150:153], v[10:17], v[184:191], v[150:153], v172, v172 op_sel_hi:[0,0,0]
	s_nop 1
	v_mfma_scale_f32_16x16x128_f8f6f4 v[146:149], v[2:9], v[184:191], v[146:149], v172, v172 op_sel_hi:[0,0,0]
	s_nop 1
	v_mfma_scale_f32_16x16x128_f8f6f4 v[134:137], v[10:17], v[192:199], v[134:137], v172, v172 op_sel_hi:[0,0,0]
	s_nop 1
	v_mfma_scale_f32_16x16x128_f8f6f4 v[130:133], v[2:9], v[192:199], v[130:133], v172, v172 op_sel_hi:[0,0,0]
	s_nop 1
	v_mfma_scale_f32_16x16x128_f8f6f4 v[118:121], v[10:17], v[200:207], v[118:121], v172, v172 op_sel_hi:[0,0,0]
	s_nop 1
	v_mfma_scale_f32_16x16x128_f8f6f4 v[114:117], v[2:9], v[200:207], v[114:117], v172, v172 op_sel_hi:[0,0,0]
	s_nop 1
	v_mfma_scale_f32_16x16x128_f8f6f4 v[102:105], v[10:17], v[236:243], v[102:105], v172, v172 op_sel_hi:[0,0,0]
	s_nop 1
	v_mfma_scale_f32_16x16x128_f8f6f4 v[98:101], v[2:9], v[236:243], v[98:101], v172, v172 op_sel_hi:[0,0,0]
	s_barrier
	s_add_i32 s86, 0, 0x14000
	s_add_i32 s30, s30, s25
	v_add_u32_e32 v22, s86, v174
	v_lshl_add_u64 v[164:165], s[10:11], 0, v[0:1]
	s_mov_b32 m0, s30
	ds_read_b128 v[208:211], v22
	ds_read_b128 v[212:215], v22 offset:1024
	ds_read_b128 v[18:21], v22 offset:2048
	ds_read_b128 v[22:25], v22 offset:3072
	global_load_lds_dwordx4 v[164:165], off
	v_lshl_add_u64 v[166:167], s[10:11], 0, v[154:155]
	s_add_i32 m0, s30, 0x2000
	s_nop 0
	global_load_lds_dwordx4 v[166:167], off
	s_barrier
	s_waitcnt lgkmcnt(0)
	s_waitcnt lgkmcnt(0)
	s_nop 1
	v_mfma_scale_f32_16x16x128_f8f6f4 v[142:145], v[208:215], v[184:191], v[142:145], v172, v172 op_sel_hi:[0,0,0]
	s_nop 1
	v_mfma_scale_f32_16x16x128_f8f6f4 v[138:141], v[18:25], v[184:191], v[138:141], v172, v172 op_sel_hi:[0,0,0]
	s_nop 1
	v_mfma_scale_f32_16x16x128_f8f6f4 v[126:129], v[208:215], v[192:199], v[126:129], v172, v172 op_sel_hi:[0,0,0]
	s_nop 1
	v_mfma_scale_f32_16x16x128_f8f6f4 v[122:125], v[18:25], v[192:199], v[122:125], v172, v172 op_sel_hi:[0,0,0]
	s_nop 1
	v_mfma_scale_f32_16x16x128_f8f6f4 v[110:113], v[208:215], v[200:207], v[110:113], v172, v172 op_sel_hi:[0,0,0]
	s_nop 1
	v_mfma_scale_f32_16x16x128_f8f6f4 v[106:109], v[18:25], v[200:207], v[106:109], v172, v172 op_sel_hi:[0,0,0]
	s_nop 1
	v_mfma_scale_f32_16x16x128_f8f6f4 v[94:97], v[208:215], v[236:243], v[94:97], v172, v172 op_sel_hi:[0,0,0]
	s_nop 1
	v_mfma_scale_f32_16x16x128_f8f6f4 v[90:93], v[18:25], v[236:243], v[90:93], v172, v172 op_sel_hi:[0,0,0]
	s_mov_b32 m0, s26
	v_lshl_add_u64 v[168:169], s[68:69], 0, v[158:159]
	s_barrier
	ds_read_b128 v[184:187], v182 offset:16384
	ds_read_b128 v[188:191], v182 offset:17408
	ds_read_b128 v[192:195], v182 offset:18432
	ds_read_b128 v[196:199], v182 offset:19456
	ds_read_b128 v[200:203], v182 offset:20480
	ds_read_b128 v[204:207], v182 offset:21504
	ds_read_b128 v[236:239], v182 offset:22528
	ds_read_b128 v[240:243], v182 offset:23552
	global_load_lds_dwordx4 v[168:169], off
	v_lshl_add_u64 v[170:171], s[68:69], 0, v[156:157]
	s_mov_b32 m0, s27
	s_nop 0
	global_load_lds_dwordx4 v[170:171], off
	s_barrier
	s_waitcnt lgkmcnt(0)
	s_waitcnt lgkmcnt(0)
	s_nop 1
	v_mfma_scale_f32_16x16x128_f8f6f4 v[86:89], v[10:17], v[184:191], v[86:89], v172, v172 op_sel_hi:[0,0,0]
	s_nop 1
	v_mfma_scale_f32_16x16x128_f8f6f4 v[82:85], v[2:9], v[184:191], v[82:85], v172, v172 op_sel_hi:[0,0,0]
	s_nop 1
	v_mfma_scale_f32_16x16x128_f8f6f4 v[70:73], v[10:17], v[192:199], v[70:73], v172, v172 op_sel_hi:[0,0,0]
	s_nop 1
	v_mfma_scale_f32_16x16x128_f8f6f4 v[66:69], v[2:9], v[192:199], v[66:69], v172, v172 op_sel_hi:[0,0,0]
	s_nop 1
	v_mfma_scale_f32_16x16x128_f8f6f4 v[54:57], v[10:17], v[200:207], v[54:57], v172, v172 op_sel_hi:[0,0,0]
	s_nop 1
	v_mfma_scale_f32_16x16x128_f8f6f4 v[50:53], v[2:9], v[200:207], v[50:53], v172, v172 op_sel_hi:[0,0,0]
	s_nop 1
	v_mfma_scale_f32_16x16x128_f8f6f4 v[38:41], v[10:17], v[236:243], v[38:41], v172, v172 op_sel_hi:[0,0,0]
	s_nop 1
	v_mfma_scale_f32_16x16x128_f8f6f4 v[34:37], v[2:9], v[236:243], v[34:37], v172, v172 op_sel_hi:[0,0,0]
	s_barrier
	s_add_u32 s30, s10, 0x40000
	s_addc_u32 s31, s11, 0
	s_add_i32 s86, s86, s25
	v_lshl_add_u64 v[2:3], s[30:31], 0, v[0:1]
	s_mov_b32 m0, s86
	s_nop 0
	global_load_lds_dwordx4 v[2:3], off
	v_lshl_add_u64 v[2:3], s[30:31], 0, v[154:155]
	s_add_i32 m0, s86, 0x2000
	s_nop 0
	global_load_lds_dwordx4 v[2:3], off
	s_waitcnt vmcnt(6)
	s_barrier
; #define PG8_STAGE(bufoff, gbase, voff) do { _Pragma("unroll") for (int _i = 0; _i < 2; ++_i) \
;         __builtin_amdgcn_global_load_lds((const unsigned*)((const char*)(gbase) + (voff)[_i]), (PG8_LAS unsigned*)(lds + (bufoff) + ldsw + _i * 8192), 16, 0, 0); } while (0)
; #define PG8_LDA(dst, b, h) do { _Pragma("unroll") for (int m = 0; m < 4; ++m) _Pragma("unroll") for (int k = 0; k < 2; ++k) dst[m][k] = *(const PG8_LAS bf16x8*)(lds + PG8_SA(b, h) + aoff + m * 2048 + k * 1024); } while (0)
; #define PG8_LDB(dst, b, h) do { _Pragma("unroll") for (int n = 0; n < 2; ++n) _Pragma("unroll") for (int k = 0; k < 2; ++k) dst[n][k] = *(const PG8_LAS bf16x8*)(lds + PG8_SB(b, h) + boff + n * 2048 + k * 1024); } while (0)
; #define PG8_WAIT_V(n) asm volatile("s_waitcnt vmcnt(" #n ")" ::: "memory")
; #define PG8_WAIT_L(n) asm volatile("s_waitcnt lgkmcnt(" #n ")" ::: "memory")
; #define PG8_BAR __builtin_amdgcn_s_barrier()
; #define PG8_SCHED __builtin_amdgcn_sched_barrier(0)
; template <bool FP8, class Epi, class Sched>
; __device__ __forceinline__ void gemm_phase(PG8_LAS unsigned char* lds, const Gemm g, const Sched& S, const Epi& E) {
;     ...
;             PG8_STAGE(PG8_SB(0, 1), b2 + hstep, voffB);
;             PG8_WAIT_V(6); PG8_BAR; PG8_MMA(1, 1, At, B1); PG8_BAR;
;             PG8_LDB(B0, 1, 0); PG8_SCHED; PG8_LDA(At, 1, 0); PG8_STAGE(PG8_SA(0, 1), a2 + hstepA, voffA);
;             PG8_WAIT_L(8); PG8_BAR; PG8_WAIT_L(0); PG8_MMA(0, 0, At, B0); PG8_BAR; PG8_SCHED;
;             PG8_LDB(B1, 1, 1); PG8_STAGE(PG8_SB(1, 0), b3, voffB);
;             PG8_BAR; PG8_WAIT_L(0); PG8_MMA(0, 1, At, B1); PG8_BAR;
	s_nop 1
	v_mfma_scale_f32_16x16x128_f8f6f4 v[78:81], v[208:215], v[184:191], v[78:81], v172, v172 op_sel_hi:[0,0,0]
	s_nop 1
	v_mfma_scale_f32_16x16x128_f8f6f4 v[74:77], v[18:25], v[184:191], v[74:77], v172, v172 op_sel_hi:[0,0,0]
	s_nop 1
	v_mfma_scale_f32_16x16x128_f8f6f4 v[62:65], v[208:215], v[192:199], v[62:65], v172, v172 op_sel_hi:[0,0,0]
	s_nop 1
	v_mfma_scale_f32_16x16x128_f8f6f4 v[58:61], v[18:25], v[192:199], v[58:61], v172, v172 op_sel_hi:[0,0,0]
	s_nop 1
	v_mfma_scale_f32_16x16x128_f8f6f4 v[46:49], v[208:215], v[200:207], v[46:49], v172, v172 op_sel_hi:[0,0,0]
	s_nop 1
	v_mfma_scale_f32_16x16x128_f8f6f4 v[42:45], v[18:25], v[200:207], v[42:45], v172, v172 op_sel_hi:[0,0,0]
	s_nop 1
	v_mfma_scale_f32_16x16x128_f8f6f4 v[30:33], v[208:215], v[236:243], v[30:33], v172, v172 op_sel_hi:[0,0,0]
	s_nop 1
	v_mfma_scale_f32_16x16x128_f8f6f4 v[26:29], v[18:25], v[236:243], v[26:29], v172, v172 op_sel_hi:[0,0,0]
	s_add_i32 s86, 0, 0x18000
	v_add_u32_e32 v14, s86, v174
	s_barrier
	ds_read_b128 v[2:5], v14
	ds_read_b128 v[6:9], v14 offset:1024
	ds_read_b128 v[10:13], v14 offset:2048
	ds_read_b128 v[14:17], v14 offset:3072
	s_add_u32 s30, s68, 0x40000
	s_addc_u32 s31, s69, 0
	s_mov_b32 m0, s54
	v_lshl_add_u64 v[208:209], s[30:31], 0, v[158:159]
	ds_read_b128 v[18:21], v182 offset:32768
	ds_read_b128 v[22:25], v182 offset:33792
	ds_read_b128 v[184:187], v182 offset:34816
	ds_read_b128 v[188:191], v182 offset:35840
	ds_read_b128 v[192:195], v182 offset:36864
	ds_read_b128 v[196:199], v182 offset:37888
	ds_read_b128 v[200:203], v182 offset:38912
	ds_read_b128 v[204:207], v182 offset:39936
	global_load_lds_dwordx4 v[208:209], off
	v_lshl_add_u64 v[208:209], s[30:31], 0, v[156:157]
	s_mov_b32 m0, s70
	s_nop 0
	global_load_lds_dwordx4 v[208:209], off
	s_waitcnt lgkmcnt(8)
	s_barrier
	s_waitcnt lgkmcnt(0)
	s_waitcnt lgkmcnt(0)
	s_nop 1
	v_mfma_scale_f32_16x16x128_f8f6f4 v[150:153], v[2:9], v[18:25], v[150:153], v172, v172 op_sel_hi:[0,0,0]
	s_nop 1
	v_mfma_scale_f32_16x16x128_f8f6f4 v[146:149], v[10:17], v[18:25], v[146:149], v172, v172 op_sel_hi:[0,0,0]
	s_nop 1
	v_mfma_scale_f32_16x16x128_f8f6f4 v[134:137], v[2:9], v[184:191], v[134:137], v172, v172 op_sel_hi:[0,0,0]
	s_nop 1
	v_mfma_scale_f32_16x16x128_f8f6f4 v[130:133], v[10:17], v[184:191], v[130:133], v172, v172 op_sel_hi:[0,0,0]
	s_nop 1
	v_mfma_scale_f32_16x16x128_f8f6f4 v[118:121], v[2:9], v[192:199], v[118:121], v172, v172 op_sel_hi:[0,0,0]
	s_nop 1
	v_mfma_scale_f32_16x16x128_f8f6f4 v[114:117], v[10:17], v[192:199], v[114:117], v172, v172 op_sel_hi:[0,0,0]
	s_nop 1
	v_mfma_scale_f32_16x16x128_f8f6f4 v[102:105], v[2:9], v[200:207], v[102:105], v172, v172 op_sel_hi:[0,0,0]
	s_nop 1
	v_mfma_scale_f32_16x16x128_f8f6f4 v[98:101], v[10:17], v[200:207], v[98:101], v172, v172 op_sel_hi:[0,0,0]
	s_barrier
	s_add_i32 s30, 0, 0x1c000
	s_add_i32 s31, s86, s25
	v_add_u32_e32 v183, s30, v174
	v_lshl_add_u64 v[164:165], v[164:165], 0, s[56:57]
	s_mov_b32 m0, s31
	ds_read_b128 v[208:211], v183
	ds_read_b128 v[212:215], v183 offset:1024
	ds_read_b128 v[236:239], v183 offset:2048
	ds_read_b128 v[240:243], v183 offset:3072
	global_load_lds_dwordx4 v[164:165], off
	v_lshl_add_u64 v[164:165], v[166:167], 0, s[56:57]
	s_add_i32 m0, s31, 0x2000
	s_nop 0
	global_load_lds_dwordx4 v[164:165], off
	s_barrier
	s_waitcnt lgkmcnt(0)
	s_waitcnt lgkmcnt(0)
	s_nop 1
	v_mfma_scale_f32_16x16x128_f8f6f4 v[142:145], v[208:215], v[18:25], v[142:145], v172, v172 op_sel_hi:[0,0,0]
	s_nop 1
	v_mfma_scale_f32_16x16x128_f8f6f4 v[138:141], v[236:243], v[18:25], v[138:141], v172, v172 op_sel_hi:[0,0,0]
	s_nop 1
	v_mfma_scale_f32_16x16x128_f8f6f4 v[126:129], v[208:215], v[184:191], v[126:129], v172, v172 op_sel_hi:[0,0,0]
	s_nop 1
	v_mfma_scale_f32_16x16x128_f8f6f4 v[122:125], v[236:243], v[184:191], v[122:125], v172, v172 op_sel_hi:[0,0,0]
	s_nop 1
	v_mfma_scale_f32_16x16x128_f8f6f4 v[110:113], v[208:215], v[192:199], v[110:113], v172, v172 op_sel_hi:[0,0,0]
	s_nop 1
	v_mfma_scale_f32_16x16x128_f8f6f4 v[106:109], v[236:243], v[192:199], v[106:109], v172, v172 op_sel_hi:[0,0,0]
	s_nop 1
	v_mfma_scale_f32_16x16x128_f8f6f4 v[94:97], v[208:215], v[200:207], v[94:97], v172, v172 op_sel_hi:[0,0,0]
	s_nop 1
	v_mfma_scale_f32_16x16x128_f8f6f4 v[90:93], v[236:243], v[200:207], v[90:93], v172, v172 op_sel_hi:[0,0,0]
	s_mov_b32 m0, s71
	v_lshl_add_u64 v[164:165], v[168:169], 0, s[56:57]
	s_barrier
; #define PG8_STAGE(bufoff, gbase, voff) do { _Pragma("unroll") for (int _i = 0; _i < 2; ++_i) \
;         __builtin_amdgcn_global_load_lds((const unsigned*)((const char*)(gbase) + (voff)[_i]), (PG8_LAS unsigned*)(lds + (bufoff) + ldsw + _i * 8192), 16, 0, 0); } while (0)
; #define PG8_LDA(dst, b, h) do { _Pragma("unroll") for (int m = 0; m < 4; ++m) _Pragma("unroll") for (int k = 0; k < 2; ++k) dst[m][k] = *(const PG8_LAS bf16x8*)(lds + PG8_SA(b, h) + aoff + m * 2048 + k * 1024); } while (0)
; #define PG8_WAIT_V(n) asm volatile("s_waitcnt vmcnt(" #n ")" ::: "memory")
; #define PG8_WAIT_L(n) asm volatile("s_waitcnt lgkmcnt(" #n ")" ::: "memory")
; #define PG8_BAR __builtin_amdgcn_s_barrier()
; #define PG8_SCHED __builtin_amdgcn_sched_barrier(0)
; template <bool FP8, class Epi, class Sched>
; __device__ __forceinline__ void gemm_phase(PG8_LAS unsigned char* lds, const Gemm g, const Sched& S, const Epi& E) {
;     ...
;             PG8_LDA(At, 1, 1); PG8_STAGE(PG8_SA(1, 0), a3, voffA);
;             PG8_BAR; PG8_WAIT_L(0); PG8_MMA(1, 0, At, B0); PG8_BAR; PG8_SCHED;
;             PG8_STAGE(PG8_SB(1, 1), b3 + hstep, voffB);
;             PG8_WAIT_V(6); PG8_BAR; PG8_MMA(1, 1, At, B1); PG8_BAR;
;         }
;         if constexpr (FP8) asm volatile("s_nop 15\n\ts_nop 15" ::: "memory");
;   DI void operator()(const f32x4 (&acc)[2][2][4][2], const pg8::Unit& u, int wr, int wc, int fr, int fq) const {
;     ...
;             }
;           } else if (MODE == 3) {
;             if (col < N) { const bool lo = col < csplit; u16* bp = lo ? d0 : d1; const int ldd = lo ? 2048 : 4096, oc = lo ? col : col + (coff2 - 2112); dst = bp + (size_t)row * ldd + oc + (lo ? coff1 : 0); }
;           } else {
;             if (((col >> 6) % 3) == 2) rot(v0, v1, row, col);
;             dst = d0 + (size_t)row * 3072 + col;
;           }
;           if (dst) { u32x4 w = {pk2(v0[0], v0[1]), pk2(v0[2], v0[3]), pk2(v1[0], v1[1]), pk2(v1[2], v1[3])}; *(u32x4*)dst = w; }
	ds_read_b128 v[18:21], v182 offset:49152
	ds_read_b128 v[22:25], v182 offset:50176
	ds_read_b128 v[184:187], v182 offset:51200
	ds_read_b128 v[188:191], v182 offset:52224
	ds_read_b128 v[192:195], v182 offset:53248
	ds_read_b128 v[196:199], v182 offset:54272
	ds_read_b128 v[200:203], v182 offset:55296
	ds_read_b128 v[204:207], v182 offset:56320
	global_load_lds_dwordx4 v[164:165], off
	v_lshl_add_u64 v[164:165], v[170:171], 0, s[56:57]
	s_mov_b32 m0, s72
	s_nop 0
	global_load_lds_dwordx4 v[164:165], off
	s_barrier
	s_waitcnt lgkmcnt(0)
	s_waitcnt lgkmcnt(0)
	s_nop 1
	v_mfma_scale_f32_16x16x128_f8f6f4 v[86:89], v[2:9], v[18:25], v[86:89], v172, v172 op_sel_hi:[0,0,0]
	s_nop 1
	v_mfma_scale_f32_16x16x128_f8f6f4 v[82:85], v[10:17], v[18:25], v[82:85], v172, v172 op_sel_hi:[0,0,0]
	s_nop 1
	v_mfma_scale_f32_16x16x128_f8f6f4 v[70:73], v[2:9], v[184:191], v[70:73], v172, v172 op_sel_hi:[0,0,0]
	s_nop 1
	v_mfma_scale_f32_16x16x128_f8f6f4 v[66:69], v[10:17], v[184:191], v[66:69], v172, v172 op_sel_hi:[0,0,0]
	s_nop 1
	v_mfma_scale_f32_16x16x128_f8f6f4 v[54:57], v[2:9], v[192:199], v[54:57], v172, v172 op_sel_hi:[0,0,0]
	s_nop 1
	v_mfma_scale_f32_16x16x128_f8f6f4 v[50:53], v[10:17], v[192:199], v[50:53], v172, v172 op_sel_hi:[0,0,0]
	s_nop 1
	v_mfma_scale_f32_16x16x128_f8f6f4 v[38:41], v[2:9], v[200:207], v[38:41], v172, v172 op_sel_hi:[0,0,0]
	s_nop 1
	v_mfma_scale_f32_16x16x128_f8f6f4 v[34:37], v[10:17], v[200:207], v[34:37], v172, v172 op_sel_hi:[0,0,0]
	s_barrier
	s_add_u32 s10, s10, 0x40080
	s_addc_u32 s11, s11, 0
	s_add_i32 s30, s30, s25
	v_lshl_add_u64 v[2:3], s[10:11], 0, v[0:1]
	s_mov_b32 m0, s30
	s_nop 0
	global_load_lds_dwordx4 v[2:3], off
	v_lshl_add_u64 v[2:3], s[10:11], 0, v[154:155]
	s_add_i32 m0, s30, 0x2000
	s_nop 0
	global_load_lds_dwordx4 v[2:3], off
	s_waitcnt vmcnt(6)
	s_barrier
	s_nop 1
	v_mfma_scale_f32_16x16x128_f8f6f4 v[78:81], v[208:215], v[18:25], v[78:81], v172, v172 op_sel_hi:[0,0,0]
	s_nop 1
	v_mfma_scale_f32_16x16x128_f8f6f4 v[74:77], v[236:243], v[18:25], v[74:77], v172, v172 op_sel_hi:[0,0,0]
	s_nop 1
	v_mfma_scale_f32_16x16x128_f8f6f4 v[62:65], v[208:215], v[184:191], v[62:65], v172, v172 op_sel_hi:[0,0,0]
	s_nop 1
	v_mfma_scale_f32_16x16x128_f8f6f4 v[58:61], v[236:243], v[184:191], v[58:61], v172, v172 op_sel_hi:[0,0,0]
	s_nop 1
	v_mfma_scale_f32_16x16x128_f8f6f4 v[46:49], v[208:215], v[192:199], v[46:49], v172, v172 op_sel_hi:[0,0,0]
	s_nop 1
	v_mfma_scale_f32_16x16x128_f8f6f4 v[42:45], v[236:243], v[192:199], v[42:45], v172, v172 op_sel_hi:[0,0,0]
	s_nop 1
	v_mfma_scale_f32_16x16x128_f8f6f4 v[30:33], v[208:215], v[200:207], v[30:33], v172, v172 op_sel_hi:[0,0,0]
	s_nop 1
	v_mfma_scale_f32_16x16x128_f8f6f4 v[26:29], v[236:243], v[200:207], v[26:29], v172, v172 op_sel_hi:[0,0,0]
	s_add_i32 vcc_hi, vcc_hi, 2
	s_add_u32 s0, s0, 0x100
	s_addc_u32 s1, s1, 0
	s_add_u32 s95, s95, 0x100
	s_addc_u32 vcc_lo, vcc_lo, 0
	s_cmp_gt_u32 vcc_hi, 13
	s_barrier
	s_cbranch_scc0 .LBB0_672
	s_nop 15
	s_nop 15
	v_lshl_add_u32 v4, s29, 8, v173
	v_lshl_or_b32 v2, s28, 8, v175
	s_movk_i32 s0, 0xa00
	v_ashrrev_i32_e32 v5, 31, v4
	v_cmp_gt_i32_e32 vcc, s0, v2
	v_mov_b64_e32 v[6:7], 0
	s_and_saveexec_b64 s[10:11], vcc
	s_movk_i32 s20, 0x600
	s_cbranch_execz .LBB0_675
	v_mov_b32_e32 v3, s5
	v_mov_b32_e32 v6, s83
	v_cmp_gt_i32_e64 s[0:1], s20, v2
	s_nop 1
	v_cndmask_b32_e64 v7, v3, v6, s[0:1]
	v_mov_b32_e32 v3, s4
	v_mov_b32_e32 v6, s82
	v_cndmask_b32_e64 v6, v3, v6, s[0:1]
	v_cndmask_b32_e64 v3, v230, 0, s[0:1]
	v_add_u32_e32 v8, v3, v2
	v_cndmask_b32_e64 v3, 12, 11, s[0:1]
	v_lshlrev_b64 v[10:11], v3, v[4:5]
	v_lshl_add_u64 v[6:7], v[10:11], 1, v[6:7]
	v_ashrrev_i32_e32 v9, 31, v8
	v_lshl_add_u64 v[6:7], v[8:9], 1, v[6:7]

; #define PG8_STAGE(bufoff, gbase, voff) do { _Pragma("unroll") for (int _i = 0; _i < 2; ++_i) \
;         __builtin_amdgcn_global_load_lds((const unsigned*)((const char*)(gbase) + (voff)[_i]), (PG8_LAS unsigned*)(lds + (bufoff) + ldsw + _i * 8192), 16, 0, 0); } while (0)
; #define PG8_LDA(dst, b, h) do { _Pragma("unroll") for (int m = 0; m < 4; ++m) _Pragma("unroll") for (int k = 0; k < 2; ++k) dst[m][k] = *(const PG8_LAS bf16x8*)(lds + PG8_SA(b, h) + aoff + m * 2048 + k * 1024); } while (0)
; #define PG8_LDB(dst, b, h) do { _Pragma("unroll") for (int n = 0; n < 2; ++n) _Pragma("unroll") for (int k = 0; k < 2; ++k) dst[n][k] = *(const PG8_LAS bf16x8*)(lds + PG8_SB(b, h) + boff + n * 2048 + k * 1024); } while (0)
; #define PG8_WAIT_L(n) asm volatile("s_waitcnt lgkmcnt(" #n ")" ::: "memory")
; #define PG8_BAR __builtin_amdgcn_s_barrier()
; #define PG8_SCHED __builtin_amdgcn_sched_barrier(0)
; template <bool FP8, class Epi, class Sched>
; __device__ __forceinline__ void gemm_phase(PG8_LAS unsigned char* lds, const Gemm g, const Sched& S, const Epi& E) {
;     ...
;             PG8_LDB(B0, 0, 0); PG8_SCHED; PG8_LDA(At, 0, 0); PG8_STAGE(PG8_SA(1, 1), a1 + hstepA, voffA);
;             PG8_WAIT_L(8); PG8_BAR; PG8_WAIT_L(0); PG8_MMA(0, 0, At, B0); PG8_BAR; PG8_SCHED;
;             PG8_LDB(B1, 0, 1); PG8_STAGE(PG8_SB(0, 0), b2, voffB);
;             PG8_BAR; PG8_WAIT_L(0); PG8_MMA(0, 1, At, B1); PG8_BAR;
;             PG8_LDA(At, 0, 1); PG8_STAGE(PG8_SA(0, 0), a2, voffA);
;             PG8_BAR; PG8_WAIT_L(0); PG8_MMA(1, 0, At, B0); PG8_BAR; PG8_SCHED;
.LBB0_753:
	s_add_u32 s18, s0, 0xfff80080
	s_addc_u32 s19, s1, -1
	s_add_i32 s30, 0, 0x10000
	v_add_u32_e32 v144, s30, v147
	ds_read_b128 v[140:143], v144
	ds_read_b128 v[150:153], v144 offset:1024
	ds_read_b128 v[154:157], v144 offset:2048
	ds_read_b128 v[158:161], v144 offset:3072
	s_cmp_eq_u32 s87, 28
	s_cselect_b32 s67, s13, s19
	s_cselect_b32 s66, s70, s18
	s_cselect_b32 s19, s11, s73
	s_cselect_b32 s18, s71, s72
	v_lshl_add_u64 v[144:145], s[0:1], 0, v[136:137]
	s_add_i32 m0, s24, 0xc000
	ds_read_b128 v[162:165], v149
	ds_read_b128 v[166:169], v149 offset:1024
	ds_read_b128 v[170:173], v149 offset:2048
	ds_read_b128 v[182:185], v149 offset:3072
	ds_read_b128 v[186:189], v149 offset:4096
	ds_read_b128 v[190:193], v149 offset:5120
	ds_read_b128 v[194:197], v149 offset:6144
	ds_read_b128 v[198:201], v149 offset:7168
	global_load_lds_dwordx4 v[144:145], off
	v_lshl_add_u64 v[144:145], s[0:1], 0, v[138:139]
	s_add_i32 m0, s24, 0xe000
	s_nop 0
	global_load_lds_dwordx4 v[144:145], off
	s_waitcnt lgkmcnt(8)
	s_barrier
	s_waitcnt lgkmcnt(0)
	s_waitcnt lgkmcnt(0)
	v_mfma_f32_16x16x32_bf16 v[126:129], v[140:143], v[162:165], v[126:129]
	v_mfma_f32_16x16x32_bf16 v[122:125], v[154:157], v[162:165], v[122:125]
	v_mfma_f32_16x16x32_bf16 v[114:117], v[140:143], v[170:173], v[114:117]
	v_mfma_f32_16x16x32_bf16 v[106:109], v[154:157], v[170:173], v[106:109]
	v_mfma_f32_16x16x32_bf16 v[98:101], v[140:143], v[186:189], v[98:101]
	v_mfma_f32_16x16x32_bf16 v[90:93], v[154:157], v[186:189], v[90:93]
	v_mfma_f32_16x16x32_bf16 v[82:85], v[140:143], v[194:197], v[82:85]
	v_mfma_f32_16x16x32_bf16 v[74:77], v[154:157], v[194:197], v[74:77]
	v_mfma_f32_16x16x32_bf16 v[126:129], v[150:153], v[166:169], v[126:129]
	v_mfma_f32_16x16x32_bf16 v[122:125], v[158:161], v[166:169], v[122:125]
	v_mfma_f32_16x16x32_bf16 v[114:117], v[150:153], v[182:185], v[114:117]
	v_mfma_f32_16x16x32_bf16 v[106:109], v[158:161], v[182:185], v[106:109]
	v_mfma_f32_16x16x32_bf16 v[98:101], v[150:153], v[190:193], v[98:101]
	v_mfma_f32_16x16x32_bf16 v[90:93], v[158:161], v[190:193], v[90:93]
	v_mfma_f32_16x16x32_bf16 v[82:85], v[150:153], v[198:201], v[82:85]
	v_mfma_f32_16x16x32_bf16 v[74:77], v[158:161], v[198:201], v[74:77]
	s_barrier
	s_add_i32 s86, 0, 0x14000
	v_add_u32_e32 v144, s86, v147
	s_add_i32 s30, s30, s23
	ds_read_b128 v[202:205], v144
	ds_read_b128 v[206:209], v144 offset:1024
	ds_read_b128 v[210:213], v144 offset:2048
	ds_read_b128 v[214:217], v144 offset:3072
	v_lshl_add_u64 v[144:145], s[18:19], 0, v[0:1]
	s_mov_b32 m0, s30
	v_lshl_add_u64 v[174:175], s[18:19], 0, v[130:131]
	global_load_lds_dwordx4 v[144:145], off
	s_add_i32 m0, s30, 0x2000
	s_nop 0
	global_load_lds_dwordx4 v[174:175], off
	s_barrier
	s_waitcnt lgkmcnt(0)
	s_waitcnt lgkmcnt(0)
	v_mfma_f32_16x16x32_bf16 v[118:121], v[202:205], v[162:165], v[118:121]
	v_mfma_f32_16x16x32_bf16 v[110:113], v[210:213], v[162:165], v[110:113]
	v_mfma_f32_16x16x32_bf16 v[102:105], v[202:205], v[170:173], v[102:105]
	v_mfma_f32_16x16x32_bf16 v[94:97], v[210:213], v[170:173], v[94:97]
	v_mfma_f32_16x16x32_bf16 v[86:89], v[202:205], v[186:189], v[86:89]
	v_mfma_f32_16x16x32_bf16 v[78:81], v[210:213], v[186:189], v[78:81]
	v_mfma_f32_16x16x32_bf16 v[70:73], v[202:205], v[194:197], v[70:73]
	v_mfma_f32_16x16x32_bf16 v[66:69], v[210:213], v[194:197], v[66:69]
	v_mfma_f32_16x16x32_bf16 v[118:121], v[206:209], v[166:169], v[118:121]
	v_mfma_f32_16x16x32_bf16 v[110:113], v[214:217], v[166:169], v[110:113]
	v_mfma_f32_16x16x32_bf16 v[102:105], v[206:209], v[182:185], v[102:105]
	v_mfma_f32_16x16x32_bf16 v[94:97], v[214:217], v[182:185], v[94:97]
	v_mfma_f32_16x16x32_bf16 v[86:89], v[206:209], v[190:193], v[86:89]
	v_mfma_f32_16x16x32_bf16 v[78:81], v[214:217], v[190:193], v[78:81]
	v_mfma_f32_16x16x32_bf16 v[70:73], v[206:209], v[198:201], v[70:73]
	v_mfma_f32_16x16x32_bf16 v[66:69], v[214:217], v[198:201], v[66:69]
	s_mov_b32 m0, s24
	v_lshl_add_u64 v[236:237], s[66:67], 0, v[134:135]
	s_barrier
	ds_read_b128 v[162:165], v149 offset:16384
	ds_read_b128 v[166:169], v149 offset:17408
	ds_read_b128 v[170:173], v149 offset:18432
	ds_read_b128 v[182:185], v149 offset:19456
	ds_read_b128 v[186:189], v149 offset:20480
	ds_read_b128 v[190:193], v149 offset:21504
	ds_read_b128 v[194:197], v149 offset:22528
	ds_read_b128 v[198:201], v149 offset:23552
	global_load_lds_dwordx4 v[236:237], off
	v_lshl_add_u64 v[238:239], s[66:67], 0, v[132:133]
	s_mov_b32 m0, s25
	s_nop 0
	global_load_lds_dwordx4 v[238:239], off
	s_barrier
	s_waitcnt lgkmcnt(0)
	s_waitcnt lgkmcnt(0)
	v_mfma_f32_16x16x32_bf16 v[62:65], v[140:143], v[162:165], v[62:65]
	v_mfma_f32_16x16x32_bf16 v[58:61], v[154:157], v[162:165], v[58:61]
	v_mfma_f32_16x16x32_bf16 v[50:53], v[140:143], v[170:173], v[50:53]
	v_mfma_f32_16x16x32_bf16 v[42:45], v[154:157], v[170:173], v[42:45]
	v_mfma_f32_16x16x32_bf16 v[34:37], v[140:143], v[186:189], v[34:37]
	v_mfma_f32_16x16x32_bf16 v[26:29], v[154:157], v[186:189], v[26:29]
	v_mfma_f32_16x16x32_bf16 v[18:21], v[140:143], v[194:197], v[18:21]
	v_mfma_f32_16x16x32_bf16 v[10:13], v[154:157], v[194:197], v[10:13]
	v_mfma_f32_16x16x32_bf16 v[62:65], v[150:153], v[166:169], v[62:65]
	v_mfma_f32_16x16x32_bf16 v[58:61], v[158:161], v[166:169], v[58:61]
	v_mfma_f32_16x16x32_bf16 v[50:53], v[150:153], v[182:185], v[50:53]
	v_mfma_f32_16x16x32_bf16 v[42:45], v[158:161], v[182:185], v[42:45]
	v_mfma_f32_16x16x32_bf16 v[34:37], v[150:153], v[190:193], v[34:37]
	v_mfma_f32_16x16x32_bf16 v[26:29], v[158:161], v[190:193], v[26:29]
	v_mfma_f32_16x16x32_bf16 v[18:21], v[150:153], v[198:201], v[18:21]
	v_mfma_f32_16x16x32_bf16 v[10:13], v[158:161], v[198:201], v[10:13]
	s_barrier
; #define PG8_STAGE(bufoff, gbase, voff) do { _Pragma("unroll") for (int _i = 0; _i < 2; ++_i) \
;         __builtin_amdgcn_global_load_lds((const unsigned*)((const char*)(gbase) + (voff)[_i]), (PG8_LAS unsigned*)(lds + (bufoff) + ldsw + _i * 8192), 16, 0, 0); } while (0)
; #define PG8_LDA(dst, b, h) do { _Pragma("unroll") for (int m = 0; m < 4; ++m) _Pragma("unroll") for (int k = 0; k < 2; ++k) dst[m][k] = *(const PG8_LAS bf16x8*)(lds + PG8_SA(b, h) + aoff + m * 2048 + k * 1024); } while (0)
; #define PG8_LDB(dst, b, h) do { _Pragma("unroll") for (int n = 0; n < 2; ++n) _Pragma("unroll") for (int k = 0; k < 2; ++k) dst[n][k] = *(const PG8_LAS bf16x8*)(lds + PG8_SB(b, h) + boff + n * 2048 + k * 1024); } while (0)
; #define PG8_WAIT_V(n) asm volatile("s_waitcnt vmcnt(" #n ")" ::: "memory")
; #define PG8_WAIT_L(n) asm volatile("s_waitcnt lgkmcnt(" #n ")" ::: "memory")
; #define PG8_BAR __builtin_amdgcn_s_barrier()
; #define PG8_SCHED __builtin_amdgcn_sched_barrier(0)
; template <bool FP8, class Epi, class Sched>
; __device__ __forceinline__ void gemm_phase(PG8_LAS unsigned char* lds, const Gemm g, const Sched& S, const Epi& E) {
;     ...
;             PG8_STAGE(PG8_SB(0, 1), b2 + hstep, voffB);
;             PG8_WAIT_V(6); PG8_BAR; PG8_MMA(1, 1, At, B1); PG8_BAR;
;             PG8_LDB(B0, 1, 0); PG8_SCHED; PG8_LDA(At, 1, 0); PG8_STAGE(PG8_SA(0, 1), a2 + hstepA, voffA);
;             PG8_WAIT_L(8); PG8_BAR; PG8_WAIT_L(0); PG8_MMA(0, 0, At, B0); PG8_BAR; PG8_SCHED;
	s_add_u32 s30, s18, 0x80000
	s_addc_u32 s31, s19, 0
	s_add_i32 s86, s86, s23
	v_lshl_add_u64 v[140:141], s[30:31], 0, v[0:1]
	s_mov_b32 m0, s86
	s_nop 0
	global_load_lds_dwordx4 v[140:141], off
	v_lshl_add_u64 v[140:141], s[30:31], 0, v[130:131]
	s_add_i32 m0, s86, 0x2000
	s_nop 0
	global_load_lds_dwordx4 v[140:141], off
	s_waitcnt vmcnt(6)
	s_barrier
	v_mfma_f32_16x16x32_bf16 v[54:57], v[202:205], v[162:165], v[54:57]
	v_mfma_f32_16x16x32_bf16 v[46:49], v[210:213], v[162:165], v[46:49]
	v_mfma_f32_16x16x32_bf16 v[38:41], v[202:205], v[170:173], v[38:41]
	v_mfma_f32_16x16x32_bf16 v[30:33], v[210:213], v[170:173], v[30:33]
	v_mfma_f32_16x16x32_bf16 v[22:25], v[202:205], v[186:189], v[22:25]
	v_mfma_f32_16x16x32_bf16 v[14:17], v[210:213], v[186:189], v[14:17]
	v_mfma_f32_16x16x32_bf16 v[6:9], v[202:205], v[194:197], v[6:9]
	v_mfma_f32_16x16x32_bf16 v[2:5], v[210:213], v[194:197], v[2:5]
	v_mfma_f32_16x16x32_bf16 v[54:57], v[206:209], v[166:169], v[54:57]
	v_mfma_f32_16x16x32_bf16 v[46:49], v[214:217], v[166:169], v[46:49]
	v_mfma_f32_16x16x32_bf16 v[38:41], v[206:209], v[182:185], v[38:41]
	v_mfma_f32_16x16x32_bf16 v[30:33], v[214:217], v[182:185], v[30:33]
	v_mfma_f32_16x16x32_bf16 v[22:25], v[206:209], v[190:193], v[22:25]
	v_mfma_f32_16x16x32_bf16 v[14:17], v[214:217], v[190:193], v[14:17]
	v_mfma_f32_16x16x32_bf16 v[6:9], v[206:209], v[198:201], v[6:9]
	v_mfma_f32_16x16x32_bf16 v[2:5], v[214:217], v[198:201], v[2:5]
	s_add_i32 s86, 0, 0x18000
	v_add_u32_e32 v158, s86, v147
	s_barrier
	ds_read_b128 v[140:143], v158
	ds_read_b128 v[150:153], v158 offset:1024
	ds_read_b128 v[154:157], v158 offset:2048
	ds_read_b128 v[158:161], v158 offset:3072
	s_add_u32 s30, s66, 0x80000
	s_addc_u32 s31, s67, 0
	s_mov_b32 m0, s26
	v_lshl_add_u64 v[202:203], s[30:31], 0, v[134:135]
	ds_read_b128 v[162:165], v149 offset:32768
	ds_read_b128 v[166:169], v149 offset:33792
	ds_read_b128 v[170:173], v149 offset:34816
	ds_read_b128 v[182:185], v149 offset:35840
	ds_read_b128 v[186:189], v149 offset:36864
	ds_read_b128 v[190:193], v149 offset:37888
	ds_read_b128 v[194:197], v149 offset:38912
	ds_read_b128 v[198:201], v149 offset:39936
	global_load_lds_dwordx4 v[202:203], off
	v_lshl_add_u64 v[202:203], s[30:31], 0, v[132:133]
	s_mov_b32 m0, s27
	s_nop 0
	global_load_lds_dwordx4 v[202:203], off
	s_waitcnt lgkmcnt(8)
	s_barrier
	s_waitcnt lgkmcnt(0)
	s_waitcnt lgkmcnt(0)
	v_mfma_f32_16x16x32_bf16 v[126:129], v[140:143], v[162:165], v[126:129]
	v_mfma_f32_16x16x32_bf16 v[122:125], v[154:157], v[162:165], v[122:125]
	v_mfma_f32_16x16x32_bf16 v[114:117], v[140:143], v[170:173], v[114:117]
	v_mfma_f32_16x16x32_bf16 v[106:109], v[154:157], v[170:173], v[106:109]
	v_mfma_f32_16x16x32_bf16 v[98:101], v[140:143], v[186:189], v[98:101]
	v_mfma_f32_16x16x32_bf16 v[90:93], v[154:157], v[186:189], v[90:93]
	v_mfma_f32_16x16x32_bf16 v[82:85], v[140:143], v[194:197], v[82:85]
	v_mfma_f32_16x16x32_bf16 v[74:77], v[154:157], v[194:197], v[74:77]
	v_mfma_f32_16x16x32_bf16 v[126:129], v[150:153], v[166:169], v[126:129]
	v_mfma_f32_16x16x32_bf16 v[122:125], v[158:161], v[166:169], v[122:125]
	v_mfma_f32_16x16x32_bf16 v[114:117], v[150:153], v[182:185], v[114:117]
	v_mfma_f32_16x16x32_bf16 v[106:109], v[158:161], v[182:185], v[106:109]
	v_mfma_f32_16x16x32_bf16 v[98:101], v[150:153], v[190:193], v[98:101]
	v_mfma_f32_16x16x32_bf16 v[90:93], v[158:161], v[190:193], v[90:93]
	v_mfma_f32_16x16x32_bf16 v[82:85], v[150:153], v[198:201], v[82:85]
	v_mfma_f32_16x16x32_bf16 v[74:77], v[158:161], v[198:201], v[74:77]
	s_barrier
	s_add_i32 s30, 0, 0x1c000
	s_add_i32 s31, s86, s23
	v_add_u32_e32 v214, s30, v147
	v_lshl_add_u64 v[144:145], v[144:145], 0, s[56:57]
	s_mov_b32 m0, s31
	ds_read_b128 v[202:205], v214
	ds_read_b128 v[206:209], v214 offset:1024
	ds_read_b128 v[210:213], v214 offset:2048
	ds_read_b128 v[214:217], v214 offset:3072
	global_load_lds_dwordx4 v[144:145], off
	v_lshl_add_u64 v[144:145], v[174:175], 0, s[56:57]
	s_add_i32 m0, s31, 0x2000
	s_nop 0
	global_load_lds_dwordx4 v[144:145], off
	s_barrier
; #define PG8_STAGE(bufoff, gbase, voff) do { _Pragma("unroll") for (int _i = 0; _i < 2; ++_i) \
;         __builtin_amdgcn_global_load_lds((const unsigned*)((const char*)(gbase) + (voff)[_i]), (PG8_LAS unsigned*)(lds + (bufoff) + ldsw + _i * 8192), 16, 0, 0); } while (0)
; #define PG8_WAIT_V(n) asm volatile("s_waitcnt vmcnt(" #n ")" ::: "memory")
; #define PG8_WAIT_L(n) asm volatile("s_waitcnt lgkmcnt(" #n ")" ::: "memory")
; #define PG8_BAR __builtin_amdgcn_s_barrier()
; template <bool FP8, class Epi, class Sched>
; __device__ __forceinline__ void gemm_phase(PG8_LAS unsigned char* lds, const Gemm g, const Sched& S, const Epi& E) {
;     ...
;             PG8_LDB(B1, 1, 1); PG8_STAGE(PG8_SB(1, 0), b3, voffB);
;             PG8_BAR; PG8_WAIT_L(0); PG8_MMA(0, 1, At, B1); PG8_BAR;
;             PG8_LDA(At, 1, 1); PG8_STAGE(PG8_SA(1, 0), a3, voffA);
;             PG8_BAR; PG8_WAIT_L(0); PG8_MMA(1, 0, At, B0); PG8_BAR; PG8_SCHED;
;             PG8_STAGE(PG8_SB(1, 1), b3 + hstep, voffB);
;             PG8_WAIT_V(6); PG8_BAR; PG8_MMA(1, 1, At, B1); PG8_BAR;
;   DI void operator()(const f32x4 (&acc)[2][2][4][2], const pg8::Unit& u, int wr, int wc, int fr, int fq) const {
;     ...
;           const int col = colb + bj * 128;
;           f32x4 v0 = acc[ai][bj][m][0] * sc, v1 = acc[ai][bj][m][1] * sc;
;           u16* dst = nullptr;
;           if (MODE == 0) { if (col < N) dst = d0 + (size_t)row * ld0 + (col + coff2 + ((col < csplit) ? (coff1 - coff2) : 0)); }
;           else if (MODE == 1) {
;             const int oc = col + coff2 + ((col < csplit) ? (coff1 - coff2) : 0);
;             if (col < N) {
;               if (oc < 2048) dst = d0 + (size_t)row * 2048 + oc;
;               else if (oc < 2112) { rot(v0, v1, row, oc); dst = d2 + (size_t)row * 64 + (oc - 2048); }
;               else dst = d1 + (size_t)row * 4096 + (oc - 2112);
;             }
;           } else if (MODE == 3) {
;             if (col < N) { const bool lo = col < csplit; u16* bp = lo ? d0 : d1; const int ldd = lo ? 2048 : 4096, oc = lo ? col : col + (coff2 - 2112); dst = bp + (size_t)row * ldd + oc + (lo ? coff1 : 0); }
;           } else {
;             if (((col >> 6) % 3) == 2) rot(v0, v1, row, col);
;             dst = d0 + (size_t)row * 3072 + col;
;           }
;           if (dst) { u32x4 w = {pk2(v0[0], v0[1]), pk2(v0[2], v0[3]), pk2(v1[0], v1[1]), pk2(v1[2], v1[3])}; *(u32x4*)dst = w; }
	s_waitcnt lgkmcnt(0)
	s_waitcnt lgkmcnt(0)
	v_mfma_f32_16x16x32_bf16 v[118:121], v[202:205], v[162:165], v[118:121]
	v_mfma_f32_16x16x32_bf16 v[110:113], v[210:213], v[162:165], v[110:113]
	v_mfma_f32_16x16x32_bf16 v[102:105], v[202:205], v[170:173], v[102:105]
	v_mfma_f32_16x16x32_bf16 v[94:97], v[210:213], v[170:173], v[94:97]
	v_mfma_f32_16x16x32_bf16 v[86:89], v[202:205], v[186:189], v[86:89]
	v_mfma_f32_16x16x32_bf16 v[78:81], v[210:213], v[186:189], v[78:81]
	v_mfma_f32_16x16x32_bf16 v[70:73], v[202:205], v[194:197], v[70:73]
	v_mfma_f32_16x16x32_bf16 v[66:69], v[210:213], v[194:197], v[66:69]
	v_mfma_f32_16x16x32_bf16 v[118:121], v[206:209], v[166:169], v[118:121]
	v_mfma_f32_16x16x32_bf16 v[110:113], v[214:217], v[166:169], v[110:113]
	v_mfma_f32_16x16x32_bf16 v[102:105], v[206:209], v[182:185], v[102:105]
	v_mfma_f32_16x16x32_bf16 v[94:97], v[214:217], v[182:185], v[94:97]
	v_mfma_f32_16x16x32_bf16 v[86:89], v[206:209], v[190:193], v[86:89]
	v_mfma_f32_16x16x32_bf16 v[78:81], v[214:217], v[190:193], v[78:81]
	v_mfma_f32_16x16x32_bf16 v[70:73], v[206:209], v[198:201], v[70:73]
	v_mfma_f32_16x16x32_bf16 v[66:69], v[214:217], v[198:201], v[66:69]
	s_mov_b32 m0, s28
	v_lshl_add_u64 v[144:145], v[236:237], 0, s[56:57]
	s_barrier
	ds_read_b128 v[162:165], v149 offset:49152
	ds_read_b128 v[166:169], v149 offset:50176
	ds_read_b128 v[170:173], v149 offset:51200
	ds_read_b128 v[182:185], v149 offset:52224
	ds_read_b128 v[186:189], v149 offset:53248
	ds_read_b128 v[190:193], v149 offset:54272
	ds_read_b128 v[194:197], v149 offset:55296
	ds_read_b128 v[198:201], v149 offset:56320
	global_load_lds_dwordx4 v[144:145], off
	v_lshl_add_u64 v[144:145], v[238:239], 0, s[56:57]
	s_mov_b32 m0, s29
	s_nop 0
	global_load_lds_dwordx4 v[144:145], off
	s_barrier
	s_waitcnt lgkmcnt(0)
	s_waitcnt lgkmcnt(0)
	v_mfma_f32_16x16x32_bf16 v[62:65], v[140:143], v[162:165], v[62:65]
	v_mfma_f32_16x16x32_bf16 v[58:61], v[154:157], v[162:165], v[58:61]
	v_mfma_f32_16x16x32_bf16 v[50:53], v[140:143], v[170:173], v[50:53]
	v_mfma_f32_16x16x32_bf16 v[42:45], v[154:157], v[170:173], v[42:45]
	v_mfma_f32_16x16x32_bf16 v[34:37], v[140:143], v[186:189], v[34:37]
	v_mfma_f32_16x16x32_bf16 v[26:29], v[154:157], v[186:189], v[26:29]
	v_mfma_f32_16x16x32_bf16 v[18:21], v[140:143], v[194:197], v[18:21]
	v_mfma_f32_16x16x32_bf16 v[10:13], v[154:157], v[194:197], v[10:13]
	v_mfma_f32_16x16x32_bf16 v[62:65], v[150:153], v[166:169], v[62:65]
	v_mfma_f32_16x16x32_bf16 v[58:61], v[158:161], v[166:169], v[58:61]
	v_mfma_f32_16x16x32_bf16 v[50:53], v[150:153], v[182:185], v[50:53]
	v_mfma_f32_16x16x32_bf16 v[42:45], v[158:161], v[182:185], v[42:45]
	v_mfma_f32_16x16x32_bf16 v[34:37], v[150:153], v[190:193], v[34:37]
	v_mfma_f32_16x16x32_bf16 v[26:29], v[158:161], v[190:193], v[26:29]
	v_mfma_f32_16x16x32_bf16 v[18:21], v[150:153], v[198:201], v[18:21]
	v_mfma_f32_16x16x32_bf16 v[10:13], v[158:161], v[198:201], v[10:13]
	s_barrier
	s_add_u32 s18, s18, 0x80080
	s_addc_u32 s19, s19, 0
	s_add_i32 s30, s30, s23
	v_lshl_add_u64 v[140:141], s[18:19], 0, v[0:1]
	s_mov_b32 m0, s30
	s_nop 0
	global_load_lds_dwordx4 v[140:141], off
	v_lshl_add_u64 v[140:141], s[18:19], 0, v[130:131]
	s_add_i32 m0, s30, 0x2000
	s_nop 0
	global_load_lds_dwordx4 v[140:141], off
	s_waitcnt vmcnt(6)
	s_barrier
	v_mfma_f32_16x16x32_bf16 v[54:57], v[202:205], v[162:165], v[54:57]
	v_mfma_f32_16x16x32_bf16 v[46:49], v[210:213], v[162:165], v[46:49]
	v_mfma_f32_16x16x32_bf16 v[38:41], v[202:205], v[170:173], v[38:41]
	v_mfma_f32_16x16x32_bf16 v[30:33], v[210:213], v[170:173], v[30:33]
	v_mfma_f32_16x16x32_bf16 v[22:25], v[202:205], v[186:189], v[22:25]
	v_mfma_f32_16x16x32_bf16 v[14:17], v[210:213], v[186:189], v[14:17]
	v_mfma_f32_16x16x32_bf16 v[6:9], v[202:205], v[194:197], v[6:9]
	v_mfma_f32_16x16x32_bf16 v[2:5], v[210:213], v[194:197], v[2:5]
	v_mfma_f32_16x16x32_bf16 v[54:57], v[206:209], v[166:169], v[54:57]
	v_mfma_f32_16x16x32_bf16 v[46:49], v[214:217], v[166:169], v[46:49]
	v_mfma_f32_16x16x32_bf16 v[38:41], v[206:209], v[182:185], v[38:41]
	v_mfma_f32_16x16x32_bf16 v[30:33], v[214:217], v[182:185], v[30:33]
	v_mfma_f32_16x16x32_bf16 v[22:25], v[206:209], v[190:193], v[22:25]
	v_mfma_f32_16x16x32_bf16 v[14:17], v[214:217], v[190:193], v[14:17]
	v_mfma_f32_16x16x32_bf16 v[6:9], v[206:209], v[198:201], v[6:9]
	v_mfma_f32_16x16x32_bf16 v[2:5], v[214:217], v[198:201], v[2:5]
	s_add_i32 s87, s87, 2
	s_add_u32 s0, s0, 0x100
	s_addc_u32 s1, s1, 0
	s_add_u32 s72, s72, 0x100
	s_addc_u32 s73, s73, 0
	s_cmp_gt_u32 s87, 29
	s_barrier
	s_cbranch_scc0 .LBB0_753
	v_lshl_add_u32 v142, s69, 8, v146
	v_ashrrev_i32_e32 v143, 31, v142
	v_lshl_or_b32 v140, s68, 8, v148
	s_movk_i32 s11, 0x2000
	v_lshlrev_b64 v[144:145], 14, v[142:143]
	v_cmp_gt_i32_e32 vcc, s11, v140
	v_ashrrev_i32_e32 v141, 31, v140
	v_lshl_add_u64 v[144:145], s[76:77], 0, v[144:145]
	s_and_saveexec_b64 s[0:1], vcc
	s_cbranch_execz .LBB0_756
	v_lshl_add_u64 v[150:151], v[140:141], 1, v[144:145]
	v_cvt_pk_bf16_f32 v126, v126, v127
	v_cvt_pk_bf16_f32 v127, v128, v129
	v_cvt_pk_bf16_f32 v128, v122, v123
	v_cvt_pk_bf16_f32 v129, v124, v125
	global_store_dwordx4 v[150:151], v[126:129], off

; #define PG8_STAGE(bufoff, gbase, voff) do { _Pragma("unroll") for (int _i = 0; _i < 2; ++_i) \
;         __builtin_amdgcn_global_load_lds((const unsigned*)((const char*)(gbase) + (voff)[_i]), (PG8_LAS unsigned*)(lds + (bufoff) + ldsw + _i * 8192), 16, 0, 0); } while (0)
; #define PG8_LDA(dst, b, h) do { _Pragma("unroll") for (int m = 0; m < 4; ++m) _Pragma("unroll") for (int k = 0; k < 2; ++k) dst[m][k] = *(const PG8_LAS bf16x8*)(lds + PG8_SA(b, h) + aoff + m * 2048 + k * 1024); } while (0)
; #define PG8_LDB(dst, b, h) do { _Pragma("unroll") for (int n = 0; n < 2; ++n) _Pragma("unroll") for (int k = 0; k < 2; ++k) dst[n][k] = *(const PG8_LAS bf16x8*)(lds + PG8_SB(b, h) + boff + n * 2048 + k * 1024); } while (0)
; #define PG8_WAIT_V(n) asm volatile("s_waitcnt vmcnt(" #n ")" ::: "memory")
; #define PG8_WAIT_L(n) asm volatile("s_waitcnt lgkmcnt(" #n ")" ::: "memory")
; #define PG8_BAR __builtin_amdgcn_s_barrier()
; #define PG8_SCHED __builtin_amdgcn_sched_barrier(0)
; template <bool FP8, class Epi, class Sched>
; __device__ __forceinline__ void gemm_phase(PG8_LAS unsigned char* lds, const Gemm g, const Sched& S, const Epi& E) {
;     ...
;             PG8_LDB(B0, 0, 0); PG8_SCHED; PG8_LDA(At, 0, 0); PG8_STAGE(PG8_SA(1, 1), a1 + hstepA, voffA);
;             PG8_WAIT_L(8); PG8_BAR; PG8_WAIT_L(0); PG8_MMA(0, 0, At, B0); PG8_BAR; PG8_SCHED;
;             PG8_LDB(B1, 0, 1); PG8_STAGE(PG8_SB(0, 0), b2, voffB);
;             PG8_BAR; PG8_WAIT_L(0); PG8_MMA(0, 1, At, B1); PG8_BAR;
;             PG8_LDA(At, 0, 1); PG8_STAGE(PG8_SA(0, 0), a2, voffA);
;             PG8_BAR; PG8_WAIT_L(0); PG8_MMA(1, 0, At, B0); PG8_BAR; PG8_SCHED;
;             PG8_STAGE(PG8_SB(0, 1), b2 + hstep, voffB);
;             PG8_WAIT_V(6); PG8_BAR; PG8_MMA(1, 1, At, B1); PG8_BAR;
;             PG8_LDB(B0, 1, 0); PG8_SCHED; PG8_LDA(At, 1, 0); PG8_STAGE(PG8_SA(0, 1), a2 + hstepA, voffA);
.LBB0_1090:
	s_add_u32 s10, s16, 0x100
	s_addc_u32 s11, s17, 0
	s_add_i32 s30, 0, 0x10000
	v_add_u32_e32 v0, s30, v183
	ds_read_b128 v[10:13], v0
	ds_read_b128 v[14:17], v0 offset:1024
	ds_read_b128 v[2:5], v0 offset:2048
	ds_read_b128 v[6:9], v0 offset:3072
	s_cmp_eq_u32 s73, 8
	s_cselect_b32 s19, s1, s11
	s_cselect_b32 s18, s0, s10
	s_cselect_b32 s13, s15, s72
	s_cselect_b32 s12, s14, s71
	v_lshl_add_u64 v[18:19], s[16:17], 0, v[162:163]
	s_add_i32 m0, s24, 0xc000
	ds_read_b128 v[186:189], v184
	ds_read_b128 v[190:193], v184 offset:1024
	ds_read_b128 v[194:197], v184 offset:2048
	ds_read_b128 v[198:201], v184 offset:3072
	ds_read_b128 v[202:205], v184 offset:4096
	ds_read_b128 v[206:209], v184 offset:5120
	ds_read_b128 v[236:239], v184 offset:6144
	ds_read_b128 v[240:243], v184 offset:7168
	global_load_lds_dwordx4 v[18:19], off
	v_lshl_add_u64 v[18:19], s[16:17], 0, v[164:165]
	s_add_i32 m0, s24, 0xe000
	s_nop 0
	global_load_lds_dwordx4 v[18:19], off
	s_waitcnt lgkmcnt(8)
	s_barrier
	s_waitcnt lgkmcnt(0)
	s_waitcnt lgkmcnt(0)
	s_nop 1
	v_mfma_scale_f32_16x16x128_f8f6f4 v[150:153], v[10:17], v[186:193], v[150:153], v174, v174 op_sel_hi:[0,0,0]
	s_nop 1
	v_mfma_scale_f32_16x16x128_f8f6f4 v[146:149], v[2:9], v[186:193], v[146:149], v174, v174 op_sel_hi:[0,0,0]
	s_nop 1
	v_mfma_scale_f32_16x16x128_f8f6f4 v[134:137], v[10:17], v[194:201], v[134:137], v174, v174 op_sel_hi:[0,0,0]
	s_nop 1
	v_mfma_scale_f32_16x16x128_f8f6f4 v[130:133], v[2:9], v[194:201], v[130:133], v174, v174 op_sel_hi:[0,0,0]
	s_nop 1
	v_mfma_scale_f32_16x16x128_f8f6f4 v[118:121], v[10:17], v[202:209], v[118:121], v174, v174 op_sel_hi:[0,0,0]
	s_nop 1
	v_mfma_scale_f32_16x16x128_f8f6f4 v[114:117], v[2:9], v[202:209], v[114:117], v174, v174 op_sel_hi:[0,0,0]
	s_nop 1
	v_mfma_scale_f32_16x16x128_f8f6f4 v[102:105], v[10:17], v[236:243], v[102:105], v174, v174 op_sel_hi:[0,0,0]
	s_nop 1
	v_mfma_scale_f32_16x16x128_f8f6f4 v[98:101], v[2:9], v[236:243], v[98:101], v174, v174 op_sel_hi:[0,0,0]
	s_barrier
	s_add_i32 s31, 0, 0x14000
	s_add_i32 s16, s30, s23
	v_add_u32_e32 v0, s31, v183
	v_lshl_add_u64 v[166:167], s[12:13], 0, v[158:159]
	s_mov_b32 m0, s16
	ds_read_b128 v[210:213], v0
	ds_read_b128 v[214:217], v0 offset:1024
	ds_read_b128 v[18:21], v0 offset:2048
	ds_read_b128 v[22:25], v0 offset:3072
	global_load_lds_dwordx4 v[166:167], off
	v_lshl_add_u64 v[168:169], s[12:13], 0, v[154:155]
	s_add_i32 m0, s16, 0x2000
	s_nop 0
	global_load_lds_dwordx4 v[168:169], off
	s_barrier
	s_waitcnt lgkmcnt(0)
	s_waitcnt lgkmcnt(0)
	s_nop 1
	v_mfma_scale_f32_16x16x128_f8f6f4 v[142:145], v[210:217], v[186:193], v[142:145], v174, v174 op_sel_hi:[0,0,0]
	s_nop 1
	v_mfma_scale_f32_16x16x128_f8f6f4 v[138:141], v[18:25], v[186:193], v[138:141], v174, v174 op_sel_hi:[0,0,0]
	s_nop 1
	v_mfma_scale_f32_16x16x128_f8f6f4 v[126:129], v[210:217], v[194:201], v[126:129], v174, v174 op_sel_hi:[0,0,0]
	s_nop 1
	v_mfma_scale_f32_16x16x128_f8f6f4 v[122:125], v[18:25], v[194:201], v[122:125], v174, v174 op_sel_hi:[0,0,0]
	s_nop 1
	v_mfma_scale_f32_16x16x128_f8f6f4 v[110:113], v[210:217], v[202:209], v[110:113], v174, v174 op_sel_hi:[0,0,0]
	s_nop 1
	v_mfma_scale_f32_16x16x128_f8f6f4 v[106:109], v[18:25], v[202:209], v[106:109], v174, v174 op_sel_hi:[0,0,0]
	s_nop 1
	v_mfma_scale_f32_16x16x128_f8f6f4 v[94:97], v[210:217], v[236:243], v[94:97], v174, v174 op_sel_hi:[0,0,0]
	s_nop 1
	v_mfma_scale_f32_16x16x128_f8f6f4 v[90:93], v[18:25], v[236:243], v[90:93], v174, v174 op_sel_hi:[0,0,0]
	s_mov_b32 m0, s24
	v_lshl_add_u64 v[170:171], s[18:19], 0, v[160:161]
	s_barrier
	ds_read_b128 v[186:189], v184 offset:16384
	ds_read_b128 v[190:193], v184 offset:17408
	ds_read_b128 v[194:197], v184 offset:18432
	ds_read_b128 v[198:201], v184 offset:19456
	ds_read_b128 v[202:205], v184 offset:20480
	ds_read_b128 v[206:209], v184 offset:21504
	ds_read_b128 v[236:239], v184 offset:22528
	ds_read_b128 v[240:243], v184 offset:23552
	global_load_lds_dwordx4 v[170:171], off
	v_lshl_add_u64 v[172:173], s[18:19], 0, v[156:157]
	s_mov_b32 m0, s25
	s_nop 0
	global_load_lds_dwordx4 v[172:173], off
	s_barrier
	s_waitcnt lgkmcnt(0)
	s_waitcnt lgkmcnt(0)
	s_nop 1
	v_mfma_scale_f32_16x16x128_f8f6f4 v[86:89], v[10:17], v[186:193], v[86:89], v174, v174 op_sel_hi:[0,0,0]
	s_nop 1
	v_mfma_scale_f32_16x16x128_f8f6f4 v[82:85], v[2:9], v[186:193], v[82:85], v174, v174 op_sel_hi:[0,0,0]
	s_nop 1
	v_mfma_scale_f32_16x16x128_f8f6f4 v[70:73], v[10:17], v[194:201], v[70:73], v174, v174 op_sel_hi:[0,0,0]
	s_nop 1
	v_mfma_scale_f32_16x16x128_f8f6f4 v[66:69], v[2:9], v[194:201], v[66:69], v174, v174 op_sel_hi:[0,0,0]
	s_nop 1
	v_mfma_scale_f32_16x16x128_f8f6f4 v[54:57], v[10:17], v[202:209], v[54:57], v174, v174 op_sel_hi:[0,0,0]
	s_nop 1
	v_mfma_scale_f32_16x16x128_f8f6f4 v[50:53], v[2:9], v[202:209], v[50:53], v174, v174 op_sel_hi:[0,0,0]
	s_nop 1
	v_mfma_scale_f32_16x16x128_f8f6f4 v[38:41], v[10:17], v[236:243], v[38:41], v174, v174 op_sel_hi:[0,0,0]
	s_nop 1
	v_mfma_scale_f32_16x16x128_f8f6f4 v[34:37], v[2:9], v[236:243], v[34:37], v174, v174 op_sel_hi:[0,0,0]
	s_barrier
	s_add_u32 s16, s12, 0x30000
	s_addc_u32 s17, s13, 0
	s_add_i32 s30, s31, s23
	v_lshl_add_u64 v[2:3], s[16:17], 0, v[158:159]
	s_mov_b32 m0, s30
	s_nop 0
	global_load_lds_dwordx4 v[2:3], off
	v_lshl_add_u64 v[2:3], s[16:17], 0, v[154:155]
	s_add_i32 m0, s30, 0x2000
	s_nop 0
	global_load_lds_dwordx4 v[2:3], off
	s_waitcnt vmcnt(6)
	s_barrier
; #define PG8_STAGE(bufoff, gbase, voff) do { _Pragma("unroll") for (int _i = 0; _i < 2; ++_i) \
;         __builtin_amdgcn_global_load_lds((const unsigned*)((const char*)(gbase) + (voff)[_i]), (PG8_LAS unsigned*)(lds + (bufoff) + ldsw + _i * 8192), 16, 0, 0); } while (0)
; #define PG8_LDA(dst, b, h) do { _Pragma("unroll") for (int m = 0; m < 4; ++m) _Pragma("unroll") for (int k = 0; k < 2; ++k) dst[m][k] = *(const PG8_LAS bf16x8*)(lds + PG8_SA(b, h) + aoff + m * 2048 + k * 1024); } while (0)
; #define PG8_LDB(dst, b, h) do { _Pragma("unroll") for (int n = 0; n < 2; ++n) _Pragma("unroll") for (int k = 0; k < 2; ++k) dst[n][k] = *(const PG8_LAS bf16x8*)(lds + PG8_SB(b, h) + boff + n * 2048 + k * 1024); } while (0)
; #define PG8_WAIT_V(n) asm volatile("s_waitcnt vmcnt(" #n ")" ::: "memory")
; #define PG8_WAIT_L(n) asm volatile("s_waitcnt lgkmcnt(" #n ")" ::: "memory")
; #define PG8_BAR __builtin_amdgcn_s_barrier()
; #define PG8_SCHED __builtin_amdgcn_sched_barrier(0)
; template <bool FP8, class Epi, class Sched>
; __device__ __forceinline__ void gemm_phase(PG8_LAS unsigned char* lds, const Gemm g, const Sched& S, const Epi& E) {
;     ...
;             PG8_WAIT_V(6); PG8_BAR; PG8_MMA(1, 1, At, B1); PG8_BAR;
;             PG8_LDB(B0, 1, 0); PG8_SCHED; PG8_LDA(At, 1, 0); PG8_STAGE(PG8_SA(0, 1), a2 + hstepA, voffA);
;             PG8_WAIT_L(8); PG8_BAR; PG8_WAIT_L(0); PG8_MMA(0, 0, At, B0); PG8_BAR; PG8_SCHED;
;             PG8_LDB(B1, 1, 1); PG8_STAGE(PG8_SB(1, 0), b3, voffB);
;             PG8_BAR; PG8_WAIT_L(0); PG8_MMA(0, 1, At, B1); PG8_BAR;
;             PG8_LDA(At, 1, 1); PG8_STAGE(PG8_SA(1, 0), a3, voffA);
;             PG8_BAR; PG8_WAIT_L(0); PG8_MMA(1, 0, At, B0); PG8_BAR; PG8_SCHED;
	s_nop 1
	v_mfma_scale_f32_16x16x128_f8f6f4 v[78:81], v[210:217], v[186:193], v[78:81], v174, v174 op_sel_hi:[0,0,0]
	s_nop 1
	v_mfma_scale_f32_16x16x128_f8f6f4 v[74:77], v[18:25], v[186:193], v[74:77], v174, v174 op_sel_hi:[0,0,0]
	s_nop 1
	v_mfma_scale_f32_16x16x128_f8f6f4 v[62:65], v[210:217], v[194:201], v[62:65], v174, v174 op_sel_hi:[0,0,0]
	s_nop 1
	v_mfma_scale_f32_16x16x128_f8f6f4 v[58:61], v[18:25], v[194:201], v[58:61], v174, v174 op_sel_hi:[0,0,0]
	s_nop 1
	v_mfma_scale_f32_16x16x128_f8f6f4 v[46:49], v[210:217], v[202:209], v[46:49], v174, v174 op_sel_hi:[0,0,0]
	s_nop 1
	v_mfma_scale_f32_16x16x128_f8f6f4 v[42:45], v[18:25], v[202:209], v[42:45], v174, v174 op_sel_hi:[0,0,0]
	s_nop 1
	v_mfma_scale_f32_16x16x128_f8f6f4 v[30:33], v[210:217], v[236:243], v[30:33], v174, v174 op_sel_hi:[0,0,0]
	s_nop 1
	v_mfma_scale_f32_16x16x128_f8f6f4 v[26:29], v[18:25], v[236:243], v[26:29], v174, v174 op_sel_hi:[0,0,0]
	s_add_i32 s30, 0, 0x18000
	v_add_u32_e32 v0, s30, v183
	s_barrier
	ds_read_b128 v[2:5], v0
	ds_read_b128 v[6:9], v0 offset:1024
	ds_read_b128 v[10:13], v0 offset:2048
	ds_read_b128 v[14:17], v0 offset:3072
	s_add_u32 s16, s18, 0x30000
	s_addc_u32 s17, s19, 0
	s_mov_b32 m0, s26
	v_lshl_add_u64 v[210:211], s[16:17], 0, v[160:161]
	ds_read_b128 v[18:21], v184 offset:32768
	ds_read_b128 v[22:25], v184 offset:33792
	ds_read_b128 v[186:189], v184 offset:34816
	ds_read_b128 v[190:193], v184 offset:35840
	ds_read_b128 v[194:197], v184 offset:36864
	ds_read_b128 v[198:201], v184 offset:37888
	ds_read_b128 v[202:205], v184 offset:38912
	ds_read_b128 v[206:209], v184 offset:39936
	global_load_lds_dwordx4 v[210:211], off
	v_lshl_add_u64 v[210:211], s[16:17], 0, v[156:157]
	s_mov_b32 m0, s27
	s_nop 0
	global_load_lds_dwordx4 v[210:211], off
	s_waitcnt lgkmcnt(8)
	s_barrier
	s_waitcnt lgkmcnt(0)
	s_waitcnt lgkmcnt(0)
	s_nop 1
	v_mfma_scale_f32_16x16x128_f8f6f4 v[150:153], v[2:9], v[18:25], v[150:153], v174, v174 op_sel_hi:[0,0,0]
	s_nop 1
	v_mfma_scale_f32_16x16x128_f8f6f4 v[146:149], v[10:17], v[18:25], v[146:149], v174, v174 op_sel_hi:[0,0,0]
	s_nop 1
	v_mfma_scale_f32_16x16x128_f8f6f4 v[134:137], v[2:9], v[186:193], v[134:137], v174, v174 op_sel_hi:[0,0,0]
	s_nop 1
	v_mfma_scale_f32_16x16x128_f8f6f4 v[130:133], v[10:17], v[186:193], v[130:133], v174, v174 op_sel_hi:[0,0,0]
	s_nop 1
	v_mfma_scale_f32_16x16x128_f8f6f4 v[118:121], v[2:9], v[194:201], v[118:121], v174, v174 op_sel_hi:[0,0,0]
	s_nop 1
	v_mfma_scale_f32_16x16x128_f8f6f4 v[114:117], v[10:17], v[194:201], v[114:117], v174, v174 op_sel_hi:[0,0,0]
	s_nop 1
	v_mfma_scale_f32_16x16x128_f8f6f4 v[102:105], v[2:9], v[202:209], v[102:105], v174, v174 op_sel_hi:[0,0,0]
	s_nop 1
	v_mfma_scale_f32_16x16x128_f8f6f4 v[98:101], v[10:17], v[202:209], v[98:101], v174, v174 op_sel_hi:[0,0,0]
	s_barrier
	s_add_i32 s16, 0, 0x1c000
	s_add_i32 s17, s30, s23
	v_add_u32_e32 v0, s16, v183
	v_lshl_add_u64 v[166:167], v[166:167], 0, s[56:57]
	s_mov_b32 m0, s17
	ds_read_b128 v[210:213], v0
	ds_read_b128 v[214:217], v0 offset:1024
	ds_read_b128 v[236:239], v0 offset:2048
	ds_read_b128 v[240:243], v0 offset:3072
	global_load_lds_dwordx4 v[166:167], off
	v_lshl_add_u64 v[166:167], v[168:169], 0, s[56:57]
	s_add_i32 m0, s17, 0x2000
	s_nop 0
	global_load_lds_dwordx4 v[166:167], off
	s_barrier
	s_waitcnt lgkmcnt(0)
	s_waitcnt lgkmcnt(0)
	s_nop 1
	v_mfma_scale_f32_16x16x128_f8f6f4 v[142:145], v[210:217], v[18:25], v[142:145], v174, v174 op_sel_hi:[0,0,0]
	s_nop 1
	v_mfma_scale_f32_16x16x128_f8f6f4 v[138:141], v[236:243], v[18:25], v[138:141], v174, v174 op_sel_hi:[0,0,0]
	s_nop 1
	v_mfma_scale_f32_16x16x128_f8f6f4 v[126:129], v[210:217], v[186:193], v[126:129], v174, v174 op_sel_hi:[0,0,0]
	s_nop 1
	v_mfma_scale_f32_16x16x128_f8f6f4 v[122:125], v[236:243], v[186:193], v[122:125], v174, v174 op_sel_hi:[0,0,0]
	s_nop 1
	v_mfma_scale_f32_16x16x128_f8f6f4 v[110:113], v[210:217], v[194:201], v[110:113], v174, v174 op_sel_hi:[0,0,0]
	s_nop 1
	v_mfma_scale_f32_16x16x128_f8f6f4 v[106:109], v[236:243], v[194:201], v[106:109], v174, v174 op_sel_hi:[0,0,0]
	s_nop 1
	v_mfma_scale_f32_16x16x128_f8f6f4 v[94:97], v[210:217], v[202:209], v[94:97], v174, v174 op_sel_hi:[0,0,0]
	s_nop 1
	v_mfma_scale_f32_16x16x128_f8f6f4 v[90:93], v[236:243], v[202:209], v[90:93], v174, v174 op_sel_hi:[0,0,0]
	s_mov_b32 m0, s54
	v_lshl_add_u64 v[166:167], v[170:171], 0, s[56:57]
	s_barrier
	ds_read_b128 v[18:21], v184 offset:49152
	ds_read_b128 v[22:25], v184 offset:50176
	ds_read_b128 v[186:189], v184 offset:51200
	ds_read_b128 v[190:193], v184 offset:52224
	ds_read_b128 v[194:197], v184 offset:53248
	ds_read_b128 v[198:201], v184 offset:54272
	ds_read_b128 v[202:205], v184 offset:55296
	ds_read_b128 v[206:209], v184 offset:56320
	global_load_lds_dwordx4 v[166:167], off
	v_lshl_add_u64 v[166:167], v[172:173], 0, s[56:57]
	s_mov_b32 m0, s66
	s_nop 0
	global_load_lds_dwordx4 v[166:167], off
	s_barrier
	s_waitcnt lgkmcnt(0)
	s_waitcnt lgkmcnt(0)
	s_nop 1
	v_mfma_scale_f32_16x16x128_f8f6f4 v[86:89], v[2:9], v[18:25], v[86:89], v174, v174 op_sel_hi:[0,0,0]
	s_nop 1
	v_mfma_scale_f32_16x16x128_f8f6f4 v[82:85], v[10:17], v[18:25], v[82:85], v174, v174 op_sel_hi:[0,0,0]
	s_nop 1
	v_mfma_scale_f32_16x16x128_f8f6f4 v[70:73], v[2:9], v[186:193], v[70:73], v174, v174 op_sel_hi:[0,0,0]
	s_nop 1
	v_mfma_scale_f32_16x16x128_f8f6f4 v[66:69], v[10:17], v[186:193], v[66:69], v174, v174 op_sel_hi:[0,0,0]
	s_nop 1
	v_mfma_scale_f32_16x16x128_f8f6f4 v[54:57], v[2:9], v[194:201], v[54:57], v174, v174 op_sel_hi:[0,0,0]
	s_nop 1
	v_mfma_scale_f32_16x16x128_f8f6f4 v[50:53], v[10:17], v[194:201], v[50:53], v174, v174 op_sel_hi:[0,0,0]
	s_nop 1
	v_mfma_scale_f32_16x16x128_f8f6f4 v[38:41], v[2:9], v[202:209], v[38:41], v174, v174 op_sel_hi:[0,0,0]
	s_nop 1
	v_mfma_scale_f32_16x16x128_f8f6f4 v[34:37], v[10:17], v[202:209], v[34:37], v174, v174 op_sel_hi:[0,0,0]
	s_barrier
; #define PG8_STAGE(bufoff, gbase, voff) do { _Pragma("unroll") for (int _i = 0; _i < 2; ++_i) \
;         __builtin_amdgcn_global_load_lds((const unsigned*)((const char*)(gbase) + (voff)[_i]), (PG8_LAS unsigned*)(lds + (bufoff) + ldsw + _i * 8192), 16, 0, 0); } while (0)
; #define PG8_WAIT_V(n) asm volatile("s_waitcnt vmcnt(" #n ")" ::: "memory")
; template <bool FP8, class Epi, class Sched>
; __device__ __forceinline__ void gemm_phase(PG8_LAS unsigned char* lds, const Gemm g, const Sched& S, const Epi& E) {
;     ...
;             PG8_BAR; PG8_WAIT_L(0); PG8_MMA(1, 0, At, B0); PG8_BAR; PG8_SCHED;
;             PG8_STAGE(PG8_SB(1, 1), b3 + hstep, voffB);
;             PG8_WAIT_V(6); PG8_BAR; PG8_MMA(1, 1, At, B1); PG8_BAR;
;         }
;   DI void operator()(const f32x4 (&acc)[2][2][4][2], const pg8::Unit& u, int wr, int wc, int fr, int fq) const {
;     const int row0 = u.pm * 256 + wr * 64 + fr, colb = u.pn * 256 + wc * 32 + 8 * fq;
; #pragma unroll
;     for (int ai = 0; ai < 2; ++ai)
; #pragma unroll
;       for (int m = 0; m < 4; ++m) {
;         const int row = row0 + ai * 128 + m * 16;
; #pragma unroll
;         for (int bj = 0; bj < 2; ++bj) {
;           const int col = colb + bj * 128;
;           f32x4 v0 = acc[ai][bj][m][0] * sc, v1 = acc[ai][bj][m][1] * sc;
;           u16* dst = nullptr;
;           if (MODE == 0) { if (col < N) dst = d0 + (size_t)row * ld0 + (col + coff2 + ((col < csplit) ? (coff1 - coff2) : 0)); }
;           else if (MODE == 1) {
;             const int oc = col + coff2 + ((col < csplit) ? (coff1 - coff2) : 0);
;             if (col < N) {
;               if (oc < 2048) dst = d0 + (size_t)row * 2048 + oc;
;               else if (oc < 2112) { rot(v0, v1, row, oc); dst = d2 + (size_t)row * 64 + (oc - 2048); }
;               else dst = d1 + (size_t)row * 4096 + (oc - 2112);
;             }
;           } else if (MODE == 3) {
;             if (col < N) { const bool lo = col < csplit; u16* bp = lo ? d0 : d1; const int ldd = lo ? 2048 : 4096, oc = lo ? col : col + (coff2 - 2112); dst = bp + (size_t)row * ldd + oc + (lo ? coff1 : 0); }
;           } else {
;             if (((col >> 6) % 3) == 2) rot(v0, v1, row, col);
;             dst = d0 + (size_t)row * 3072 + col;
;           }
;           if (dst) { u32x4 w = {pk2(v0[0], v0[1]), pk2(v0[2], v0[3]), pk2(v1[0], v1[1]), pk2(v1[2], v1[3])}; *(u32x4*)dst = w; }
	s_add_u32 s12, s12, 0x30080
	s_addc_u32 s13, s13, 0
	s_add_i32 s16, s16, s23
	v_lshl_add_u64 v[2:3], s[12:13], 0, v[158:159]
	s_mov_b32 m0, s16
	s_nop 0
	global_load_lds_dwordx4 v[2:3], off
	v_lshl_add_u64 v[2:3], s[12:13], 0, v[154:155]
	s_add_i32 m0, s16, 0x2000
	s_nop 0
	global_load_lds_dwordx4 v[2:3], off
	s_waitcnt vmcnt(6)
	s_barrier
	s_nop 1
	v_mfma_scale_f32_16x16x128_f8f6f4 v[78:81], v[210:217], v[18:25], v[78:81], v174, v174 op_sel_hi:[0,0,0]
	s_nop 1
	v_mfma_scale_f32_16x16x128_f8f6f4 v[74:77], v[236:243], v[18:25], v[74:77], v174, v174 op_sel_hi:[0,0,0]
	s_nop 1
	v_mfma_scale_f32_16x16x128_f8f6f4 v[62:65], v[210:217], v[186:193], v[62:65], v174, v174 op_sel_hi:[0,0,0]
	s_nop 1
	v_mfma_scale_f32_16x16x128_f8f6f4 v[58:61], v[236:243], v[186:193], v[58:61], v174, v174 op_sel_hi:[0,0,0]
	s_nop 1
	v_mfma_scale_f32_16x16x128_f8f6f4 v[46:49], v[210:217], v[194:201], v[46:49], v174, v174 op_sel_hi:[0,0,0]
	s_nop 1
	v_mfma_scale_f32_16x16x128_f8f6f4 v[42:45], v[236:243], v[194:201], v[42:45], v174, v174 op_sel_hi:[0,0,0]
	s_nop 1
	v_mfma_scale_f32_16x16x128_f8f6f4 v[30:33], v[210:217], v[202:209], v[30:33], v174, v174 op_sel_hi:[0,0,0]
	s_nop 1
	v_mfma_scale_f32_16x16x128_f8f6f4 v[26:29], v[236:243], v[202:209], v[26:29], v174, v174 op_sel_hi:[0,0,0]
	s_add_i32 s73, s73, 2
	s_add_u32 s71, s71, 0x100
	s_addc_u32 s72, s72, 0
	s_cmp_gt_u32 s73, 9
	s_mov_b64 s[16:17], s[10:11]
	s_barrier
	s_cbranch_scc0 .LBB0_1090
	s_lshl_b32 s10, s28, 8
	s_or_b32 s10, s10, s67
	v_or_b32_e32 v4, s10, v182
	s_ashr_i32 s10, s10, 6
	s_mul_hi_i32 s11, s10, 0x55555556
	s_lshr_b32 s12, s11, 31
	s_add_i32 s11, s11, s12
	v_lshl_add_u32 v16, s29, 8, v175
	v_lshrrev_b32_e32 v0, 1, v4
	s_mul_i32 s11, s11, 3
	s_nop 15
	s_nop 15
	v_and_b32_e32 v2, 28, v0
	v_lshlrev_b32_e32 v0, 5, v16
	s_sub_i32 s10, s10, s11
	v_and_b32_e32 v0, 0xf9e0, v0
	s_cmp_eq_u32 s10, 2
	v_pk_mul_f32 v[14:15], v[152:153], s[58:59] op_sel_hi:[1,0]
	v_pk_mul_f32 v[8:9], v[150:151], s[58:59] op_sel_hi:[1,0]
	v_pk_mul_f32 v[12:13], v[148:149], s[58:59] op_sel_hi:[1,0]
	v_pk_mul_f32 v[10:11], v[146:147], s[58:59] op_sel_hi:[1,0]
	s_cselect_b64 s[16:17], -1, 0
	s_cmp_lg_u32 s10, 2
	v_lshlrev_b32_e32 v0, 3, v0
	v_lshlrev_b32_e32 v2, 3, v2
	v_mov_b32_e32 v238, v2
	v_mov_b32_e32 v239, 0
	v_mov_b32_e32 v236, v16
	v_lshlrev_b32_e32 v236, 5, v236
	v_and_b32_e32 v236, 0xffe0, v236
	v_lshlrev_b32_e32 v236, 3, v236
	v_mov_b32_e32 v237, 0
	v_lshl_add_u64 v[236:237], s[52:53], 0, v[236:237]
	v_lshl_add_u64 v[236:237], v[236:237], 0, v[238:239]
	global_load_dwordx4 v[186:189], v[236:237], off offset:16
	global_load_dwordx4 v[190:193], v[236:237], off
	v_add_u32_e32 v236, 16, v16
	v_lshlrev_b32_e32 v236, 5, v236
	v_and_b32_e32 v236, 0xffe0, v236
	v_lshlrev_b32_e32 v236, 3, v236
	v_mov_b32_e32 v237, 0
	v_lshl_add_u64 v[236:237], s[52:53], 0, v[236:237]
	v_lshl_add_u64 v[236:237], v[236:237], 0, v[238:239]
	global_load_dwordx4 v[194:197], v[236:237], off offset:16
	global_load_dwordx4 v[198:201], v[236:237], off
	v_add_u32_e32 v236, 32, v16
	v_lshlrev_b32_e32 v236, 5, v236
	v_and_b32_e32 v236, 0xffe0, v236
	v_lshlrev_b32_e32 v236, 3, v236
	v_mov_b32_e32 v237, 0
	v_lshl_add_u64 v[236:237], s[52:53], 0, v[236:237]
	v_lshl_add_u64 v[236:237], v[236:237], 0, v[238:239]
	global_load_dwordx4 v[202:205], v[236:237], off offset:16
	global_load_dwordx4 v[206:209], v[236:237], off
	v_add_u32_e32 v236, 48, v16
	v_lshlrev_b32_e32 v236, 5, v236
	v_and_b32_e32 v236, 0xffe0, v236
	v_lshlrev_b32_e32 v236, 3, v236
	v_mov_b32_e32 v237, 0
	v_lshl_add_u64 v[236:237], s[52:53], 0, v[236:237]
	v_lshl_add_u64 v[236:237], v[236:237], 0, v[238:239]
	global_load_dwordx4 v[210:213], v[236:237], off offset:16
	global_load_dwordx4 v[214:217], v[236:237], off
	s_waitcnt vmcnt(0)
	s_cbranch_scc1 .LBB0_1093
	v_mov_b32_e32 v3, v1
	v_mov_b32_e32 v18, v186
	v_mov_b32_e32 v19, v187
	v_mov_b32_e32 v20, v188
	v_mov_b32_e32 v21, v189
	v_mov_b32_e32 v22, v190
	v_mov_b32_e32 v23, v191
	v_mov_b32_e32 v24, v192
	v_mov_b32_e32 v25, v193
	v_pk_mul_f32 v[148:149], v[10:11], v[18:19] op_sel:[1,1] op_sel_hi:[0,1]
	v_pk_mul_f32 v[146:147], v[8:9], v[22:23] op_sel:[1,1] op_sel_hi:[0,1]
	v_pk_mul_f32 v[6:7], v[8:9], v[22:23]
	v_pk_fma_f32 v[8:9], v[8:9], v[22:23], v[146:147] op_sel_hi:[1,0,1]
	s_nop 0
	v_mul_f32_e32 v8, v15, v25
	v_pk_fma_f32 v[22:23], v[14:15], v[24:25], v[8:9] op_sel_hi:[1,1,0] neg_lo:[0,0,1] neg_hi:[0,0,1]
	v_mul_f32_e32 v8, v14, v25
	v_pk_fma_f32 v[24:25], v[14:15], v[24:25], v[8:9] op_sel:[1,0,0] op_sel_hi:[0,1,0]
	v_mul_f32_e32 v8, v13, v21
	v_pk_mul_f32 v[14:15], v[10:11], v[18:19]
	v_pk_fma_f32 v[10:11], v[10:11], v[18:19], v[148:149] op_sel_hi:[1,0,1]
	v_pk_fma_f32 v[18:19], v[12:13], v[20:21], v[8:9] op_sel_hi:[1,1,0] neg_lo:[0,0,1] neg_hi:[0,0,1]
	v_mul_f32_e32 v8, v12, v21
	v_pk_fma_f32 v[20:21], v[12:13], v[20:21], v[8:9] op_sel:[1,0,0] op_sel_hi:[0,1,0]
	v_sub_f32_e32 v10, v14, v148
	v_sub_f32_e32 v8, v6, v146
	v_mov_b32_e32 v12, v18
	v_mov_b32_e32 v13, v20
	v_mov_b32_e32 v14, v22
	v_mov_b32_e32 v15, v24

; #define PG8_STAGE(bufoff, gbase, voff) do { _Pragma("unroll") for (int _i = 0; _i < 2; ++_i) \
;         __builtin_amdgcn_global_load_lds((const unsigned*)((const char*)(gbase) + (voff)[_i]), (PG8_LAS unsigned*)(lds + (bufoff) + ldsw + _i * 8192), 16, 0, 0); } while (0)
; #define PG8_LDA(dst, b, h) do { _Pragma("unroll") for (int m = 0; m < 4; ++m) _Pragma("unroll") for (int k = 0; k < 2; ++k) dst[m][k] = *(const PG8_LAS bf16x8*)(lds + PG8_SA(b, h) + aoff + m * 2048 + k * 1024); } while (0)
; #define PG8_LDB(dst, b, h) do { _Pragma("unroll") for (int n = 0; n < 2; ++n) _Pragma("unroll") for (int k = 0; k < 2; ++k) dst[n][k] = *(const PG8_LAS bf16x8*)(lds + PG8_SB(b, h) + boff + n * 2048 + k * 1024); } while (0)
; #define PG8_WAIT_V(n) asm volatile("s_waitcnt vmcnt(" #n ")" ::: "memory")
; #define PG8_WAIT_L(n) asm volatile("s_waitcnt lgkmcnt(" #n ")" ::: "memory")
; #define PG8_BAR __builtin_amdgcn_s_barrier()
; #define PG8_SCHED __builtin_amdgcn_sched_barrier(0)
; template <bool FP8, class Epi, class Sched>
; __device__ __forceinline__ void gemm_phase(PG8_LAS unsigned char* lds, const Gemm g, const Sched& S, const Epi& E) {
;     ...
;             PG8_LDB(B0, 0, 0); PG8_SCHED; PG8_LDA(At, 0, 0); PG8_STAGE(PG8_SA(1, 1), a1 + hstepA, voffA);
;             PG8_WAIT_L(8); PG8_BAR; PG8_WAIT_L(0); PG8_MMA(0, 0, At, B0); PG8_BAR; PG8_SCHED;
;             PG8_LDB(B1, 0, 1); PG8_STAGE(PG8_SB(0, 0), b2, voffB);
;             PG8_BAR; PG8_WAIT_L(0); PG8_MMA(0, 1, At, B1); PG8_BAR;
;             PG8_LDA(At, 0, 1); PG8_STAGE(PG8_SA(0, 0), a2, voffA);
;             PG8_BAR; PG8_WAIT_L(0); PG8_MMA(1, 0, At, B0); PG8_BAR; PG8_SCHED;
;             PG8_STAGE(PG8_SB(0, 1), b2 + hstep, voffB);
;             PG8_WAIT_V(6); PG8_BAR; PG8_MMA(1, 1, At, B1); PG8_BAR;
;             PG8_LDB(B0, 1, 0); PG8_SCHED; PG8_LDA(At, 1, 0); PG8_STAGE(PG8_SA(0, 1), a2 + hstepA, voffA);
.LBB0_1138:
	s_add_u32 s18, s0, 0xfff80080
	s_addc_u32 s19, s1, -1
	s_add_i32 s30, 0, 0x10000
	v_add_u32_e32 v144, s30, v147
	ds_read_b128 v[140:143], v144
	ds_read_b128 v[150:153], v144 offset:1024
	ds_read_b128 v[154:157], v144 offset:2048
	ds_read_b128 v[158:161], v144 offset:3072
	s_cmp_eq_u32 s87, 4
	s_cselect_b32 s67, s13, s19
	s_cselect_b32 s66, s70, s18
	s_cselect_b32 s19, s11, s73
	s_cselect_b32 s18, s71, s72
	v_lshl_add_u64 v[144:145], s[0:1], 0, v[136:137]
	s_add_i32 m0, s24, 0xc000
	ds_read_b128 v[162:165], v149
	ds_read_b128 v[166:169], v149 offset:1024
	ds_read_b128 v[170:173], v149 offset:2048
	ds_read_b128 v[182:185], v149 offset:3072
	ds_read_b128 v[186:189], v149 offset:4096
	ds_read_b128 v[190:193], v149 offset:5120
	ds_read_b128 v[194:197], v149 offset:6144
	ds_read_b128 v[198:201], v149 offset:7168
	global_load_lds_dwordx4 v[144:145], off
	v_lshl_add_u64 v[144:145], s[0:1], 0, v[138:139]
	s_add_i32 m0, s24, 0xe000
	s_nop 0
	global_load_lds_dwordx4 v[144:145], off
	s_waitcnt lgkmcnt(8)
	s_barrier
	s_waitcnt lgkmcnt(0)
	s_waitcnt lgkmcnt(0)
	v_mfma_f32_16x16x32_bf16 v[126:129], v[140:143], v[162:165], v[126:129]
	v_mfma_f32_16x16x32_bf16 v[122:125], v[154:157], v[162:165], v[122:125]
	v_mfma_f32_16x16x32_bf16 v[114:117], v[140:143], v[170:173], v[114:117]
	v_mfma_f32_16x16x32_bf16 v[106:109], v[154:157], v[170:173], v[106:109]
	v_mfma_f32_16x16x32_bf16 v[98:101], v[140:143], v[186:189], v[98:101]
	v_mfma_f32_16x16x32_bf16 v[90:93], v[154:157], v[186:189], v[90:93]
	v_mfma_f32_16x16x32_bf16 v[82:85], v[140:143], v[194:197], v[82:85]
	v_mfma_f32_16x16x32_bf16 v[74:77], v[154:157], v[194:197], v[74:77]
	v_mfma_f32_16x16x32_bf16 v[126:129], v[150:153], v[166:169], v[126:129]
	v_mfma_f32_16x16x32_bf16 v[122:125], v[158:161], v[166:169], v[122:125]
	v_mfma_f32_16x16x32_bf16 v[114:117], v[150:153], v[182:185], v[114:117]
	v_mfma_f32_16x16x32_bf16 v[106:109], v[158:161], v[182:185], v[106:109]
	v_mfma_f32_16x16x32_bf16 v[98:101], v[150:153], v[190:193], v[98:101]
	v_mfma_f32_16x16x32_bf16 v[90:93], v[158:161], v[190:193], v[90:93]
	v_mfma_f32_16x16x32_bf16 v[82:85], v[150:153], v[198:201], v[82:85]
	v_mfma_f32_16x16x32_bf16 v[74:77], v[158:161], v[198:201], v[74:77]
	s_barrier
	s_add_i32 s86, 0, 0x14000
	v_add_u32_e32 v144, s86, v147
	s_add_i32 s30, s30, s23
	ds_read_b128 v[202:205], v144
	ds_read_b128 v[206:209], v144 offset:1024
	ds_read_b128 v[210:213], v144 offset:2048
	ds_read_b128 v[214:217], v144 offset:3072
	v_lshl_add_u64 v[144:145], s[18:19], 0, v[134:135]
	s_mov_b32 m0, s30
	v_lshl_add_u64 v[174:175], s[18:19], 0, v[130:131]
	global_load_lds_dwordx4 v[144:145], off
	s_add_i32 m0, s30, 0x2000
	s_nop 0
	global_load_lds_dwordx4 v[174:175], off
	s_barrier
	s_waitcnt lgkmcnt(0)
	s_waitcnt lgkmcnt(0)
	v_mfma_f32_16x16x32_bf16 v[118:121], v[202:205], v[162:165], v[118:121]
	v_mfma_f32_16x16x32_bf16 v[110:113], v[210:213], v[162:165], v[110:113]
	v_mfma_f32_16x16x32_bf16 v[102:105], v[202:205], v[170:173], v[102:105]
	v_mfma_f32_16x16x32_bf16 v[94:97], v[210:213], v[170:173], v[94:97]
	v_mfma_f32_16x16x32_bf16 v[86:89], v[202:205], v[186:189], v[86:89]
	v_mfma_f32_16x16x32_bf16 v[78:81], v[210:213], v[186:189], v[78:81]
	v_mfma_f32_16x16x32_bf16 v[70:73], v[202:205], v[194:197], v[70:73]
	v_mfma_f32_16x16x32_bf16 v[66:69], v[210:213], v[194:197], v[66:69]
	v_mfma_f32_16x16x32_bf16 v[118:121], v[206:209], v[166:169], v[118:121]
	v_mfma_f32_16x16x32_bf16 v[110:113], v[214:217], v[166:169], v[110:113]
	v_mfma_f32_16x16x32_bf16 v[102:105], v[206:209], v[182:185], v[102:105]
	v_mfma_f32_16x16x32_bf16 v[94:97], v[214:217], v[182:185], v[94:97]
	v_mfma_f32_16x16x32_bf16 v[86:89], v[206:209], v[190:193], v[86:89]
	v_mfma_f32_16x16x32_bf16 v[78:81], v[214:217], v[190:193], v[78:81]
	v_mfma_f32_16x16x32_bf16 v[70:73], v[206:209], v[198:201], v[70:73]
	v_mfma_f32_16x16x32_bf16 v[66:69], v[214:217], v[198:201], v[66:69]
	s_mov_b32 m0, s24
	v_lshl_add_u64 v[236:237], s[66:67], 0, v[0:1]
	s_barrier
	ds_read_b128 v[162:165], v149 offset:16384
	ds_read_b128 v[166:169], v149 offset:17408
	ds_read_b128 v[170:173], v149 offset:18432
	ds_read_b128 v[182:185], v149 offset:19456
	ds_read_b128 v[186:189], v149 offset:20480
	ds_read_b128 v[190:193], v149 offset:21504
	ds_read_b128 v[194:197], v149 offset:22528
	ds_read_b128 v[198:201], v149 offset:23552
	global_load_lds_dwordx4 v[236:237], off
	v_lshl_add_u64 v[238:239], s[66:67], 0, v[132:133]
	s_mov_b32 m0, s25
	s_nop 0
	global_load_lds_dwordx4 v[238:239], off
	s_barrier
	s_waitcnt lgkmcnt(0)
	s_waitcnt lgkmcnt(0)
	v_mfma_f32_16x16x32_bf16 v[62:65], v[140:143], v[162:165], v[62:65]
	v_mfma_f32_16x16x32_bf16 v[58:61], v[154:157], v[162:165], v[58:61]
	v_mfma_f32_16x16x32_bf16 v[50:53], v[140:143], v[170:173], v[50:53]
	v_mfma_f32_16x16x32_bf16 v[42:45], v[154:157], v[170:173], v[42:45]
	v_mfma_f32_16x16x32_bf16 v[34:37], v[140:143], v[186:189], v[34:37]
	v_mfma_f32_16x16x32_bf16 v[26:29], v[154:157], v[186:189], v[26:29]
	v_mfma_f32_16x16x32_bf16 v[18:21], v[140:143], v[194:197], v[18:21]
	v_mfma_f32_16x16x32_bf16 v[10:13], v[154:157], v[194:197], v[10:13]
	v_mfma_f32_16x16x32_bf16 v[62:65], v[150:153], v[166:169], v[62:65]
	v_mfma_f32_16x16x32_bf16 v[58:61], v[158:161], v[166:169], v[58:61]
	v_mfma_f32_16x16x32_bf16 v[50:53], v[150:153], v[182:185], v[50:53]
	v_mfma_f32_16x16x32_bf16 v[42:45], v[158:161], v[182:185], v[42:45]
	v_mfma_f32_16x16x32_bf16 v[34:37], v[150:153], v[190:193], v[34:37]
	v_mfma_f32_16x16x32_bf16 v[26:29], v[158:161], v[190:193], v[26:29]
	v_mfma_f32_16x16x32_bf16 v[18:21], v[150:153], v[198:201], v[18:21]
	v_mfma_f32_16x16x32_bf16 v[10:13], v[158:161], v[198:201], v[10:13]
	s_barrier
; #define PG8_STAGE(bufoff, gbase, voff) do { _Pragma("unroll") for (int _i = 0; _i < 2; ++_i) \
;         __builtin_amdgcn_global_load_lds((const unsigned*)((const char*)(gbase) + (voff)[_i]), (PG8_LAS unsigned*)(lds + (bufoff) + ldsw + _i * 8192), 16, 0, 0); } while (0)
; #define PG8_LDA(dst, b, h) do { _Pragma("unroll") for (int m = 0; m < 4; ++m) _Pragma("unroll") for (int k = 0; k < 2; ++k) dst[m][k] = *(const PG8_LAS bf16x8*)(lds + PG8_SA(b, h) + aoff + m * 2048 + k * 1024); } while (0)
; #define PG8_LDB(dst, b, h) do { _Pragma("unroll") for (int n = 0; n < 2; ++n) _Pragma("unroll") for (int k = 0; k < 2; ++k) dst[n][k] = *(const PG8_LAS bf16x8*)(lds + PG8_SB(b, h) + boff + n * 2048 + k * 1024); } while (0)
; #define PG8_WAIT_V(n) asm volatile("s_waitcnt vmcnt(" #n ")" ::: "memory")
; #define PG8_WAIT_L(n) asm volatile("s_waitcnt lgkmcnt(" #n ")" ::: "memory")
; #define PG8_BAR __builtin_amdgcn_s_barrier()
; #define PG8_SCHED __builtin_amdgcn_sched_barrier(0)
; template <bool FP8, class Epi, class Sched>
; __device__ __forceinline__ void gemm_phase(PG8_LAS unsigned char* lds, const Gemm g, const Sched& S, const Epi& E) {
;     ...
;             PG8_WAIT_V(6); PG8_BAR; PG8_MMA(1, 1, At, B1); PG8_BAR;
;             PG8_LDB(B0, 1, 0); PG8_SCHED; PG8_LDA(At, 1, 0); PG8_STAGE(PG8_SA(0, 1), a2 + hstepA, voffA);
;             PG8_WAIT_L(8); PG8_BAR; PG8_WAIT_L(0); PG8_MMA(0, 0, At, B0); PG8_BAR; PG8_SCHED;
;             PG8_LDB(B1, 1, 1); PG8_STAGE(PG8_SB(1, 0), b3, voffB);
;             PG8_BAR; PG8_WAIT_L(0); PG8_MMA(0, 1, At, B1); PG8_BAR;
	s_add_u32 s30, s18, 0x20000
	s_addc_u32 s31, s19, 0
	s_add_i32 s86, s86, s23
	v_lshl_add_u64 v[140:141], s[30:31], 0, v[134:135]
	s_mov_b32 m0, s86
	s_nop 0
	global_load_lds_dwordx4 v[140:141], off
	v_lshl_add_u64 v[140:141], s[30:31], 0, v[130:131]
	s_add_i32 m0, s86, 0x2000
	s_nop 0
	global_load_lds_dwordx4 v[140:141], off
	s_waitcnt vmcnt(6)
	s_barrier
	v_mfma_f32_16x16x32_bf16 v[54:57], v[202:205], v[162:165], v[54:57]
	v_mfma_f32_16x16x32_bf16 v[46:49], v[210:213], v[162:165], v[46:49]
	v_mfma_f32_16x16x32_bf16 v[38:41], v[202:205], v[170:173], v[38:41]
	v_mfma_f32_16x16x32_bf16 v[30:33], v[210:213], v[170:173], v[30:33]
	v_mfma_f32_16x16x32_bf16 v[22:25], v[202:205], v[186:189], v[22:25]
	v_mfma_f32_16x16x32_bf16 v[14:17], v[210:213], v[186:189], v[14:17]
	v_mfma_f32_16x16x32_bf16 v[6:9], v[202:205], v[194:197], v[6:9]
	v_mfma_f32_16x16x32_bf16 v[2:5], v[210:213], v[194:197], v[2:5]
	v_mfma_f32_16x16x32_bf16 v[54:57], v[206:209], v[166:169], v[54:57]
	v_mfma_f32_16x16x32_bf16 v[46:49], v[214:217], v[166:169], v[46:49]
	v_mfma_f32_16x16x32_bf16 v[38:41], v[206:209], v[182:185], v[38:41]
	v_mfma_f32_16x16x32_bf16 v[30:33], v[214:217], v[182:185], v[30:33]
	v_mfma_f32_16x16x32_bf16 v[22:25], v[206:209], v[190:193], v[22:25]
	v_mfma_f32_16x16x32_bf16 v[14:17], v[214:217], v[190:193], v[14:17]
	v_mfma_f32_16x16x32_bf16 v[6:9], v[206:209], v[198:201], v[6:9]
	v_mfma_f32_16x16x32_bf16 v[2:5], v[214:217], v[198:201], v[2:5]
	s_add_i32 s86, 0, 0x18000
	v_add_u32_e32 v158, s86, v147
	s_barrier
	ds_read_b128 v[140:143], v158
	ds_read_b128 v[150:153], v158 offset:1024
	ds_read_b128 v[154:157], v158 offset:2048
	ds_read_b128 v[158:161], v158 offset:3072
	s_add_u32 s30, s66, 0x80000
	s_addc_u32 s31, s67, 0
	s_mov_b32 m0, s26
	v_lshl_add_u64 v[202:203], s[30:31], 0, v[0:1]
	ds_read_b128 v[162:165], v149 offset:32768
	ds_read_b128 v[166:169], v149 offset:33792
	ds_read_b128 v[170:173], v149 offset:34816
	ds_read_b128 v[182:185], v149 offset:35840
	ds_read_b128 v[186:189], v149 offset:36864
	ds_read_b128 v[190:193], v149 offset:37888
	ds_read_b128 v[194:197], v149 offset:38912
	ds_read_b128 v[198:201], v149 offset:39936
	global_load_lds_dwordx4 v[202:203], off
	v_lshl_add_u64 v[202:203], s[30:31], 0, v[132:133]
	s_mov_b32 m0, s27
	s_nop 0
	global_load_lds_dwordx4 v[202:203], off
	s_waitcnt lgkmcnt(8)
	s_barrier
	s_waitcnt lgkmcnt(0)
	s_waitcnt lgkmcnt(0)
	v_mfma_f32_16x16x32_bf16 v[126:129], v[140:143], v[162:165], v[126:129]
	v_mfma_f32_16x16x32_bf16 v[122:125], v[154:157], v[162:165], v[122:125]
	v_mfma_f32_16x16x32_bf16 v[114:117], v[140:143], v[170:173], v[114:117]
	v_mfma_f32_16x16x32_bf16 v[106:109], v[154:157], v[170:173], v[106:109]
	v_mfma_f32_16x16x32_bf16 v[98:101], v[140:143], v[186:189], v[98:101]
	v_mfma_f32_16x16x32_bf16 v[90:93], v[154:157], v[186:189], v[90:93]
	v_mfma_f32_16x16x32_bf16 v[82:85], v[140:143], v[194:197], v[82:85]
	v_mfma_f32_16x16x32_bf16 v[74:77], v[154:157], v[194:197], v[74:77]
	v_mfma_f32_16x16x32_bf16 v[126:129], v[150:153], v[166:169], v[126:129]
	v_mfma_f32_16x16x32_bf16 v[122:125], v[158:161], v[166:169], v[122:125]
	v_mfma_f32_16x16x32_bf16 v[114:117], v[150:153], v[182:185], v[114:117]
	v_mfma_f32_16x16x32_bf16 v[106:109], v[158:161], v[182:185], v[106:109]
	v_mfma_f32_16x16x32_bf16 v[98:101], v[150:153], v[190:193], v[98:101]
	v_mfma_f32_16x16x32_bf16 v[90:93], v[158:161], v[190:193], v[90:93]
	v_mfma_f32_16x16x32_bf16 v[82:85], v[150:153], v[198:201], v[82:85]
	v_mfma_f32_16x16x32_bf16 v[74:77], v[158:161], v[198:201], v[74:77]
	s_barrier
	s_add_i32 s30, 0, 0x1c000
	s_add_i32 s31, s86, s23
	v_add_u32_e32 v214, s30, v147
	v_lshl_add_u64 v[144:145], v[144:145], 0, s[56:57]
	s_mov_b32 m0, s31
	ds_read_b128 v[202:205], v214
	ds_read_b128 v[206:209], v214 offset:1024
	ds_read_b128 v[210:213], v214 offset:2048
	ds_read_b128 v[214:217], v214 offset:3072
	global_load_lds_dwordx4 v[144:145], off
	v_lshl_add_u64 v[144:145], v[174:175], 0, s[56:57]
	s_add_i32 m0, s31, 0x2000
	s_nop 0
	global_load_lds_dwordx4 v[144:145], off
	s_barrier
; #define PG8_STAGE(bufoff, gbase, voff) do { _Pragma("unroll") for (int _i = 0; _i < 2; ++_i) \
;         __builtin_amdgcn_global_load_lds((const unsigned*)((const char*)(gbase) + (voff)[_i]), (PG8_LAS unsigned*)(lds + (bufoff) + ldsw + _i * 8192), 16, 0, 0); } while (0)
; #define PG8_WAIT_V(n) asm volatile("s_waitcnt vmcnt(" #n ")" ::: "memory")
; #define PG8_WAIT_L(n) asm volatile("s_waitcnt lgkmcnt(" #n ")" ::: "memory")
; template <bool FP8, class Epi, class Sched>
; __device__ __forceinline__ void gemm_phase(PG8_LAS unsigned char* lds, const Gemm g, const Sched& S, const Epi& E) {
;     ...
;             PG8_BAR; PG8_WAIT_L(0); PG8_MMA(0, 1, At, B1); PG8_BAR;
;             PG8_LDA(At, 1, 1); PG8_STAGE(PG8_SA(1, 0), a3, voffA);
;             PG8_BAR; PG8_WAIT_L(0); PG8_MMA(1, 0, At, B0); PG8_BAR; PG8_SCHED;
;             PG8_STAGE(PG8_SB(1, 1), b3 + hstep, voffB);
;             PG8_WAIT_V(6); PG8_BAR; PG8_MMA(1, 1, At, B1); PG8_BAR;
;   DI void operator()(const f32x4 (&acc)[2][2][4][2], const pg8::Unit& u, int wr, int wc, int fr, int fq) const {
;     ...
;         const int row = row0 + ai * 128 + m * 16;
; #pragma unroll
;         for (int bj = 0; bj < 2; ++bj) {
;           const int col = colb + bj * 128;
;           f32x4 v0 = acc[ai][bj][m][0] * sc, v1 = acc[ai][bj][m][1] * sc;
;           u16* dst = nullptr;
;           if (MODE == 0) { if (col < N) dst = d0 + (size_t)row * ld0 + (col + coff2 + ((col < csplit) ? (coff1 - coff2) : 0)); }
;           else if (MODE == 1) {
;             const int oc = col + coff2 + ((col < csplit) ? (coff1 - coff2) : 0);
;             if (col < N) {
;               if (oc < 2048) dst = d0 + (size_t)row * 2048 + oc;
;               else if (oc < 2112) { rot(v0, v1, row, oc); dst = d2 + (size_t)row * 64 + (oc - 2048); }
;               else dst = d1 + (size_t)row * 4096 + (oc - 2112);
;             }
;           } else if (MODE == 3) {
;             if (col < N) { const bool lo = col < csplit; u16* bp = lo ? d0 : d1; const int ldd = lo ? 2048 : 4096, oc = lo ? col : col + (coff2 - 2112); dst = bp + (size_t)row * ldd + oc + (lo ? coff1 : 0); }
;           } else {
;             if (((col >> 6) % 3) == 2) rot(v0, v1, row, col);
;             dst = d0 + (size_t)row * 3072 + col;
;           }
;           if (dst) { u32x4 w = {pk2(v0[0], v0[1]), pk2(v0[2], v0[3]), pk2(v1[0], v1[1]), pk2(v1[2], v1[3])}; *(u32x4*)dst = w; }
	s_waitcnt lgkmcnt(0)
	s_waitcnt lgkmcnt(0)
	v_mfma_f32_16x16x32_bf16 v[118:121], v[202:205], v[162:165], v[118:121]
	v_mfma_f32_16x16x32_bf16 v[110:113], v[210:213], v[162:165], v[110:113]
	v_mfma_f32_16x16x32_bf16 v[102:105], v[202:205], v[170:173], v[102:105]
	v_mfma_f32_16x16x32_bf16 v[94:97], v[210:213], v[170:173], v[94:97]
	v_mfma_f32_16x16x32_bf16 v[86:89], v[202:205], v[186:189], v[86:89]
	v_mfma_f32_16x16x32_bf16 v[78:81], v[210:213], v[186:189], v[78:81]
	v_mfma_f32_16x16x32_bf16 v[70:73], v[202:205], v[194:197], v[70:73]
	v_mfma_f32_16x16x32_bf16 v[66:69], v[210:213], v[194:197], v[66:69]
	v_mfma_f32_16x16x32_bf16 v[118:121], v[206:209], v[166:169], v[118:121]
	v_mfma_f32_16x16x32_bf16 v[110:113], v[214:217], v[166:169], v[110:113]
	v_mfma_f32_16x16x32_bf16 v[102:105], v[206:209], v[182:185], v[102:105]
	v_mfma_f32_16x16x32_bf16 v[94:97], v[214:217], v[182:185], v[94:97]
	v_mfma_f32_16x16x32_bf16 v[86:89], v[206:209], v[190:193], v[86:89]
	v_mfma_f32_16x16x32_bf16 v[78:81], v[214:217], v[190:193], v[78:81]
	v_mfma_f32_16x16x32_bf16 v[70:73], v[206:209], v[198:201], v[70:73]
	v_mfma_f32_16x16x32_bf16 v[66:69], v[214:217], v[198:201], v[66:69]
	s_mov_b32 m0, s28
	v_lshl_add_u64 v[144:145], v[236:237], 0, s[56:57]
	s_barrier
	ds_read_b128 v[162:165], v149 offset:49152
	ds_read_b128 v[166:169], v149 offset:50176
	ds_read_b128 v[170:173], v149 offset:51200
	ds_read_b128 v[182:185], v149 offset:52224
	ds_read_b128 v[186:189], v149 offset:53248
	ds_read_b128 v[190:193], v149 offset:54272
	ds_read_b128 v[194:197], v149 offset:55296
	ds_read_b128 v[198:201], v149 offset:56320
	global_load_lds_dwordx4 v[144:145], off
	v_lshl_add_u64 v[144:145], v[238:239], 0, s[56:57]
	s_mov_b32 m0, s29
	s_nop 0
	global_load_lds_dwordx4 v[144:145], off
	s_barrier
	s_waitcnt lgkmcnt(0)
	s_waitcnt lgkmcnt(0)
	v_mfma_f32_16x16x32_bf16 v[62:65], v[140:143], v[162:165], v[62:65]
	v_mfma_f32_16x16x32_bf16 v[58:61], v[154:157], v[162:165], v[58:61]
	v_mfma_f32_16x16x32_bf16 v[50:53], v[140:143], v[170:173], v[50:53]
	v_mfma_f32_16x16x32_bf16 v[42:45], v[154:157], v[170:173], v[42:45]
	v_mfma_f32_16x16x32_bf16 v[34:37], v[140:143], v[186:189], v[34:37]
	v_mfma_f32_16x16x32_bf16 v[26:29], v[154:157], v[186:189], v[26:29]
	v_mfma_f32_16x16x32_bf16 v[18:21], v[140:143], v[194:197], v[18:21]
	v_mfma_f32_16x16x32_bf16 v[10:13], v[154:157], v[194:197], v[10:13]
	v_mfma_f32_16x16x32_bf16 v[62:65], v[150:153], v[166:169], v[62:65]
	v_mfma_f32_16x16x32_bf16 v[58:61], v[158:161], v[166:169], v[58:61]
	v_mfma_f32_16x16x32_bf16 v[50:53], v[150:153], v[182:185], v[50:53]
	v_mfma_f32_16x16x32_bf16 v[42:45], v[158:161], v[182:185], v[42:45]
	v_mfma_f32_16x16x32_bf16 v[34:37], v[150:153], v[190:193], v[34:37]
	v_mfma_f32_16x16x32_bf16 v[26:29], v[158:161], v[190:193], v[26:29]
	v_mfma_f32_16x16x32_bf16 v[18:21], v[150:153], v[198:201], v[18:21]
	v_mfma_f32_16x16x32_bf16 v[10:13], v[158:161], v[198:201], v[10:13]
	s_barrier
	s_add_u32 s18, s18, 0x20080
	s_addc_u32 s19, s19, 0
	s_add_i32 s30, s30, s23
	v_lshl_add_u64 v[140:141], s[18:19], 0, v[134:135]
	s_mov_b32 m0, s30
	s_nop 0
	global_load_lds_dwordx4 v[140:141], off
	v_lshl_add_u64 v[140:141], s[18:19], 0, v[130:131]
	s_add_i32 m0, s30, 0x2000
	s_nop 0
	global_load_lds_dwordx4 v[140:141], off
	s_waitcnt vmcnt(6)
	s_barrier
	v_mfma_f32_16x16x32_bf16 v[54:57], v[202:205], v[162:165], v[54:57]
	v_mfma_f32_16x16x32_bf16 v[46:49], v[210:213], v[162:165], v[46:49]
	v_mfma_f32_16x16x32_bf16 v[38:41], v[202:205], v[170:173], v[38:41]
	v_mfma_f32_16x16x32_bf16 v[30:33], v[210:213], v[170:173], v[30:33]
	v_mfma_f32_16x16x32_bf16 v[22:25], v[202:205], v[186:189], v[22:25]
	v_mfma_f32_16x16x32_bf16 v[14:17], v[210:213], v[186:189], v[14:17]
	v_mfma_f32_16x16x32_bf16 v[6:9], v[202:205], v[194:197], v[6:9]
	v_mfma_f32_16x16x32_bf16 v[2:5], v[210:213], v[194:197], v[2:5]
	v_mfma_f32_16x16x32_bf16 v[54:57], v[206:209], v[166:169], v[54:57]
	v_mfma_f32_16x16x32_bf16 v[46:49], v[214:217], v[166:169], v[46:49]
	v_mfma_f32_16x16x32_bf16 v[38:41], v[206:209], v[182:185], v[38:41]
	v_mfma_f32_16x16x32_bf16 v[30:33], v[214:217], v[182:185], v[30:33]
	v_mfma_f32_16x16x32_bf16 v[22:25], v[206:209], v[190:193], v[22:25]
	v_mfma_f32_16x16x32_bf16 v[14:17], v[214:217], v[190:193], v[14:17]
	v_mfma_f32_16x16x32_bf16 v[6:9], v[206:209], v[198:201], v[6:9]
	v_mfma_f32_16x16x32_bf16 v[2:5], v[214:217], v[198:201], v[2:5]
	s_add_i32 s87, s87, 2
	s_add_u32 s0, s0, 0x100
	s_addc_u32 s1, s1, 0
	s_add_u32 s72, s72, 0x100
	s_addc_u32 s73, s73, 0
	s_cmp_gt_u32 s87, 5
	s_barrier
	s_cbranch_scc0 .LBB0_1138
	v_lshl_add_u32 v142, s69, 8, v146
	v_ashrrev_i32_e32 v143, 31, v142
	v_lshl_or_b32 v140, s68, 8, v148
	s_movk_i32 s0, 0x1000
	v_lshlrev_b64 v[144:145], 13, v[142:143]
	v_cmp_gt_i32_e32 vcc, s0, v140
	v_ashrrev_i32_e32 v141, 31, v140
	v_lshl_add_u64 v[144:145], s[90:91], 0, v[144:145]
	s_and_saveexec_b64 s[0:1], vcc
	s_cbranch_execz .LBB0_1141
	v_lshl_add_u64 v[150:151], v[140:141], 1, v[144:145]
	v_cvt_pk_bf16_f32 v126, v126, v127
	v_cvt_pk_bf16_f32 v127, v128, v129
	v_cvt_pk_bf16_f32 v128, v122, v123
	v_cvt_pk_bf16_f32 v129, v124, v125
	global_store_dwordx4 v[150:151], v[126:129], off

; #define PG8_STAGE(bufoff, gbase, voff) do { _Pragma("unroll") for (int _i = 0; _i < 2; ++_i) \
;         __builtin_amdgcn_global_load_lds((const unsigned*)((const char*)(gbase) + (voff)[_i]), (PG8_LAS unsigned*)(lds + (bufoff) + ldsw + _i * 8192), 16, 0, 0); } while (0)
; #define PG8_LDA(dst, b, h) do { _Pragma("unroll") for (int m = 0; m < 4; ++m) _Pragma("unroll") for (int k = 0; k < 2; ++k) dst[m][k] = *(const PG8_LAS bf16x8*)(lds + PG8_SA(b, h) + aoff + m * 2048 + k * 1024); } while (0)
; #define PG8_LDB(dst, b, h) do { _Pragma("unroll") for (int n = 0; n < 2; ++n) _Pragma("unroll") for (int k = 0; k < 2; ++k) dst[n][k] = *(const PG8_LAS bf16x8*)(lds + PG8_SB(b, h) + boff + n * 2048 + k * 1024); } while (0)
; #define PG8_WAIT_V(n) asm volatile("s_waitcnt vmcnt(" #n ")" ::: "memory")
; #define PG8_WAIT_L(n) asm volatile("s_waitcnt lgkmcnt(" #n ")" ::: "memory")
; #define PG8_BAR __builtin_amdgcn_s_barrier()
; #define PG8_SCHED __builtin_amdgcn_sched_barrier(0)
; template <bool FP8, class Epi, class Sched>
; __device__ __forceinline__ void gemm_phase(PG8_LAS unsigned char* lds, const Gemm g, const Sched& S, const Epi& E) {
;     ...
;             PG8_LDB(B0, 0, 0); PG8_SCHED; PG8_LDA(At, 0, 0); PG8_STAGE(PG8_SA(1, 1), a1 + hstepA, voffA);
;             PG8_WAIT_L(8); PG8_BAR; PG8_WAIT_L(0); PG8_MMA(0, 0, At, B0); PG8_BAR; PG8_SCHED;
;             PG8_LDB(B1, 0, 1); PG8_STAGE(PG8_SB(0, 0), b2, voffB);
;             PG8_BAR; PG8_WAIT_L(0); PG8_MMA(0, 1, At, B1); PG8_BAR;
;             PG8_LDA(At, 0, 1); PG8_STAGE(PG8_SA(0, 0), a2, voffA);
;             PG8_BAR; PG8_WAIT_L(0); PG8_MMA(1, 0, At, B0); PG8_BAR; PG8_SCHED;
;             PG8_STAGE(PG8_SB(0, 1), b2 + hstep, voffB);
;             PG8_WAIT_V(6); PG8_BAR; PG8_MMA(1, 1, At, B1); PG8_BAR;
;             PG8_LDB(B0, 1, 0); PG8_SCHED; PG8_LDA(At, 1, 0); PG8_STAGE(PG8_SA(0, 1), a2 + hstepA, voffA);
.LBB0_1543:
	s_add_u32 s12, s16, 0x100
	s_addc_u32 s13, s17, 0
	s_add_i32 s30, 0, 0x10000
	v_add_u32_e32 v6, s30, v170
	ds_read_b128 v[10:13], v6
	ds_read_b128 v[14:17], v6 offset:1024
	ds_read_b128 v[2:5], v6 offset:2048
	ds_read_b128 v[6:9], v6 offset:3072
	s_cmp_eq_u32 s72, 20
	s_cselect_b32 s19, s1, s13
	s_cselect_b32 s18, s0, s12
	s_cselect_b32 s15, s11, s71
	s_cselect_b32 s14, s10, s70
	v_lshl_add_u64 v[18:19], s[16:17], 0, v[156:157]
	s_add_i32 m0, s24, 0xc000
	ds_read_b128 v[182:185], v172
	ds_read_b128 v[186:189], v172 offset:1024
	ds_read_b128 v[190:193], v172 offset:2048
	ds_read_b128 v[194:197], v172 offset:3072
	ds_read_b128 v[198:201], v172 offset:4096
	ds_read_b128 v[202:205], v172 offset:5120
	ds_read_b128 v[206:209], v172 offset:6144
	ds_read_b128 v[210:213], v172 offset:7168
	global_load_lds_dwordx4 v[18:19], off
	v_lshl_add_u64 v[18:19], s[16:17], 0, v[158:159]
	s_add_i32 m0, s24, 0xe000
	s_nop 0
	global_load_lds_dwordx4 v[18:19], off
	s_waitcnt lgkmcnt(8)
	s_barrier
	s_waitcnt lgkmcnt(0)
	s_waitcnt lgkmcnt(0)
	s_nop 1
	v_mfma_scale_f32_16x16x128_f8f6f4 v[150:153], v[10:17], v[182:189], v[150:153], v168, v168 op_sel_hi:[0,0,0]
	s_nop 1
	v_mfma_scale_f32_16x16x128_f8f6f4 v[146:149], v[2:9], v[182:189], v[146:149], v168, v168 op_sel_hi:[0,0,0]
	s_nop 1
	v_mfma_scale_f32_16x16x128_f8f6f4 v[142:145], v[10:17], v[190:197], v[142:145], v168, v168 op_sel_hi:[0,0,0]
	s_nop 1
	v_mfma_scale_f32_16x16x128_f8f6f4 v[138:141], v[2:9], v[190:197], v[138:141], v168, v168 op_sel_hi:[0,0,0]
	s_nop 1
	v_mfma_scale_f32_16x16x128_f8f6f4 v[118:121], v[10:17], v[198:205], v[118:121], v168, v168 op_sel_hi:[0,0,0]
	s_nop 1
	v_mfma_scale_f32_16x16x128_f8f6f4 v[114:117], v[2:9], v[198:205], v[114:117], v168, v168 op_sel_hi:[0,0,0]
	s_nop 1
	v_mfma_scale_f32_16x16x128_f8f6f4 v[110:113], v[10:17], v[206:213], v[110:113], v168, v168 op_sel_hi:[0,0,0]
	s_nop 1
	v_mfma_scale_f32_16x16x128_f8f6f4 v[106:109], v[2:9], v[206:213], v[106:109], v168, v168 op_sel_hi:[0,0,0]
	s_barrier
	s_add_i32 s31, 0, 0x14000
	s_add_i32 s16, s30, s23
	v_add_u32_e32 v22, s31, v170
	v_lshl_add_u64 v[160:161], s[14:15], 0, v[0:1]
	s_mov_b32 m0, s16
	ds_read_b128 v[236:239], v22
	ds_read_b128 v[240:243], v22 offset:1024
	ds_read_b128 v[18:21], v22 offset:2048
	ds_read_b128 v[22:25], v22 offset:3072
	global_load_lds_dwordx4 v[160:161], off
	v_lshl_add_u64 v[162:163], s[14:15], 0, v[154:155]
	s_add_i32 m0, s16, 0x2000
	s_nop 0
	global_load_lds_dwordx4 v[162:163], off
	s_barrier
	s_waitcnt lgkmcnt(0)
	s_waitcnt lgkmcnt(0)
	s_nop 1
	v_mfma_scale_f32_16x16x128_f8f6f4 v[134:137], v[236:243], v[182:189], v[134:137], v168, v168 op_sel_hi:[0,0,0]
	s_nop 1
	v_mfma_scale_f32_16x16x128_f8f6f4 v[130:133], v[18:25], v[182:189], v[130:133], v168, v168 op_sel_hi:[0,0,0]
	s_nop 1
	v_mfma_scale_f32_16x16x128_f8f6f4 v[126:129], v[236:243], v[190:197], v[126:129], v168, v168 op_sel_hi:[0,0,0]
	s_nop 1
	v_mfma_scale_f32_16x16x128_f8f6f4 v[122:125], v[18:25], v[190:197], v[122:125], v168, v168 op_sel_hi:[0,0,0]
	s_nop 1
	v_mfma_scale_f32_16x16x128_f8f6f4 v[102:105], v[236:243], v[198:205], v[102:105], v168, v168 op_sel_hi:[0,0,0]
	s_nop 1
	v_mfma_scale_f32_16x16x128_f8f6f4 v[98:101], v[18:25], v[198:205], v[98:101], v168, v168 op_sel_hi:[0,0,0]
	s_nop 1
	v_mfma_scale_f32_16x16x128_f8f6f4 v[94:97], v[236:243], v[206:213], v[94:97], v168, v168 op_sel_hi:[0,0,0]
	s_nop 1
	v_mfma_scale_f32_16x16x128_f8f6f4 v[90:93], v[18:25], v[206:213], v[90:93], v168, v168 op_sel_hi:[0,0,0]
	s_mov_b32 m0, s24
	v_lshl_add_u64 v[164:165], s[18:19], 0, v[0:1]
	s_barrier
	ds_read_b128 v[182:185], v172 offset:16384
	ds_read_b128 v[186:189], v172 offset:17408
	ds_read_b128 v[190:193], v172 offset:18432
	ds_read_b128 v[194:197], v172 offset:19456
	ds_read_b128 v[198:201], v172 offset:20480
	ds_read_b128 v[202:205], v172 offset:21504
	ds_read_b128 v[206:209], v172 offset:22528
	ds_read_b128 v[210:213], v172 offset:23552
	global_load_lds_dwordx4 v[164:165], off
	v_lshl_add_u64 v[166:167], s[18:19], 0, v[154:155]
	s_mov_b32 m0, s25
	s_nop 0
	global_load_lds_dwordx4 v[166:167], off
	s_barrier
	s_waitcnt lgkmcnt(0)
	s_waitcnt lgkmcnt(0)
	s_nop 1
	v_mfma_scale_f32_16x16x128_f8f6f4 v[86:89], v[10:17], v[182:189], v[86:89], v168, v168 op_sel_hi:[0,0,0]
	s_nop 1
	v_mfma_scale_f32_16x16x128_f8f6f4 v[82:85], v[2:9], v[182:189], v[82:85], v168, v168 op_sel_hi:[0,0,0]
	s_nop 1
	v_mfma_scale_f32_16x16x128_f8f6f4 v[78:81], v[10:17], v[190:197], v[78:81], v168, v168 op_sel_hi:[0,0,0]
	s_nop 1
	v_mfma_scale_f32_16x16x128_f8f6f4 v[74:77], v[2:9], v[190:197], v[74:77], v168, v168 op_sel_hi:[0,0,0]
	s_nop 1
	v_mfma_scale_f32_16x16x128_f8f6f4 v[54:57], v[10:17], v[198:205], v[54:57], v168, v168 op_sel_hi:[0,0,0]
	s_nop 1
	v_mfma_scale_f32_16x16x128_f8f6f4 v[50:53], v[2:9], v[198:205], v[50:53], v168, v168 op_sel_hi:[0,0,0]
	s_nop 1
	v_mfma_scale_f32_16x16x128_f8f6f4 v[46:49], v[10:17], v[206:213], v[46:49], v168, v168 op_sel_hi:[0,0,0]
	s_nop 1
	v_mfma_scale_f32_16x16x128_f8f6f4 v[42:45], v[2:9], v[206:213], v[42:45], v168, v168 op_sel_hi:[0,0,0]
	s_barrier
	s_add_u32 s16, s14, 0x60000
	s_addc_u32 s17, s15, 0
	s_add_i32 s30, s31, s23
	v_lshl_add_u64 v[2:3], s[16:17], 0, v[0:1]
	s_mov_b32 m0, s30
	s_nop 0
	global_load_lds_dwordx4 v[2:3], off
	v_lshl_add_u64 v[2:3], s[16:17], 0, v[154:155]
	s_add_i32 m0, s30, 0x2000
	s_nop 0
	global_load_lds_dwordx4 v[2:3], off
	s_waitcnt vmcnt(6)
	s_barrier
; #define PG8_STAGE(bufoff, gbase, voff) do { _Pragma("unroll") for (int _i = 0; _i < 2; ++_i) \
;         __builtin_amdgcn_global_load_lds((const unsigned*)((const char*)(gbase) + (voff)[_i]), (PG8_LAS unsigned*)(lds + (bufoff) + ldsw + _i * 8192), 16, 0, 0); } while (0)
; #define PG8_LDA(dst, b, h) do { _Pragma("unroll") for (int m = 0; m < 4; ++m) _Pragma("unroll") for (int k = 0; k < 2; ++k) dst[m][k] = *(const PG8_LAS bf16x8*)(lds + PG8_SA(b, h) + aoff + m * 2048 + k * 1024); } while (0)
; #define PG8_LDB(dst, b, h) do { _Pragma("unroll") for (int n = 0; n < 2; ++n) _Pragma("unroll") for (int k = 0; k < 2; ++k) dst[n][k] = *(const PG8_LAS bf16x8*)(lds + PG8_SB(b, h) + boff + n * 2048 + k * 1024); } while (0)
; #define PG8_WAIT_V(n) asm volatile("s_waitcnt vmcnt(" #n ")" ::: "memory")
; #define PG8_WAIT_L(n) asm volatile("s_waitcnt lgkmcnt(" #n ")" ::: "memory")
; #define PG8_BAR __builtin_amdgcn_s_barrier()
; #define PG8_SCHED __builtin_amdgcn_sched_barrier(0)
; template <bool FP8, class Epi, class Sched>
; __device__ __forceinline__ void gemm_phase(PG8_LAS unsigned char* lds, const Gemm g, const Sched& S, const Epi& E) {
;     ...
;             PG8_WAIT_V(6); PG8_BAR; PG8_MMA(1, 1, At, B1); PG8_BAR;
;             PG8_LDB(B0, 1, 0); PG8_SCHED; PG8_LDA(At, 1, 0); PG8_STAGE(PG8_SA(0, 1), a2 + hstepA, voffA);
;             PG8_WAIT_L(8); PG8_BAR; PG8_WAIT_L(0); PG8_MMA(0, 0, At, B0); PG8_BAR; PG8_SCHED;
;             PG8_LDB(B1, 1, 1); PG8_STAGE(PG8_SB(1, 0), b3, voffB);
;             PG8_BAR; PG8_WAIT_L(0); PG8_MMA(0, 1, At, B1); PG8_BAR;
;             PG8_LDA(At, 1, 1); PG8_STAGE(PG8_SA(1, 0), a3, voffA);
;             PG8_BAR; PG8_WAIT_L(0); PG8_MMA(1, 0, At, B0); PG8_BAR; PG8_SCHED;
	s_nop 1
	v_mfma_scale_f32_16x16x128_f8f6f4 v[70:73], v[236:243], v[182:189], v[70:73], v168, v168 op_sel_hi:[0,0,0]
	s_nop 1
	v_mfma_scale_f32_16x16x128_f8f6f4 v[66:69], v[18:25], v[182:189], v[66:69], v168, v168 op_sel_hi:[0,0,0]
	s_nop 1
	v_mfma_scale_f32_16x16x128_f8f6f4 v[62:65], v[236:243], v[190:197], v[62:65], v168, v168 op_sel_hi:[0,0,0]
	s_nop 1
	v_mfma_scale_f32_16x16x128_f8f6f4 v[58:61], v[18:25], v[190:197], v[58:61], v168, v168 op_sel_hi:[0,0,0]
	s_nop 1
	v_mfma_scale_f32_16x16x128_f8f6f4 v[38:41], v[236:243], v[198:205], v[38:41], v168, v168 op_sel_hi:[0,0,0]
	s_nop 1
	v_mfma_scale_f32_16x16x128_f8f6f4 v[34:37], v[18:25], v[198:205], v[34:37], v168, v168 op_sel_hi:[0,0,0]
	s_nop 1
	v_mfma_scale_f32_16x16x128_f8f6f4 v[30:33], v[236:243], v[206:213], v[30:33], v168, v168 op_sel_hi:[0,0,0]
	s_nop 1
	v_mfma_scale_f32_16x16x128_f8f6f4 v[26:29], v[18:25], v[206:213], v[26:29], v168, v168 op_sel_hi:[0,0,0]
	s_add_i32 s30, 0, 0x18000
	v_add_u32_e32 v14, s30, v170
	s_barrier
	ds_read_b128 v[2:5], v14
	ds_read_b128 v[6:9], v14 offset:1024
	ds_read_b128 v[10:13], v14 offset:2048
	ds_read_b128 v[14:17], v14 offset:3072
	s_add_u32 s16, s18, 0x60000
	s_addc_u32 s17, s19, 0
	s_mov_b32 m0, s26
	v_lshl_add_u64 v[174:175], s[16:17], 0, v[0:1]
	ds_read_b128 v[18:21], v172 offset:32768
	ds_read_b128 v[22:25], v172 offset:33792
	ds_read_b128 v[182:185], v172 offset:34816
	ds_read_b128 v[186:189], v172 offset:35840
	ds_read_b128 v[190:193], v172 offset:36864
	ds_read_b128 v[194:197], v172 offset:37888
	ds_read_b128 v[198:201], v172 offset:38912
	ds_read_b128 v[202:205], v172 offset:39936
	global_load_lds_dwordx4 v[174:175], off
	v_lshl_add_u64 v[174:175], s[16:17], 0, v[154:155]
	s_mov_b32 m0, s27
	s_nop 0
	global_load_lds_dwordx4 v[174:175], off
	s_waitcnt lgkmcnt(8)
	s_barrier
	s_waitcnt lgkmcnt(0)
	s_waitcnt lgkmcnt(0)
	s_nop 1
	v_mfma_scale_f32_16x16x128_f8f6f4 v[150:153], v[2:9], v[18:25], v[150:153], v168, v168 op_sel_hi:[0,0,0]
	s_nop 1
	v_mfma_scale_f32_16x16x128_f8f6f4 v[146:149], v[10:17], v[18:25], v[146:149], v168, v168 op_sel_hi:[0,0,0]
	s_nop 1
	v_mfma_scale_f32_16x16x128_f8f6f4 v[142:145], v[2:9], v[182:189], v[142:145], v168, v168 op_sel_hi:[0,0,0]
	s_nop 1
	v_mfma_scale_f32_16x16x128_f8f6f4 v[138:141], v[10:17], v[182:189], v[138:141], v168, v168 op_sel_hi:[0,0,0]
	s_nop 1
	v_mfma_scale_f32_16x16x128_f8f6f4 v[118:121], v[2:9], v[190:197], v[118:121], v168, v168 op_sel_hi:[0,0,0]
	s_nop 1
	v_mfma_scale_f32_16x16x128_f8f6f4 v[114:117], v[10:17], v[190:197], v[114:117], v168, v168 op_sel_hi:[0,0,0]
	s_nop 1
	v_mfma_scale_f32_16x16x128_f8f6f4 v[110:113], v[2:9], v[198:205], v[110:113], v168, v168 op_sel_hi:[0,0,0]
	s_nop 1
	v_mfma_scale_f32_16x16x128_f8f6f4 v[106:109], v[10:17], v[198:205], v[106:109], v168, v168 op_sel_hi:[0,0,0]
	s_barrier
	s_add_i32 s16, 0, 0x1c000
	s_add_i32 s17, s30, s23
	v_add_u32_e32 v173, s16, v170
	v_lshl_add_u64 v[160:161], v[160:161], 0, s[56:57]
	s_mov_b32 m0, s17
	ds_read_b128 v[206:209], v173
	ds_read_b128 v[210:213], v173 offset:1024
	ds_read_b128 v[236:239], v173 offset:2048
	ds_read_b128 v[240:243], v173 offset:3072
	global_load_lds_dwordx4 v[160:161], off
	v_lshl_add_u64 v[160:161], v[162:163], 0, s[56:57]
	s_add_i32 m0, s17, 0x2000
	s_nop 0
	global_load_lds_dwordx4 v[160:161], off
	s_barrier
	s_waitcnt lgkmcnt(0)
	s_waitcnt lgkmcnt(0)
	s_nop 1
	v_mfma_scale_f32_16x16x128_f8f6f4 v[134:137], v[206:213], v[18:25], v[134:137], v168, v168 op_sel_hi:[0,0,0]
	s_nop 1
	v_mfma_scale_f32_16x16x128_f8f6f4 v[130:133], v[236:243], v[18:25], v[130:133], v168, v168 op_sel_hi:[0,0,0]
	s_nop 1
	v_mfma_scale_f32_16x16x128_f8f6f4 v[126:129], v[206:213], v[182:189], v[126:129], v168, v168 op_sel_hi:[0,0,0]
	s_nop 1
	v_mfma_scale_f32_16x16x128_f8f6f4 v[122:125], v[236:243], v[182:189], v[122:125], v168, v168 op_sel_hi:[0,0,0]
	s_nop 1
	v_mfma_scale_f32_16x16x128_f8f6f4 v[102:105], v[206:213], v[190:197], v[102:105], v168, v168 op_sel_hi:[0,0,0]
	s_nop 1
	v_mfma_scale_f32_16x16x128_f8f6f4 v[98:101], v[236:243], v[190:197], v[98:101], v168, v168 op_sel_hi:[0,0,0]
	s_nop 1
	v_mfma_scale_f32_16x16x128_f8f6f4 v[94:97], v[206:213], v[198:205], v[94:97], v168, v168 op_sel_hi:[0,0,0]
	s_nop 1
	v_mfma_scale_f32_16x16x128_f8f6f4 v[90:93], v[236:243], v[198:205], v[90:93], v168, v168 op_sel_hi:[0,0,0]
	s_mov_b32 m0, s54
	v_lshl_add_u64 v[160:161], v[164:165], 0, s[56:57]
	s_barrier
	ds_read_b128 v[18:21], v172 offset:49152
	ds_read_b128 v[22:25], v172 offset:50176
	ds_read_b128 v[182:185], v172 offset:51200
	ds_read_b128 v[186:189], v172 offset:52224
	ds_read_b128 v[190:193], v172 offset:53248
	ds_read_b128 v[194:197], v172 offset:54272
	ds_read_b128 v[198:201], v172 offset:55296
	ds_read_b128 v[202:205], v172 offset:56320
	global_load_lds_dwordx4 v[160:161], off
	v_lshl_add_u64 v[160:161], v[166:167], 0, s[56:57]
	s_mov_b32 m0, s66
	s_nop 0
	global_load_lds_dwordx4 v[160:161], off
	s_barrier
	s_waitcnt lgkmcnt(0)
	s_waitcnt lgkmcnt(0)
	s_nop 1
	v_mfma_scale_f32_16x16x128_f8f6f4 v[86:89], v[2:9], v[18:25], v[86:89], v168, v168 op_sel_hi:[0,0,0]
	s_nop 1
	v_mfma_scale_f32_16x16x128_f8f6f4 v[82:85], v[10:17], v[18:25], v[82:85], v168, v168 op_sel_hi:[0,0,0]
	s_nop 1
	v_mfma_scale_f32_16x16x128_f8f6f4 v[78:81], v[2:9], v[182:189], v[78:81], v168, v168 op_sel_hi:[0,0,0]
	s_nop 1
	v_mfma_scale_f32_16x16x128_f8f6f4 v[74:77], v[10:17], v[182:189], v[74:77], v168, v168 op_sel_hi:[0,0,0]
	s_nop 1
	v_mfma_scale_f32_16x16x128_f8f6f4 v[54:57], v[2:9], v[190:197], v[54:57], v168, v168 op_sel_hi:[0,0,0]
	s_nop 1
	v_mfma_scale_f32_16x16x128_f8f6f4 v[50:53], v[10:17], v[190:197], v[50:53], v168, v168 op_sel_hi:[0,0,0]
	s_nop 1
	v_mfma_scale_f32_16x16x128_f8f6f4 v[46:49], v[2:9], v[198:205], v[46:49], v168, v168 op_sel_hi:[0,0,0]
	s_nop 1
	v_mfma_scale_f32_16x16x128_f8f6f4 v[42:45], v[10:17], v[198:205], v[42:45], v168, v168 op_sel_hi:[0,0,0]
	s_barrier
; #define PG8_STAGE(bufoff, gbase, voff) do { _Pragma("unroll") for (int _i = 0; _i < 2; ++_i) \
;         __builtin_amdgcn_global_load_lds((const unsigned*)((const char*)(gbase) + (voff)[_i]), (PG8_LAS unsigned*)(lds + (bufoff) + ldsw + _i * 8192), 16, 0, 0); } while (0)
; #define PG8_WAIT_V(n) asm volatile("s_waitcnt vmcnt(" #n ")" ::: "memory")
; #define PG8_WAIT_L(n) asm volatile("s_waitcnt lgkmcnt(" #n ")" ::: "memory")
; #define PG8_BAR __builtin_amdgcn_s_barrier()
; #define PG8_SCHED __builtin_amdgcn_sched_barrier(0)
; template <bool FP8, class Epi, class Sched>
; __device__ __forceinline__ void gemm_phase(PG8_LAS unsigned char* lds, const Gemm g, const Sched& S, const Epi& E) {
;     ...
;             PG8_BAR; PG8_WAIT_L(0); PG8_MMA(1, 0, At, B0); PG8_BAR; PG8_SCHED;
;             PG8_STAGE(PG8_SB(1, 1), b3 + hstep, voffB);
;             PG8_WAIT_V(6); PG8_BAR; PG8_MMA(1, 1, At, B1); PG8_BAR;
;   DI void operator()(const f32x4 (&acc)[2][2][4][2], const pg8::Unit& u, int wr, int wc, int fr, int fq) const {
;     const int row0 = u.pm * 256 + wr * 64 + fr, col0 = u.pn * 256 + wc * 32 + 4 * fq;
; #pragma unroll
;     for (int ai = 0; ai < 2; ++ai)
; #pragma unroll
;       for (int mp = 0; mp < 2; ++mp) {
;         f32x4 xv[2][2][2];
; #pragma unroll
;         for (int mm = 0; mm < 2; ++mm)
; #pragma unroll
;           for (int bj = 0; bj < 2; ++bj)
; #pragma unroll
;             for (int n = 0; n < 2; ++n)
;               xv[mm][bj][n] = *(const f32x4*)(xin + (size_t)(row0 + ai * 128 + (mp * 2 + mm) * 16) * 2048 + col0 + bj * 128 + n * 16);
; #pragma unroll
;         for (int mm = 0; mm < 2; ++mm)
; #pragma unroll
;           for (int bj = 0; bj < 2; ++bj)
; #pragma unroll
;             for (int n = 0; n < 2; ++n)
;               *(f32x4*)(xout + (size_t)(row0 + ai * 128 + (mp * 2 + mm) * 16) * 2048 + col0 + bj * 128 + n * 16) = xv[mm][bj][n] + acc[ai][bj][mp * 2 + mm][n] * sc;
;         asm volatile("" ::: "memory");
	s_add_u32 s14, s14, 0x60080
	s_addc_u32 s15, s15, 0
	s_add_i32 s16, s16, s23
	v_lshl_add_u64 v[2:3], s[14:15], 0, v[0:1]
	s_mov_b32 m0, s16
	s_nop 0
	global_load_lds_dwordx4 v[2:3], off
	v_lshl_add_u64 v[2:3], s[14:15], 0, v[154:155]
	s_add_i32 m0, s16, 0x2000
	s_nop 0
	global_load_lds_dwordx4 v[2:3], off
	s_waitcnt vmcnt(6)
	s_barrier
	s_nop 1
	v_mfma_scale_f32_16x16x128_f8f6f4 v[70:73], v[206:213], v[18:25], v[70:73], v168, v168 op_sel_hi:[0,0,0]
	s_nop 1
	v_mfma_scale_f32_16x16x128_f8f6f4 v[66:69], v[236:243], v[18:25], v[66:69], v168, v168 op_sel_hi:[0,0,0]
	s_nop 1
	v_mfma_scale_f32_16x16x128_f8f6f4 v[62:65], v[206:213], v[182:189], v[62:65], v168, v168 op_sel_hi:[0,0,0]
	s_nop 1
	v_mfma_scale_f32_16x16x128_f8f6f4 v[58:61], v[236:243], v[182:189], v[58:61], v168, v168 op_sel_hi:[0,0,0]
	s_nop 1
	v_mfma_scale_f32_16x16x128_f8f6f4 v[38:41], v[206:213], v[190:197], v[38:41], v168, v168 op_sel_hi:[0,0,0]
	s_nop 1
	v_mfma_scale_f32_16x16x128_f8f6f4 v[34:37], v[236:243], v[190:197], v[34:37], v168, v168 op_sel_hi:[0,0,0]
	s_nop 1
	v_mfma_scale_f32_16x16x128_f8f6f4 v[30:33], v[206:213], v[198:205], v[30:33], v168, v168 op_sel_hi:[0,0,0]
	s_nop 1
	v_mfma_scale_f32_16x16x128_f8f6f4 v[26:29], v[236:243], v[198:205], v[26:29], v168, v168 op_sel_hi:[0,0,0]
	s_add_i32 s72, s72, 2
	s_add_u32 s70, s70, 0x100
	s_addc_u32 s71, s71, 0
	s_cmp_gt_u32 s72, 21
	s_mov_b64 s[16:17], s[12:13]
	s_barrier
	s_cbranch_scc0 .LBB0_1543
	v_lshl_or_b32 v2, s28, 8, v171
	v_lshl_add_u32 v8, s29, 8, v169
	v_ashrrev_i32_e32 v3, 31, v2
	v_readlane_b32 s12, v254, 47
	v_lshlrev_b64 v[2:3], 2, v[2:3]
	v_readlane_b32 s13, v254, 48
	v_ashrrev_i32_e32 v9, 31, v8
	v_lshlrev_b64 v[6:7], 13, v[8:9]
	v_lshl_add_u64 v[4:5], s[12:13], 0, v[2:3]
	s_nop 15
	s_nop 15
	v_lshl_add_u64 v[22:23], v[4:5], 0, v[6:7]
	global_load_dwordx4 v[10:13], v[22:23], off
	global_load_dwordx4 v[14:17], v[22:23], off offset:64
	global_load_dwordx4 v[18:21], v[22:23], off offset:512
	s_nop 0
	global_load_dwordx4 v[22:25], v[22:23], off offset:576
	v_or_b32_e32 v160, 16, v8
	v_ashrrev_i32_e32 v161, 31, v160
	v_lshlrev_b64 v[174:175], 13, v[160:161]
	v_lshl_add_u64 v[186:187], v[4:5], 0, v[174:175]
	global_load_dwordx4 v[160:163], v[186:187], off
	global_load_dwordx4 v[164:167], v[186:187], off offset:64
	global_load_dwordx4 v[182:185], v[186:187], off offset:512
	s_nop 0
	global_load_dwordx4 v[186:189], v[186:187], off offset:576
	s_mov_b64 s[12:13], 0x120000
	s_and_b64 vcc, exec, s[8:9]
	s_mov_b32 s28, s68
	s_mov_b32 s29, s69
	s_mov_b64 s[16:17], s[0:1]
	s_waitcnt vmcnt(0)
	v_pk_fma_f32 v[10:11], v[150:151], s[88:89], v[10:11] op_sel_hi:[1,0,1]
	v_lshl_add_u64 v[150:151], s[80:81], 0, v[6:7]
	v_pk_fma_f32 v[12:13], v[152:153], s[88:89], v[12:13] op_sel_hi:[1,0,1]
	v_lshl_add_u64 v[150:151], v[150:151], 0, v[2:3]
	global_store_dwordx4 v[150:151], v[10:13], off
	s_nop 1
	v_pk_fma_f32 v[12:13], v[148:149], s[88:89], v[16:17] op_sel_hi:[1,0,1]
	v_pk_fma_f32 v[10:11], v[146:147], s[88:89], v[14:15] op_sel_hi:[1,0,1]
	global_store_dwordx4 v[150:151], v[10:13], off offset:64
	v_lshl_add_u64 v[14:15], s[80:81], 0, v[174:175]
	v_lshl_add_u64 v[14:15], v[14:15], 0, v[2:3]
	v_pk_fma_f32 v[12:13], v[136:137], s[88:89], v[20:21] op_sel_hi:[1,0,1]
	v_pk_fma_f32 v[10:11], v[134:135], s[88:89], v[18:19] op_sel_hi:[1,0,1]
	global_store_dwordx4 v[150:151], v[10:13], off offset:512
	s_nop 1
	v_pk_fma_f32 v[12:13], v[132:133], s[88:89], v[24:25] op_sel_hi:[1,0,1]
	v_pk_fma_f32 v[10:11], v[130:131], s[88:89], v[22:23] op_sel_hi:[1,0,1]
	global_store_dwordx4 v[150:151], v[10:13], off offset:576
	s_nop 1
	v_pk_fma_f32 v[12:13], v[144:145], s[88:89], v[162:163] op_sel_hi:[1,0,1]
	v_pk_fma_f32 v[10:11], v[142:143], s[88:89], v[160:161] op_sel_hi:[1,0,1]
	global_store_dwordx4 v[14:15], v[10:13], off
	s_nop 1
	v_pk_fma_f32 v[12:13], v[140:141], s[88:89], v[166:167] op_sel_hi:[1,0,1]
	v_pk_fma_f32 v[10:11], v[138:139], s[88:89], v[164:165] op_sel_hi:[1,0,1]
	global_store_dwordx4 v[14:15], v[10:13], off offset:64
	s_nop 1
	v_pk_fma_f32 v[12:13], v[128:129], s[88:89], v[184:185] op_sel_hi:[1,0,1]
	v_pk_fma_f32 v[10:11], v[126:127], s[88:89], v[182:183] op_sel_hi:[1,0,1]
	global_store_dwordx4 v[14:15], v[10:13], off offset:512
	s_nop 1
	v_pk_fma_f32 v[12:13], v[124:125], s[88:89], v[188:189] op_sel_hi:[1,0,1]
	v_pk_fma_f32 v[10:11], v[122:123], s[88:89], v[186:187] op_sel_hi:[1,0,1]
	global_store_dwordx4 v[14:15], v[10:13], off offset:576
	s_nop 1
	v_or_b32_e32 v10, 32, v8
	v_ashrrev_i32_e32 v11, 31, v10
	v_lshlrev_b64 v[138:139], 13, v[10:11]
	v_lshl_add_u64 v[22:23], v[4:5], 0, v[138:139]
	global_load_dwordx4 v[10:13], v[22:23], off
	global_load_dwordx4 v[14:17], v[22:23], off offset:64
	global_load_dwordx4 v[18:21], v[22:23], off offset:512
	s_nop 0
	global_load_dwordx4 v[22:25], v[22:23], off offset:576
	v_or_b32_e32 v8, 48, v8
	v_ashrrev_i32_e32 v9, 31, v8
	v_lshlrev_b64 v[140:141], 13, v[8:9]
	v_lshl_add_u64 v[8:9], v[4:5], 0, v[140:141]
	global_load_dwordx4 v[122:125], v[8:9], off
	global_load_dwordx4 v[126:129], v[8:9], off offset:64
	global_load_dwordx4 v[130:133], v[8:9], off offset:512
	global_load_dwordx4 v[134:137], v[8:9], off offset:576
	v_lshl_add_u64 v[8:9], s[80:81], 0, v[138:139]
	s_waitcnt vmcnt(0)
; #define PG8_WAIT_V(n) asm volatile("s_waitcnt vmcnt(" #n ")" ::: "memory")
; #define PG8_BAR __builtin_amdgcn_s_barrier()
; template <bool FP8, class Epi, class Sched>
; __device__ __forceinline__ void gemm_phase(PG8_LAS unsigned char* lds, const Gemm g, const Sched& S, const Epi& E) {
;     ...
;         if constexpr (!Epi::AFTER_DRAIN) { E(acc, cur, wr, wc, fr, fq); S.done(cur); }
;         if (!has_next) break;
; #pragma unroll
;         for (int a = 0; a < 2; ++a)
; #pragma unroll
;             for (int b = 0; b < 2; ++b)
; #pragma unroll
;                 for (int m = 0; m < 4; ++m)
; #pragma unroll
;                     for (int n = 0; n < 2; ++n) acc[a][b][m][n] = (f32x4){0.f, 0.f, 0.f, 0.f};
;         cur = nxt; cA = nA; cB = nB; ++ui;
;     }
;     PG8_WAIT_V(0);
;     if (wr == 0) PG8_BAR;
;     PG8_BAR;
;   DI void operator()(const f32x4 (&acc)[2][2][4][2], const pg8::Unit& u, int wr, int wc, int fr, int fq) const {
;     const int row0 = u.pm * 256 + wr * 64 + fr, col0 = u.pn * 256 + wc * 32 + 4 * fq;
; #pragma unroll
;     for (int ai = 0; ai < 2; ++ai)
; #pragma unroll
;       for (int mp = 0; mp < 2; ++mp) {
;         f32x4 xv[2][2][2];
; #pragma unroll
;         for (int mm = 0; mm < 2; ++mm)
; #pragma unroll
;           for (int bj = 0; bj < 2; ++bj)
; #pragma unroll
;             for (int n = 0; n < 2; ++n)
;               xv[mm][bj][n] = *(const f32x4*)(xin + (size_t)(row0 + ai * 128 + (mp * 2 + mm) * 16) * 2048 + col0 + bj * 128 + n * 16);
; #pragma unroll
;         for (int mm = 0; mm < 2; ++mm)
; #pragma unroll
;           for (int bj = 0; bj < 2; ++bj)
; #pragma unroll
;             for (int n = 0; n < 2; ++n)
;               *(f32x4*)(xout + (size_t)(row0 + ai * 128 + (mp * 2 + mm) * 16) * 2048 + col0 + bj * 128 + n * 16) = xv[mm][bj][n] + acc[ai][bj][mp * 2 + mm][n] * sc;
;         asm volatile("" ::: "memory");
;       }
;   }
	v_pk_fma_f32 v[12:13], v[120:121], s[88:89], v[12:13] op_sel_hi:[1,0,1]
	v_pk_fma_f32 v[10:11], v[118:119], s[88:89], v[10:11] op_sel_hi:[1,0,1]
	v_lshl_add_u64 v[118:119], v[8:9], 0, v[2:3]
	global_store_dwordx4 v[118:119], v[10:13], off
	v_pk_fma_f32 v[8:9], v[114:115], s[88:89], v[14:15] op_sel_hi:[1,0,1]
	s_nop 0
	v_pk_fma_f32 v[10:11], v[116:117], s[88:89], v[16:17] op_sel_hi:[1,0,1]
	global_store_dwordx4 v[118:119], v[8:11], off offset:64
	v_lshl_add_u64 v[12:13], s[80:81], 0, v[140:141]
	v_lshl_add_u64 v[12:13], v[12:13], 0, v[2:3]
	v_pk_fma_f32 v[10:11], v[104:105], s[88:89], v[20:21] op_sel_hi:[1,0,1]
	v_pk_fma_f32 v[8:9], v[102:103], s[88:89], v[18:19] op_sel_hi:[1,0,1]
	global_store_dwordx4 v[118:119], v[8:11], off offset:512
	s_nop 1
	v_pk_fma_f32 v[10:11], v[100:101], s[88:89], v[24:25] op_sel_hi:[1,0,1]
	v_pk_fma_f32 v[8:9], v[98:99], s[88:89], v[22:23] op_sel_hi:[1,0,1]
	global_store_dwordx4 v[118:119], v[8:11], off offset:576
	v_lshl_add_u64 v[24:25], v[6:7], 0, s[60:61]
	v_lshl_add_u64 v[20:21], v[4:5], 0, v[24:25]
	v_pk_fma_f32 v[10:11], v[112:113], s[88:89], v[124:125] op_sel_hi:[1,0,1]
	v_pk_fma_f32 v[8:9], v[110:111], s[88:89], v[122:123] op_sel_hi:[1,0,1]
	global_store_dwordx4 v[12:13], v[8:11], off
	v_lshl_add_u64 v[24:25], s[80:81], 0, v[24:25]
	v_lshl_add_u64 v[24:25], v[24:25], 0, v[2:3]
	v_pk_fma_f32 v[10:11], v[108:109], s[88:89], v[128:129] op_sel_hi:[1,0,1]
	v_pk_fma_f32 v[8:9], v[106:107], s[88:89], v[126:127] op_sel_hi:[1,0,1]
	global_store_dwordx4 v[12:13], v[8:11], off offset:64
	v_lshl_add_u64 v[106:107], v[6:7], 0, s[12:13]
	v_lshl_add_u64 v[102:103], v[4:5], 0, v[106:107]
	v_pk_fma_f32 v[10:11], v[96:97], s[88:89], v[132:133] op_sel_hi:[1,0,1]
	v_pk_fma_f32 v[8:9], v[94:95], s[88:89], v[130:131] op_sel_hi:[1,0,1]
	global_store_dwordx4 v[12:13], v[8:11], off offset:512
	s_mov_b64 s[12:13], 0x140000
	s_nop 0
	v_pk_fma_f32 v[10:11], v[92:93], s[88:89], v[136:137] op_sel_hi:[1,0,1]
	v_pk_fma_f32 v[8:9], v[90:91], s[88:89], v[134:135] op_sel_hi:[1,0,1]
	global_store_dwordx4 v[12:13], v[8:11], off offset:576
	global_load_dwordx4 v[8:11], v[20:21], off
	global_load_dwordx4 v[12:15], v[20:21], off offset:64
	global_load_dwordx4 v[16:19], v[20:21], off offset:512
	s_nop 0
	global_load_dwordx4 v[20:23], v[20:21], off offset:576
	s_nop 0
	global_load_dwordx4 v[90:93], v[102:103], off
	global_load_dwordx4 v[94:97], v[102:103], off offset:64
	global_load_dwordx4 v[98:101], v[102:103], off offset:512
	s_nop 0
	global_load_dwordx4 v[102:105], v[102:103], off offset:576
	s_waitcnt vmcnt(0)
	v_pk_fma_f32 v[10:11], v[88:89], s[88:89], v[10:11] op_sel_hi:[1,0,1]
	v_pk_fma_f32 v[8:9], v[86:87], s[88:89], v[8:9] op_sel_hi:[1,0,1]
	global_store_dwordx4 v[24:25], v[8:11], off
	s_nop 1
	v_pk_fma_f32 v[10:11], v[84:85], s[88:89], v[14:15] op_sel_hi:[1,0,1]
	v_pk_fma_f32 v[8:9], v[82:83], s[88:89], v[12:13] op_sel_hi:[1,0,1]
	global_store_dwordx4 v[24:25], v[8:11], off offset:64
	v_lshl_add_u64 v[12:13], s[80:81], 0, v[106:107]
	v_lshl_add_u64 v[12:13], v[12:13], 0, v[2:3]
	v_pk_fma_f32 v[10:11], v[72:73], s[88:89], v[18:19] op_sel_hi:[1,0,1]
	v_pk_fma_f32 v[8:9], v[70:71], s[88:89], v[16:17] op_sel_hi:[1,0,1]
	global_store_dwordx4 v[24:25], v[8:11], off offset:512
	s_nop 1
	v_pk_fma_f32 v[10:11], v[68:69], s[88:89], v[22:23] op_sel_hi:[1,0,1]
	v_pk_fma_f32 v[8:9], v[66:67], s[88:89], v[20:21] op_sel_hi:[1,0,1]
	global_store_dwordx4 v[24:25], v[8:11], off offset:576
	v_lshl_add_u64 v[24:25], v[6:7], 0, s[12:13]
	v_lshl_add_u64 v[20:21], v[4:5], 0, v[24:25]
	v_pk_fma_f32 v[10:11], v[80:81], s[88:89], v[92:93] op_sel_hi:[1,0,1]
	v_pk_fma_f32 v[8:9], v[78:79], s[88:89], v[90:91] op_sel_hi:[1,0,1]
	global_store_dwordx4 v[12:13], v[8:11], off
	s_mov_b64 s[12:13], 0x160000
	v_lshl_add_u64 v[70:71], v[6:7], 0, s[12:13]
	v_pk_fma_f32 v[10:11], v[76:77], s[88:89], v[96:97] op_sel_hi:[1,0,1]
	v_pk_fma_f32 v[8:9], v[74:75], s[88:89], v[94:95] op_sel_hi:[1,0,1]
	global_store_dwordx4 v[12:13], v[8:11], off offset:64
	v_lshl_add_u64 v[66:67], v[4:5], 0, v[70:71]
	v_lshl_add_u64 v[24:25], s[80:81], 0, v[24:25]
	v_pk_fma_f32 v[10:11], v[64:65], s[88:89], v[100:101] op_sel_hi:[1,0,1]
	v_pk_fma_f32 v[8:9], v[62:63], s[88:89], v[98:99] op_sel_hi:[1,0,1]
	global_store_dwordx4 v[12:13], v[8:11], off offset:512
	v_lshl_add_u64 v[24:25], v[24:25], 0, v[2:3]
	s_mov_b64 s[12:13], s[10:11]
	v_pk_fma_f32 v[10:11], v[60:61], s[88:89], v[104:105] op_sel_hi:[1,0,1]
	v_pk_fma_f32 v[8:9], v[58:59], s[88:89], v[102:103] op_sel_hi:[1,0,1]
	global_store_dwordx4 v[12:13], v[8:11], off offset:576
	global_load_dwordx4 v[8:11], v[20:21], off
	global_load_dwordx4 v[12:15], v[20:21], off offset:64
	global_load_dwordx4 v[16:19], v[20:21], off offset:512
	s_nop 0
	global_load_dwordx4 v[20:23], v[20:21], off offset:576
	s_nop 0
	global_load_dwordx4 v[4:7], v[66:67], off
	global_load_dwordx4 v[58:61], v[66:67], off offset:64
	global_load_dwordx4 v[62:65], v[66:67], off offset:512
	s_nop 0
	global_load_dwordx4 v[66:69], v[66:67], off offset:576
	s_waitcnt vmcnt(0)
	v_pk_fma_f32 v[10:11], v[56:57], s[88:89], v[10:11] op_sel_hi:[1,0,1]
	v_pk_fma_f32 v[8:9], v[54:55], s[88:89], v[8:9] op_sel_hi:[1,0,1]
	global_store_dwordx4 v[24:25], v[8:11], off
	v_pk_fma_f32 v[6:7], v[48:49], s[88:89], v[6:7] op_sel_hi:[1,0,1]
	v_pk_fma_f32 v[4:5], v[46:47], s[88:89], v[4:5] op_sel_hi:[1,0,1]
	v_pk_fma_f32 v[10:11], v[52:53], s[88:89], v[14:15] op_sel_hi:[1,0,1]
	v_pk_fma_f32 v[8:9], v[50:51], s[88:89], v[12:13] op_sel_hi:[1,0,1]
	global_store_dwordx4 v[24:25], v[8:11], off offset:64
	s_nop 1
	v_pk_fma_f32 v[10:11], v[40:41], s[88:89], v[18:19] op_sel_hi:[1,0,1]
	v_pk_fma_f32 v[8:9], v[38:39], s[88:89], v[16:17] op_sel_hi:[1,0,1]
	global_store_dwordx4 v[24:25], v[8:11], off offset:512
	s_nop 1
	v_pk_fma_f32 v[10:11], v[36:37], s[88:89], v[22:23] op_sel_hi:[1,0,1]
	v_pk_fma_f32 v[8:9], v[34:35], s[88:89], v[20:21] op_sel_hi:[1,0,1]
	global_store_dwordx4 v[24:25], v[8:11], off offset:576
	s_nop 1
	v_lshl_add_u64 v[8:9], s[80:81], 0, v[70:71]
	v_lshl_add_u64 v[8:9], v[8:9], 0, v[2:3]
	global_store_dwordx4 v[8:9], v[4:7], off
	v_pk_fma_f32 v[2:3], v[42:43], s[88:89], v[58:59] op_sel_hi:[1,0,1]
	s_nop 0
	v_pk_fma_f32 v[4:5], v[44:45], s[88:89], v[60:61] op_sel_hi:[1,0,1]
	global_store_dwordx4 v[8:9], v[2:5], off offset:64
	s_nop 1
	v_pk_fma_f32 v[4:5], v[32:33], s[88:89], v[64:65] op_sel_hi:[1,0,1]
	v_pk_fma_f32 v[2:3], v[30:31], s[88:89], v[62:63] op_sel_hi:[1,0,1]
	global_store_dwordx4 v[8:9], v[2:5], off offset:512
	s_nop 1
	v_pk_fma_f32 v[4:5], v[28:29], s[88:89], v[68:69] op_sel_hi:[1,0,1]
	v_pk_fma_f32 v[2:3], v[26:27], s[88:89], v[66:67] op_sel_hi:[1,0,1]
	global_store_dwordx4 v[8:9], v[2:5], off offset:576
	s_cbranch_vccz .LBB0_1532
	s_waitcnt vmcnt(0)
	s_cmpk_gt_u32 s22, 0xff
	v_readlane_b32 s28, v254, 27
	v_readlane_b32 s29, v254, 28
	s_cbranch_scc1 .LBB0_1547
	s_barrier
